# all 7 GEMM loops: static s_setprio 1 for the trailing wave half per phase instead of per-segment flips; base priority restored at each phase start
# speedup vs baseline: 1.0078x; 1.0034x over previous
.LBB0_6:
	s_setprio 0
	s_mov_b32 s1, s93
	s_mov_b32 s2, s0
	v_writelane_b32 v240, s2, 11
	s_lshl_b64 s[0:1], s[0:1], 1
	v_readlane_b32 s10, v243, 12
	v_writelane_b32 v240, s3, 12
	s_getpc_b64 s[2:3]
	s_add_u32 s2, s2, PROG@rel32@lo+4
	s_addc_u32 s3, s3, PROG@rel32@hi+12
	s_add_u32 s0, s2, s0
	s_addc_u32 s1, s3, s1
	global_load_ushort v1, v0, s[0:1]
	v_readlane_b32 s11, v243, 13
	s_waitcnt vmcnt(0)
	v_readfirstlane_b32 s1, v1
	s_lshr_b32 s0, s1, 3
	s_and_b32 s0, s0, 3
	s_cmp_eq_u32 s0, 0
	s_cselect_b64 s[2:3], -1, 0
	s_cmp_lg_u32 s0, 1
	s_cselect_b64 s[4:5], -1, 0
	s_nor_b64 s[8:9], s[4:5], s[10:11]
	s_and_b64 s[4:5], s[4:5], s[10:11]
	s_or_b64 s[2:3], s[2:3], s[8:9]
	s_or_b64 s[2:3], s[2:3], s[4:5]
	s_andn2_b64 vcc, exec, s[2:3]
	s_cbranch_vccz .LBB0_9
	s_bfe_u32 s2, s1, 0x20005
	s_cmp_lg_u32 s2, 1
	s_mov_b64 s[0:1], -1
	s_cbranch_scc0 .LBB0_8
	s_getpc_b64 s[98:99]

.LBB0_239:
	s_waitcnt lgkmcnt(0)
	v_bfe_i32 v3, v8, 27, 1
	v_lshlrev_b32_e32 v1, 4, v8
	v_lshrrev_b32_e32 v3, 22, v3
	v_add_u32_e32 v3, v1, v3
	v_and_b32_e32 v3, 0xfffffc00, v3
	v_ashrrev_i32_e32 v2, 31, v8
	v_sub_u32_e32 v3, v1, v3
	v_lshrrev_b32_e32 v2, 26, v2
	v_lshrrev_b32_e32 v4, 4, v3
	v_add_u32_e32 v2, v8, v2
	v_bitop3_b32 v4, v4, v3, 32 bitop3:0x6c
	v_ashrrev_i32_e32 v3, 31, v3
	v_ashrrev_i32_e32 v2, 6, v2
	v_lshrrev_b32_e32 v3, 26, v3
	v_lshlrev_b32_e32 v5, 3, v2
	v_add_u32_e32 v3, v4, v3
	v_and_b32_e32 v5, -16, v5
	v_ashrrev_i32_e32 v6, 6, v3
	v_add_u32_e32 v5, v6, v5
	v_mul_i32_i24_e32 v3, 64, v6
	v_sub_u32_e32 v3, v4, v3
	v_lshlrev_b32_e32 v4, 1, v5
	v_lshrrev_b32_e32 v9, 2, v5
	v_and_b32_e32 v6, 3, v6
	s_mov_b32 s0, 0x7fffffe0
	v_lshlrev_b32_e32 v2, 5, v2
	v_ashrrev_i16_sdwa v3, v190, sext(v3) dst_sel:DWORD dst_unused:UNUSED_PAD src0_sel:DWORD src1_sel:BYTE_0
	v_and_b32_e32 v4, 24, v4
	v_and_b32_e32 v9, 4, v9
	v_and_or_b32 v6, v5, s0, v6
	v_and_b32_e32 v2, 32, v2
	v_bfe_i32 v3, v3, 0, 16
	v_or3_b32 v6, v6, v9, v4
	v_add_u32_e32 v7, v2, v3
	v_mul_lo_u32 v4, v5, s64
	v_mul_lo_u32 v5, v6, s64
	v_add_u32_e32 v1, 0x2000, v1
	v_add_lshl_u32 v132, v5, v7, 1
	v_ashrrev_i32_e32 v5, 31, v1
	v_lshrrev_b32_e32 v5, 22, v5
	v_add_u32_e32 v5, v1, v5
	v_ashrrev_i32_e32 v5, 10, v5
	v_mul_i32_i24_e32 v6, 0x400, v5
	v_sub_u32_e32 v1, v1, v6
	v_lshrrev_b32_e32 v6, 4, v1
	v_bitop3_b32 v1, v6, v1, 32 bitop3:0x6c
	v_add_lshl_u32 v130, v7, v4, 1
	v_ashrrev_i32_e32 v7, 31, v1
	v_lshrrev_b32_e32 v7, 26, v7
	v_lshlrev_b32_e32 v6, 3, v5
	v_add_u32_e32 v7, v1, v7
	v_and_b32_e32 v6, -16, v6
	v_ashrrev_i32_e32 v9, 6, v7
	v_add_u32_e32 v10, v9, v6
	v_and_b32_e32 v6, 0xc0, v7
	v_lshlrev_b32_e32 v7, 1, v10
	v_lshrrev_b32_e32 v11, 2, v10
	v_and_b32_e32 v9, 3, v9
	v_and_b32_e32 v7, 24, v7
	v_and_b32_e32 v11, 4, v11
	v_and_or_b32 v9, v10, s0, v9
	s_lshl_b32 s23, s57, 3
	v_sub_u32_e32 v1, v1, v6
	v_or3_b32 v9, v9, v11, v7
	v_mul_lo_u32 v7, v10, s64
	v_cvt_f32_u32_e32 v10, s23
	v_lshlrev_b32_e32 v5, 5, v5
	v_ashrrev_i16_sdwa v1, v190, sext(v1) dst_sel:DWORD dst_unused:UNUSED_PAD src0_sel:DWORD src1_sel:BYTE_0
	v_and_b32_e32 v5, 32, v5
	v_bfe_i32 v6, v1, 0, 16
	v_add_u32_e32 v1, v5, v6
	v_mul_lo_u32 v9, v9, s64
	v_add_lshl_u32 v134, v1, v7, 1
	v_add_lshl_u32 v136, v9, v1, 1
	v_rcp_iflag_f32_e32 v1, v10
	s_sub_i32 s5, 0, s23
	s_add_i32 s0, s4, s58
	s_abs_i32 s4, s0
	v_mul_f32_e32 v1, 0x4f7ffffe, v1
	v_cvt_u32_f32_e32 v1, v1
	s_ashr_i32 s12, s18, 6
	s_lshl_b32 s92, s64, 8
	s_ashr_i32 s9, s18, 8
	v_readfirstlane_b32 s25, v1
	s_mul_i32 s5, s5, s25
	s_mul_hi_u32 s5, s25, s5
	s_add_i32 s25, s25, s5
	s_mul_hi_u32 s5, s4, s25
	s_mul_i32 s8, s5, s23
	s_sub_i32 s4, s4, s8
	s_lshl_b64 s[14:15], s[92:93], 1
	s_lshl_b32 s24, s12, 10
	s_ashr_i32 s1, s0, 31
	s_add_i32 s8, s5, 1
	s_sub_i32 s10, s4, s23
	s_cmp_ge_u32 s4, s23
	s_cselect_b32 s5, s8, s5
	s_cselect_b32 s4, s10, s4
	s_add_i32 s8, s5, 1
	s_cmp_ge_u32 s4, s23
	s_cselect_b32 s4, s8, s5
	s_xor_b32 s4, s4, s1
	s_sub_i32 s1, s4, s1
	s_lshl_b32 s4, s1, 3
	s_sub_i32 s5, s53, s4
	s_min_i32 s5, s5, 8
	s_sext_i32_i16 s8, s5
	v_cvt_f32_i32_e32 v1, s8
	s_mul_i32 s1, s1, s23
	s_sub_i32 s10, s0, s1
	s_sext_i32_i16 s0, s10
	v_cvt_f32_i32_e32 v9, s0
	v_rcp_iflag_f32_e32 v10, v1
	s_xor_b32 s0, s0, s8
	s_ashr_i32 s0, s0, 30
	s_or_b32 s8, s0, 1
	v_mul_f32_e32 v10, v9, v10
	v_trunc_f32_e32 v10, v10
	v_fma_f32 v9, -v10, v1, v9
	v_cvt_i32_f32_e32 v10, v10
	v_cmp_ge_f32_e64 s[0:1], |v9|, |v1|
	s_and_b64 s[0:1], s[0:1], exec
	s_cselect_b32 s0, s8, 0
	v_readfirstlane_b32 s1, v10
	s_add_i32 s8, s1, s0
	s_mul_i32 s0, s8, s5
	s_sub_i32 s0, s10, s0
	s_sext_i32_i16 s0, s0
	s_add_i32 s45, s4, s0
	s_ashr_i32 s0, s45, 31
	s_mul_i32 s0, s14, s0
	s_mul_hi_u32 s1, s14, s45
	s_bfe_u32 s4, s64, 0x10017
	s_add_i32 s0, s1, s0
	s_mul_i32 s1, s4, s45
	s_add_i32 s10, s0, s1
	s_bfe_i64 s[0:1], s[8:9], 0x100000
	s_mul_i32 s1, s14, s1
	s_mul_hi_u32 s5, s14, s0
	s_add_i32 s1, s5, s1
	s_mul_i32 s4, s4, s0
	s_add_i32 s1, s1, s4
	s_mul_i32 s0, s14, s0
	s_add_u32 s4, s36, s0
	s_addc_u32 s5, s37, s1
	s_add_i32 s26, s24, 0
	s_add_i32 m0, s26, 0x10000
	s_mul_i32 s11, s14, s45
	global_load_lds_dwordx4 v132, s[4:5]
	s_add_i32 m0, s26, 0x12000
	s_add_u32 s0, s56, s11
	global_load_lds_dwordx4 v136, s[4:5]
	s_addc_u32 s1, s52, s10
	s_mov_b32 m0, s26
	s_add_i32 s27, s26, 0x2000
	global_load_lds_dwordx4 v130, s[0:1]
	s_mov_b32 m0, s27
	s_add_u32 s10, s4, s92
	global_load_lds_dwordx4 v134, s[0:1]
	s_addc_u32 s11, s5, 0
	s_add_i32 m0, s26, 0x14000
	s_nop 0
	global_load_lds_dwordx4 v132, s[10:11]
	s_add_i32 m0, s26, 0x16000
	s_add_u32 s16, s0, s92
	s_addc_u32 s17, s1, 0
	s_add_i32 s28, s26, 0x4000
	global_load_lds_dwordx4 v136, s[10:11]
	s_mov_b32 m0, s28
	s_add_i32 s29, s26, 0x6000
	global_load_lds_dwordx4 v130, s[16:17]
	s_mov_b32 m0, s29
	s_cmp_lg_u32 s9, 1
	global_load_lds_dwordx4 v134, s[16:17]
	s_cbranch_scc1 .LBB0_241
	s_barrier
	s_setprio 1

.LBB0_252:
	s_add_u32 s0, s0, 0x80
	s_addc_u32 s1, s1, 0
	s_add_u32 s47, s4, 0x100
	s_addc_u32 s48, s5, 0
	s_mov_b32 s4, 0
	s_waitcnt lgkmcnt(0)
	s_waitcnt vmcnt(0)
	s_add_i32 s49, s4, 2
	s_add_u32 s16, s0, 0x80
	s_addc_u32 s5, s1, 0
	s_add_i32 s65, 0, 0x10000
	v_add_u32_e32 v142, s65, v145
	ds_read_b128 v[148:151], v142
	ds_read_b128 v[152:155], v142 offset:1024
	ds_read_b128 v[156:159], v142 offset:2048
	ds_read_b128 v[160:163], v142 offset:3072
	s_cmp_eq_u32 s41, s4
	s_cselect_b32 s4, s10, s16
	s_cselect_b32 s5, s11, s5
	s_cselect_b32 s17, s13, s48
	s_cselect_b32 s16, s12, s47
	v_lshl_add_u64 v[142:143], s[0:1], 0, v[138:139]
	s_add_i32 m0, s26, 0xc000
	ds_read_b128 v[164:167], v146
	ds_read_b128 v[168:171], v146 offset:1024
	ds_read_b128 v[172:175], v146 offset:2048
	ds_read_b128 v[176:179], v146 offset:3072
	ds_read_b128 v[180:183], v146 offset:4096
	ds_read_b128 v[204:207], v146 offset:5120
	ds_read_b128 v[208:211], v146 offset:6144
	ds_read_b128 v[212:215], v146 offset:7168
	global_load_lds_dwordx4 v[142:143], off
	v_lshl_add_u64 v[142:143], s[0:1], 0, v[140:141]
	s_add_i32 m0, s26, 0xe000
	s_nop 0
	global_load_lds_dwordx4 v[142:143], off
	s_waitcnt lgkmcnt(8)
	s_barrier
	s_waitcnt lgkmcnt(0)
	s_waitcnt lgkmcnt(0)
	v_mfma_f32_16x16x32_bf16 v[126:129], v[148:151], v[164:167], 0
	v_mfma_f32_16x16x32_bf16 v[122:125], v[156:159], v[164:167], 0
	v_mfma_f32_16x16x32_bf16 v[110:113], v[148:151], v[172:175], 0
	v_mfma_f32_16x16x32_bf16 v[106:109], v[156:159], v[172:175], 0
	v_mfma_f32_16x16x32_bf16 v[94:97], v[148:151], v[180:183], 0
	v_mfma_f32_16x16x32_bf16 v[90:93], v[156:159], v[180:183], 0
	v_mfma_f32_16x16x32_bf16 v[78:81], v[148:151], v[208:211], 0
	v_mfma_f32_16x16x32_bf16 v[74:77], v[156:159], v[208:211], 0
	v_mfma_f32_16x16x32_bf16 v[126:129], v[152:155], v[168:171], v[126:129]
	v_mfma_f32_16x16x32_bf16 v[122:125], v[160:163], v[168:171], v[122:125]
	v_mfma_f32_16x16x32_bf16 v[110:113], v[152:155], v[176:179], v[110:113]
	v_mfma_f32_16x16x32_bf16 v[106:109], v[160:163], v[176:179], v[106:109]
	v_mfma_f32_16x16x32_bf16 v[94:97], v[152:155], v[204:207], v[94:97]
	v_mfma_f32_16x16x32_bf16 v[90:93], v[160:163], v[204:207], v[90:93]
	v_mfma_f32_16x16x32_bf16 v[78:81], v[152:155], v[212:215], v[78:81]
	v_mfma_f32_16x16x32_bf16 v[74:77], v[160:163], v[212:215], v[74:77]
	s_barrier
	s_add_i32 s66, 0, 0x14000
	v_add_u32_e32 v142, s66, v145
	s_add_i32 s65, s65, s24
	ds_read_b128 v[216:219], v142
	ds_read_b128 v[220:223], v142 offset:1024
	ds_read_b128 v[224:227], v142 offset:2048
	ds_read_b128 v[228:231], v142 offset:3072
	v_lshl_add_u64 v[142:143], s[16:17], 0, v[132:133]
	s_mov_b32 m0, s65
	v_lshl_add_u64 v[184:185], s[16:17], 0, v[136:137]
	global_load_lds_dwordx4 v[142:143], off
	s_add_i32 m0, s65, 0x2000
	s_nop 0
	global_load_lds_dwordx4 v[184:185], off
	s_barrier
	s_waitcnt lgkmcnt(0)
	s_waitcnt lgkmcnt(0)
	v_mfma_f32_16x16x32_bf16 v[114:117], v[216:219], v[164:167], 0
	v_mfma_f32_16x16x32_bf16 v[118:121], v[224:227], v[164:167], 0
	v_mfma_f32_16x16x32_bf16 v[98:101], v[216:219], v[172:175], 0
	v_mfma_f32_16x16x32_bf16 v[102:105], v[224:227], v[172:175], 0
	v_mfma_f32_16x16x32_bf16 v[82:85], v[216:219], v[180:183], 0
	v_mfma_f32_16x16x32_bf16 v[86:89], v[224:227], v[180:183], 0
	v_mfma_f32_16x16x32_bf16 v[66:69], v[216:219], v[208:211], 0
	v_mfma_f32_16x16x32_bf16 v[70:73], v[224:227], v[208:211], 0
	v_mfma_f32_16x16x32_bf16 v[114:117], v[220:223], v[168:171], v[114:117]
	v_mfma_f32_16x16x32_bf16 v[118:121], v[228:231], v[168:171], v[118:121]
	v_mfma_f32_16x16x32_bf16 v[98:101], v[220:223], v[176:179], v[98:101]
	v_mfma_f32_16x16x32_bf16 v[102:105], v[228:231], v[176:179], v[102:105]
	v_mfma_f32_16x16x32_bf16 v[82:85], v[220:223], v[204:207], v[82:85]
	v_mfma_f32_16x16x32_bf16 v[86:89], v[228:231], v[204:207], v[86:89]
	v_mfma_f32_16x16x32_bf16 v[66:69], v[220:223], v[212:215], v[66:69]
	v_mfma_f32_16x16x32_bf16 v[70:73], v[228:231], v[212:215], v[70:73]
	s_mov_b32 m0, s26
	v_lshl_add_u64 v[232:233], s[4:5], 0, v[130:131]
	s_barrier
	ds_read_b128 v[164:167], v146 offset:16384
	ds_read_b128 v[168:171], v146 offset:17408
	ds_read_b128 v[172:175], v146 offset:18432
	ds_read_b128 v[176:179], v146 offset:19456
	ds_read_b128 v[180:183], v146 offset:20480
	ds_read_b128 v[204:207], v146 offset:21504
	ds_read_b128 v[208:211], v146 offset:22528
	ds_read_b128 v[212:215], v146 offset:23552
	global_load_lds_dwordx4 v[232:233], off
	v_lshl_add_u64 v[234:235], s[4:5], 0, v[134:135]
	s_mov_b32 m0, s27
	s_nop 0
	global_load_lds_dwordx4 v[234:235], off
	s_barrier
	s_waitcnt lgkmcnt(0)
	s_waitcnt lgkmcnt(0)
	v_mfma_f32_16x16x32_bf16 v[62:65], v[148:151], v[164:167], 0
	v_mfma_f32_16x16x32_bf16 v[58:61], v[156:159], v[164:167], 0
	v_mfma_f32_16x16x32_bf16 v[46:49], v[148:151], v[172:175], 0
	v_mfma_f32_16x16x32_bf16 v[42:45], v[156:159], v[172:175], 0
	v_mfma_f32_16x16x32_bf16 v[30:33], v[148:151], v[180:183], 0
	v_mfma_f32_16x16x32_bf16 v[26:29], v[156:159], v[180:183], 0
	v_mfma_f32_16x16x32_bf16 v[14:17], v[148:151], v[208:211], 0
	v_mfma_f32_16x16x32_bf16 v[10:13], v[156:159], v[208:211], 0
	v_mfma_f32_16x16x32_bf16 v[62:65], v[152:155], v[168:171], v[62:65]
	v_mfma_f32_16x16x32_bf16 v[58:61], v[160:163], v[168:171], v[58:61]
	v_mfma_f32_16x16x32_bf16 v[46:49], v[152:155], v[176:179], v[46:49]
	v_mfma_f32_16x16x32_bf16 v[42:45], v[160:163], v[176:179], v[42:45]
	v_mfma_f32_16x16x32_bf16 v[30:33], v[152:155], v[204:207], v[30:33]
	v_mfma_f32_16x16x32_bf16 v[26:29], v[160:163], v[204:207], v[26:29]
	v_mfma_f32_16x16x32_bf16 v[14:17], v[152:155], v[212:215], v[14:17]
	v_mfma_f32_16x16x32_bf16 v[10:13], v[160:163], v[212:215], v[10:13]
	s_barrier
	s_add_u32 s16, s16, s92
	s_addc_u32 s17, s17, 0
	s_add_i32 s65, s66, s24
	v_lshl_add_u64 v[236:237], s[16:17], 0, v[132:133]
	s_mov_b32 m0, s65
	v_lshl_add_u64 v[238:239], s[16:17], 0, v[136:137]
	global_load_lds_dwordx4 v[236:237], off
	s_add_i32 m0, s65, 0x2000
	s_nop 0
	global_load_lds_dwordx4 v[238:239], off
	s_waitcnt vmcnt(6)
	s_barrier
	v_mfma_f32_16x16x32_bf16 v[50:53], v[216:219], v[164:167], 0
	v_mfma_f32_16x16x32_bf16 v[54:57], v[224:227], v[164:167], 0
	v_mfma_f32_16x16x32_bf16 v[34:37], v[216:219], v[172:175], 0
	v_mfma_f32_16x16x32_bf16 v[38:41], v[224:227], v[172:175], 0
	v_mfma_f32_16x16x32_bf16 v[18:21], v[216:219], v[180:183], 0
	v_mfma_f32_16x16x32_bf16 v[22:25], v[224:227], v[180:183], 0
	v_mfma_f32_16x16x32_bf16 v[6:9], v[216:219], v[208:211], 0
	v_mfma_f32_16x16x32_bf16 v[2:5], v[224:227], v[208:211], 0
	v_mfma_f32_16x16x32_bf16 v[50:53], v[220:223], v[168:171], v[50:53]
	v_mfma_f32_16x16x32_bf16 v[54:57], v[228:231], v[168:171], v[54:57]
	v_mfma_f32_16x16x32_bf16 v[34:37], v[220:223], v[176:179], v[34:37]
	v_mfma_f32_16x16x32_bf16 v[38:41], v[228:231], v[176:179], v[38:41]
	v_mfma_f32_16x16x32_bf16 v[18:21], v[220:223], v[204:207], v[18:21]
	v_mfma_f32_16x16x32_bf16 v[22:25], v[228:231], v[204:207], v[22:25]
	v_mfma_f32_16x16x32_bf16 v[6:9], v[220:223], v[212:215], v[6:9]
	v_mfma_f32_16x16x32_bf16 v[2:5], v[228:231], v[212:215], v[2:5]
	s_add_i32 s16, 0, 0x18000
	v_add_u32_e32 v147, s16, v145
	s_barrier
	ds_read_b128 v[148:151], v147
	ds_read_b128 v[152:155], v147 offset:1024
	ds_read_b128 v[156:159], v147 offset:2048
	ds_read_b128 v[160:163], v147 offset:3072
	s_add_u32 s4, s4, s92
	s_addc_u32 s5, s5, 0
	s_mov_b32 m0, s28
	v_lshl_add_u64 v[216:217], s[4:5], 0, v[130:131]
	ds_read_b128 v[164:167], v146 offset:32768
	ds_read_b128 v[168:171], v146 offset:33792
	ds_read_b128 v[172:175], v146 offset:34816
	ds_read_b128 v[176:179], v146 offset:35840
	ds_read_b128 v[180:183], v146 offset:36864
	ds_read_b128 v[204:207], v146 offset:37888
	ds_read_b128 v[208:211], v146 offset:38912
	ds_read_b128 v[212:215], v146 offset:39936
	global_load_lds_dwordx4 v[216:217], off
	v_lshl_add_u64 v[216:217], s[4:5], 0, v[134:135]
	s_mov_b32 m0, s29
	s_nop 0
	global_load_lds_dwordx4 v[216:217], off
	s_waitcnt lgkmcnt(8)
	s_barrier
	s_waitcnt lgkmcnt(0)
	s_waitcnt lgkmcnt(0)
	v_mfma_f32_16x16x32_bf16 v[126:129], v[148:151], v[164:167], v[126:129]
	v_mfma_f32_16x16x32_bf16 v[122:125], v[156:159], v[164:167], v[122:125]
	v_mfma_f32_16x16x32_bf16 v[110:113], v[148:151], v[172:175], v[110:113]
	v_mfma_f32_16x16x32_bf16 v[106:109], v[156:159], v[172:175], v[106:109]
	v_mfma_f32_16x16x32_bf16 v[94:97], v[148:151], v[180:183], v[94:97]
	v_mfma_f32_16x16x32_bf16 v[90:93], v[156:159], v[180:183], v[90:93]
	v_mfma_f32_16x16x32_bf16 v[78:81], v[148:151], v[208:211], v[78:81]
	v_mfma_f32_16x16x32_bf16 v[74:77], v[156:159], v[208:211], v[74:77]
	v_mfma_f32_16x16x32_bf16 v[126:129], v[152:155], v[168:171], v[126:129]
	v_mfma_f32_16x16x32_bf16 v[122:125], v[160:163], v[168:171], v[122:125]
	v_mfma_f32_16x16x32_bf16 v[110:113], v[152:155], v[176:179], v[110:113]
	v_mfma_f32_16x16x32_bf16 v[106:109], v[160:163], v[176:179], v[106:109]
	v_mfma_f32_16x16x32_bf16 v[94:97], v[152:155], v[204:207], v[94:97]
	v_mfma_f32_16x16x32_bf16 v[90:93], v[160:163], v[204:207], v[90:93]
	v_mfma_f32_16x16x32_bf16 v[78:81], v[152:155], v[212:215], v[78:81]
	v_mfma_f32_16x16x32_bf16 v[74:77], v[160:163], v[212:215], v[74:77]
	s_barrier
	s_add_i32 s4, 0, 0x1c000
	s_add_i32 s5, s16, s24
	v_add_u32_e32 v147, s4, v145
	v_lshl_add_u64 v[142:143], v[142:143], 0, s[6:7]
	s_mov_b32 m0, s5
	ds_read_b128 v[216:219], v147
	ds_read_b128 v[220:223], v147 offset:1024
	ds_read_b128 v[224:227], v147 offset:2048
	ds_read_b128 v[228:231], v147 offset:3072
	global_load_lds_dwordx4 v[142:143], off
	v_lshl_add_u64 v[142:143], v[184:185], 0, s[6:7]
	s_add_i32 m0, s5, 0x2000
	s_nop 0
	global_load_lds_dwordx4 v[142:143], off
	s_barrier
	s_waitcnt lgkmcnt(0)
	s_waitcnt lgkmcnt(0)
	v_mfma_f32_16x16x32_bf16 v[114:117], v[216:219], v[164:167], v[114:117]
	v_mfma_f32_16x16x32_bf16 v[118:121], v[224:227], v[164:167], v[118:121]
	v_mfma_f32_16x16x32_bf16 v[98:101], v[216:219], v[172:175], v[98:101]
	v_mfma_f32_16x16x32_bf16 v[102:105], v[224:227], v[172:175], v[102:105]
	v_mfma_f32_16x16x32_bf16 v[82:85], v[216:219], v[180:183], v[82:85]
	v_mfma_f32_16x16x32_bf16 v[86:89], v[224:227], v[180:183], v[86:89]
	v_mfma_f32_16x16x32_bf16 v[66:69], v[216:219], v[208:211], v[66:69]
	v_mfma_f32_16x16x32_bf16 v[70:73], v[224:227], v[208:211], v[70:73]
	v_mfma_f32_16x16x32_bf16 v[114:117], v[220:223], v[168:171], v[114:117]
	v_mfma_f32_16x16x32_bf16 v[118:121], v[228:231], v[168:171], v[118:121]
	v_mfma_f32_16x16x32_bf16 v[98:101], v[220:223], v[176:179], v[98:101]
	v_mfma_f32_16x16x32_bf16 v[102:105], v[228:231], v[176:179], v[102:105]
	v_mfma_f32_16x16x32_bf16 v[82:85], v[220:223], v[204:207], v[82:85]
	v_mfma_f32_16x16x32_bf16 v[86:89], v[228:231], v[204:207], v[86:89]
	v_mfma_f32_16x16x32_bf16 v[66:69], v[220:223], v[212:215], v[66:69]
	v_mfma_f32_16x16x32_bf16 v[70:73], v[228:231], v[212:215], v[70:73]
	s_mov_b32 m0, s35
	v_lshl_add_u64 v[142:143], v[232:233], 0, s[6:7]
	s_barrier
	ds_read_b128 v[164:167], v146 offset:49152
	ds_read_b128 v[168:171], v146 offset:50176
	ds_read_b128 v[172:175], v146 offset:51200
	ds_read_b128 v[176:179], v146 offset:52224
	ds_read_b128 v[180:183], v146 offset:53248
	ds_read_b128 v[204:207], v146 offset:54272
	ds_read_b128 v[208:211], v146 offset:55296
	ds_read_b128 v[212:215], v146 offset:56320
	global_load_lds_dwordx4 v[142:143], off
	v_lshl_add_u64 v[142:143], v[234:235], 0, s[6:7]
	s_mov_b32 m0, s40
	s_nop 0
	global_load_lds_dwordx4 v[142:143], off
	s_barrier
	s_waitcnt lgkmcnt(0)
	s_waitcnt lgkmcnt(0)
	v_mfma_f32_16x16x32_bf16 v[62:65], v[148:151], v[164:167], v[62:65]
	v_mfma_f32_16x16x32_bf16 v[58:61], v[156:159], v[164:167], v[58:61]
	v_mfma_f32_16x16x32_bf16 v[46:49], v[148:151], v[172:175], v[46:49]
	v_mfma_f32_16x16x32_bf16 v[42:45], v[156:159], v[172:175], v[42:45]
	v_mfma_f32_16x16x32_bf16 v[30:33], v[148:151], v[180:183], v[30:33]
	v_mfma_f32_16x16x32_bf16 v[26:29], v[156:159], v[180:183], v[26:29]
	v_mfma_f32_16x16x32_bf16 v[14:17], v[148:151], v[208:211], v[14:17]
	v_mfma_f32_16x16x32_bf16 v[10:13], v[156:159], v[208:211], v[10:13]
	v_mfma_f32_16x16x32_bf16 v[62:65], v[152:155], v[168:171], v[62:65]
	v_mfma_f32_16x16x32_bf16 v[58:61], v[160:163], v[168:171], v[58:61]
	v_mfma_f32_16x16x32_bf16 v[46:49], v[152:155], v[176:179], v[46:49]
	v_mfma_f32_16x16x32_bf16 v[42:45], v[160:163], v[176:179], v[42:45]
	v_mfma_f32_16x16x32_bf16 v[30:33], v[152:155], v[204:207], v[30:33]
	v_mfma_f32_16x16x32_bf16 v[26:29], v[160:163], v[204:207], v[26:29]
	v_mfma_f32_16x16x32_bf16 v[14:17], v[152:155], v[212:215], v[14:17]
	v_mfma_f32_16x16x32_bf16 v[10:13], v[160:163], v[212:215], v[10:13]
	s_barrier
	s_add_i32 s4, s4, s24
	v_lshl_add_u64 v[142:143], v[236:237], 0, s[6:7]
	s_mov_b32 m0, s4
	s_nop 0
	global_load_lds_dwordx4 v[142:143], off
	v_lshl_add_u64 v[142:143], v[238:239], 0, s[6:7]
	s_add_i32 m0, s4, 0x2000
	s_nop 0
	global_load_lds_dwordx4 v[142:143], off
	s_waitcnt vmcnt(6)
	s_barrier
	v_mfma_f32_16x16x32_bf16 v[50:53], v[216:219], v[164:167], v[50:53]
	v_mfma_f32_16x16x32_bf16 v[54:57], v[224:227], v[164:167], v[54:57]
	v_mfma_f32_16x16x32_bf16 v[34:37], v[216:219], v[172:175], v[34:37]
	v_mfma_f32_16x16x32_bf16 v[38:41], v[224:227], v[172:175], v[38:41]
	v_mfma_f32_16x16x32_bf16 v[18:21], v[216:219], v[180:183], v[18:21]
	v_mfma_f32_16x16x32_bf16 v[22:25], v[224:227], v[180:183], v[22:25]
	v_mfma_f32_16x16x32_bf16 v[6:9], v[216:219], v[208:211], v[6:9]
	v_mfma_f32_16x16x32_bf16 v[2:5], v[224:227], v[208:211], v[2:5]
	v_mfma_f32_16x16x32_bf16 v[50:53], v[220:223], v[168:171], v[50:53]
	v_mfma_f32_16x16x32_bf16 v[54:57], v[228:231], v[168:171], v[54:57]
	v_mfma_f32_16x16x32_bf16 v[34:37], v[220:223], v[176:179], v[34:37]
	v_mfma_f32_16x16x32_bf16 v[38:41], v[228:231], v[176:179], v[38:41]
	v_mfma_f32_16x16x32_bf16 v[18:21], v[220:223], v[204:207], v[18:21]
	v_mfma_f32_16x16x32_bf16 v[22:25], v[228:231], v[204:207], v[22:25]
	v_mfma_f32_16x16x32_bf16 v[6:9], v[220:223], v[212:215], v[6:9]
	v_mfma_f32_16x16x32_bf16 v[2:5], v[228:231], v[212:215], v[2:5]
	s_add_u32 s0, s0, 0x100
	s_addc_u32 s1, s1, 0
	s_add_u32 s47, s47, 0x100
	s_addc_u32 s48, s48, 0
	s_cmp_ge_u32 s49, s30
	s_mov_b32 s4, s49
	s_barrier
	s_cbranch_scc1 .Lkexit_253
.LBB0_253:
	s_add_i32 s49, s4, 2
	s_add_u32 s16, s0, 0x80
	s_addc_u32 s5, s1, 0
	s_add_i32 s65, 0, 0x10000
	v_add_u32_e32 v142, s65, v145
	ds_read_b128 v[148:151], v142
	ds_read_b128 v[152:155], v142 offset:1024
	ds_read_b128 v[156:159], v142 offset:2048
	ds_read_b128 v[160:163], v142 offset:3072
	s_cmp_eq_u32 s41, s4
	s_cselect_b32 s4, s10, s16
	s_cselect_b32 s5, s11, s5
	s_cselect_b32 s17, s13, s48
	s_cselect_b32 s16, s12, s47
	v_lshl_add_u64 v[142:143], s[0:1], 0, v[138:139]
	s_add_i32 m0, s26, 0xc000
	ds_read_b128 v[164:167], v146
	ds_read_b128 v[168:171], v146 offset:1024
	ds_read_b128 v[172:175], v146 offset:2048
	ds_read_b128 v[176:179], v146 offset:3072
	ds_read_b128 v[180:183], v146 offset:4096
	ds_read_b128 v[204:207], v146 offset:5120
	ds_read_b128 v[208:211], v146 offset:6144
	ds_read_b128 v[212:215], v146 offset:7168
	global_load_lds_dwordx4 v[142:143], off
	v_lshl_add_u64 v[142:143], s[0:1], 0, v[140:141]
	s_add_i32 m0, s26, 0xe000
	s_nop 0
	global_load_lds_dwordx4 v[142:143], off
	s_waitcnt lgkmcnt(8)
	s_barrier
	s_waitcnt lgkmcnt(0)
	s_waitcnt lgkmcnt(0)
	v_mfma_f32_16x16x32_bf16 v[126:129], v[148:151], v[164:167], v[126:129]
	v_mfma_f32_16x16x32_bf16 v[122:125], v[156:159], v[164:167], v[122:125]
	v_mfma_f32_16x16x32_bf16 v[110:113], v[148:151], v[172:175], v[110:113]
	v_mfma_f32_16x16x32_bf16 v[106:109], v[156:159], v[172:175], v[106:109]
	v_mfma_f32_16x16x32_bf16 v[94:97], v[148:151], v[180:183], v[94:97]
	v_mfma_f32_16x16x32_bf16 v[90:93], v[156:159], v[180:183], v[90:93]
	v_mfma_f32_16x16x32_bf16 v[78:81], v[148:151], v[208:211], v[78:81]
	v_mfma_f32_16x16x32_bf16 v[74:77], v[156:159], v[208:211], v[74:77]
	v_mfma_f32_16x16x32_bf16 v[126:129], v[152:155], v[168:171], v[126:129]
	v_mfma_f32_16x16x32_bf16 v[122:125], v[160:163], v[168:171], v[122:125]
	v_mfma_f32_16x16x32_bf16 v[110:113], v[152:155], v[176:179], v[110:113]
	v_mfma_f32_16x16x32_bf16 v[106:109], v[160:163], v[176:179], v[106:109]
	v_mfma_f32_16x16x32_bf16 v[94:97], v[152:155], v[204:207], v[94:97]
	v_mfma_f32_16x16x32_bf16 v[90:93], v[160:163], v[204:207], v[90:93]
	v_mfma_f32_16x16x32_bf16 v[78:81], v[152:155], v[212:215], v[78:81]
	v_mfma_f32_16x16x32_bf16 v[74:77], v[160:163], v[212:215], v[74:77]
	s_barrier
	s_add_i32 s66, 0, 0x14000
	v_add_u32_e32 v142, s66, v145
	s_add_i32 s65, s65, s24
	ds_read_b128 v[216:219], v142
	ds_read_b128 v[220:223], v142 offset:1024
	ds_read_b128 v[224:227], v142 offset:2048
	ds_read_b128 v[228:231], v142 offset:3072
	v_lshl_add_u64 v[142:143], s[16:17], 0, v[132:133]
	s_mov_b32 m0, s65
	v_lshl_add_u64 v[184:185], s[16:17], 0, v[136:137]
	global_load_lds_dwordx4 v[142:143], off
	s_add_i32 m0, s65, 0x2000
	s_nop 0
	global_load_lds_dwordx4 v[184:185], off
	s_barrier
	s_waitcnt lgkmcnt(0)
	s_waitcnt lgkmcnt(0)
	v_mfma_f32_16x16x32_bf16 v[114:117], v[216:219], v[164:167], v[114:117]
	v_mfma_f32_16x16x32_bf16 v[118:121], v[224:227], v[164:167], v[118:121]
	v_mfma_f32_16x16x32_bf16 v[98:101], v[216:219], v[172:175], v[98:101]
	v_mfma_f32_16x16x32_bf16 v[102:105], v[224:227], v[172:175], v[102:105]
	v_mfma_f32_16x16x32_bf16 v[82:85], v[216:219], v[180:183], v[82:85]
	v_mfma_f32_16x16x32_bf16 v[86:89], v[224:227], v[180:183], v[86:89]
	v_mfma_f32_16x16x32_bf16 v[66:69], v[216:219], v[208:211], v[66:69]
	v_mfma_f32_16x16x32_bf16 v[70:73], v[224:227], v[208:211], v[70:73]
	v_mfma_f32_16x16x32_bf16 v[114:117], v[220:223], v[168:171], v[114:117]
	v_mfma_f32_16x16x32_bf16 v[118:121], v[228:231], v[168:171], v[118:121]
	v_mfma_f32_16x16x32_bf16 v[98:101], v[220:223], v[176:179], v[98:101]
	v_mfma_f32_16x16x32_bf16 v[102:105], v[228:231], v[176:179], v[102:105]
	v_mfma_f32_16x16x32_bf16 v[82:85], v[220:223], v[204:207], v[82:85]
	v_mfma_f32_16x16x32_bf16 v[86:89], v[228:231], v[204:207], v[86:89]
	v_mfma_f32_16x16x32_bf16 v[66:69], v[220:223], v[212:215], v[66:69]
	v_mfma_f32_16x16x32_bf16 v[70:73], v[228:231], v[212:215], v[70:73]
	s_mov_b32 m0, s26
	v_lshl_add_u64 v[232:233], s[4:5], 0, v[130:131]
	s_barrier
	ds_read_b128 v[164:167], v146 offset:16384
	ds_read_b128 v[168:171], v146 offset:17408
	ds_read_b128 v[172:175], v146 offset:18432
	ds_read_b128 v[176:179], v146 offset:19456
	ds_read_b128 v[180:183], v146 offset:20480
	ds_read_b128 v[204:207], v146 offset:21504
	ds_read_b128 v[208:211], v146 offset:22528
	ds_read_b128 v[212:215], v146 offset:23552
	global_load_lds_dwordx4 v[232:233], off
	v_lshl_add_u64 v[234:235], s[4:5], 0, v[134:135]
	s_mov_b32 m0, s27
	s_nop 0
	global_load_lds_dwordx4 v[234:235], off
	s_barrier
	s_waitcnt lgkmcnt(0)
	s_waitcnt lgkmcnt(0)
	v_mfma_f32_16x16x32_bf16 v[62:65], v[148:151], v[164:167], v[62:65]
	v_mfma_f32_16x16x32_bf16 v[58:61], v[156:159], v[164:167], v[58:61]
	v_mfma_f32_16x16x32_bf16 v[46:49], v[148:151], v[172:175], v[46:49]
	v_mfma_f32_16x16x32_bf16 v[42:45], v[156:159], v[172:175], v[42:45]
	v_mfma_f32_16x16x32_bf16 v[30:33], v[148:151], v[180:183], v[30:33]
	v_mfma_f32_16x16x32_bf16 v[26:29], v[156:159], v[180:183], v[26:29]
	v_mfma_f32_16x16x32_bf16 v[14:17], v[148:151], v[208:211], v[14:17]
	v_mfma_f32_16x16x32_bf16 v[10:13], v[156:159], v[208:211], v[10:13]
	v_mfma_f32_16x16x32_bf16 v[62:65], v[152:155], v[168:171], v[62:65]
	v_mfma_f32_16x16x32_bf16 v[58:61], v[160:163], v[168:171], v[58:61]
	v_mfma_f32_16x16x32_bf16 v[46:49], v[152:155], v[176:179], v[46:49]
	v_mfma_f32_16x16x32_bf16 v[42:45], v[160:163], v[176:179], v[42:45]
	v_mfma_f32_16x16x32_bf16 v[30:33], v[152:155], v[204:207], v[30:33]
	v_mfma_f32_16x16x32_bf16 v[26:29], v[160:163], v[204:207], v[26:29]
	v_mfma_f32_16x16x32_bf16 v[14:17], v[152:155], v[212:215], v[14:17]
	v_mfma_f32_16x16x32_bf16 v[10:13], v[160:163], v[212:215], v[10:13]
	s_barrier
	s_add_u32 s16, s16, s92
	s_addc_u32 s17, s17, 0
	s_add_i32 s65, s66, s24
	v_lshl_add_u64 v[236:237], s[16:17], 0, v[132:133]
	s_mov_b32 m0, s65
	v_lshl_add_u64 v[238:239], s[16:17], 0, v[136:137]
	global_load_lds_dwordx4 v[236:237], off
	s_add_i32 m0, s65, 0x2000
	s_nop 0
	global_load_lds_dwordx4 v[238:239], off
	s_waitcnt vmcnt(6)
	s_barrier
	v_mfma_f32_16x16x32_bf16 v[50:53], v[216:219], v[164:167], v[50:53]
	v_mfma_f32_16x16x32_bf16 v[54:57], v[224:227], v[164:167], v[54:57]
	v_mfma_f32_16x16x32_bf16 v[34:37], v[216:219], v[172:175], v[34:37]
	v_mfma_f32_16x16x32_bf16 v[38:41], v[224:227], v[172:175], v[38:41]
	v_mfma_f32_16x16x32_bf16 v[18:21], v[216:219], v[180:183], v[18:21]
	v_mfma_f32_16x16x32_bf16 v[22:25], v[224:227], v[180:183], v[22:25]
	v_mfma_f32_16x16x32_bf16 v[6:9], v[216:219], v[208:211], v[6:9]
	v_mfma_f32_16x16x32_bf16 v[2:5], v[224:227], v[208:211], v[2:5]
	v_mfma_f32_16x16x32_bf16 v[50:53], v[220:223], v[168:171], v[50:53]
	v_mfma_f32_16x16x32_bf16 v[54:57], v[228:231], v[168:171], v[54:57]
	v_mfma_f32_16x16x32_bf16 v[34:37], v[220:223], v[176:179], v[34:37]
	v_mfma_f32_16x16x32_bf16 v[38:41], v[228:231], v[176:179], v[38:41]
	v_mfma_f32_16x16x32_bf16 v[18:21], v[220:223], v[204:207], v[18:21]
	v_mfma_f32_16x16x32_bf16 v[22:25], v[228:231], v[204:207], v[22:25]
	v_mfma_f32_16x16x32_bf16 v[6:9], v[220:223], v[212:215], v[6:9]
	v_mfma_f32_16x16x32_bf16 v[2:5], v[228:231], v[212:215], v[2:5]
	s_add_i32 s16, 0, 0x18000
	v_add_u32_e32 v147, s16, v145
	s_barrier
	ds_read_b128 v[148:151], v147
	ds_read_b128 v[152:155], v147 offset:1024
	ds_read_b128 v[156:159], v147 offset:2048
	ds_read_b128 v[160:163], v147 offset:3072
	s_add_u32 s4, s4, s92
	s_addc_u32 s5, s5, 0
	s_mov_b32 m0, s28
	v_lshl_add_u64 v[216:217], s[4:5], 0, v[130:131]
	ds_read_b128 v[164:167], v146 offset:32768
	ds_read_b128 v[168:171], v146 offset:33792
	ds_read_b128 v[172:175], v146 offset:34816
	ds_read_b128 v[176:179], v146 offset:35840
	ds_read_b128 v[180:183], v146 offset:36864
	ds_read_b128 v[204:207], v146 offset:37888
	ds_read_b128 v[208:211], v146 offset:38912
	ds_read_b128 v[212:215], v146 offset:39936
	global_load_lds_dwordx4 v[216:217], off
	v_lshl_add_u64 v[216:217], s[4:5], 0, v[134:135]
	s_mov_b32 m0, s29
	s_nop 0
	global_load_lds_dwordx4 v[216:217], off
	s_waitcnt lgkmcnt(8)
	s_barrier
	s_waitcnt lgkmcnt(0)
	s_waitcnt lgkmcnt(0)
	v_mfma_f32_16x16x32_bf16 v[126:129], v[148:151], v[164:167], v[126:129]
	v_mfma_f32_16x16x32_bf16 v[122:125], v[156:159], v[164:167], v[122:125]
	v_mfma_f32_16x16x32_bf16 v[110:113], v[148:151], v[172:175], v[110:113]
	v_mfma_f32_16x16x32_bf16 v[106:109], v[156:159], v[172:175], v[106:109]
	v_mfma_f32_16x16x32_bf16 v[94:97], v[148:151], v[180:183], v[94:97]
	v_mfma_f32_16x16x32_bf16 v[90:93], v[156:159], v[180:183], v[90:93]
	v_mfma_f32_16x16x32_bf16 v[78:81], v[148:151], v[208:211], v[78:81]
	v_mfma_f32_16x16x32_bf16 v[74:77], v[156:159], v[208:211], v[74:77]
	v_mfma_f32_16x16x32_bf16 v[126:129], v[152:155], v[168:171], v[126:129]
	v_mfma_f32_16x16x32_bf16 v[122:125], v[160:163], v[168:171], v[122:125]
	v_mfma_f32_16x16x32_bf16 v[110:113], v[152:155], v[176:179], v[110:113]
	v_mfma_f32_16x16x32_bf16 v[106:109], v[160:163], v[176:179], v[106:109]
	v_mfma_f32_16x16x32_bf16 v[94:97], v[152:155], v[204:207], v[94:97]
	v_mfma_f32_16x16x32_bf16 v[90:93], v[160:163], v[204:207], v[90:93]
	v_mfma_f32_16x16x32_bf16 v[78:81], v[152:155], v[212:215], v[78:81]
	v_mfma_f32_16x16x32_bf16 v[74:77], v[160:163], v[212:215], v[74:77]
	s_barrier
	s_add_i32 s4, 0, 0x1c000
	s_add_i32 s5, s16, s24
	v_add_u32_e32 v147, s4, v145
	v_lshl_add_u64 v[142:143], v[142:143], 0, s[6:7]
	s_mov_b32 m0, s5
	ds_read_b128 v[216:219], v147
	ds_read_b128 v[220:223], v147 offset:1024
	ds_read_b128 v[224:227], v147 offset:2048
	ds_read_b128 v[228:231], v147 offset:3072
	global_load_lds_dwordx4 v[142:143], off
	v_lshl_add_u64 v[142:143], v[184:185], 0, s[6:7]
	s_add_i32 m0, s5, 0x2000
	s_nop 0
	global_load_lds_dwordx4 v[142:143], off
	s_barrier
	s_waitcnt lgkmcnt(0)
	s_waitcnt lgkmcnt(0)
	v_mfma_f32_16x16x32_bf16 v[114:117], v[216:219], v[164:167], v[114:117]
	v_mfma_f32_16x16x32_bf16 v[118:121], v[224:227], v[164:167], v[118:121]
	v_mfma_f32_16x16x32_bf16 v[98:101], v[216:219], v[172:175], v[98:101]
	v_mfma_f32_16x16x32_bf16 v[102:105], v[224:227], v[172:175], v[102:105]
	v_mfma_f32_16x16x32_bf16 v[82:85], v[216:219], v[180:183], v[82:85]
	v_mfma_f32_16x16x32_bf16 v[86:89], v[224:227], v[180:183], v[86:89]
	v_mfma_f32_16x16x32_bf16 v[66:69], v[216:219], v[208:211], v[66:69]
	v_mfma_f32_16x16x32_bf16 v[70:73], v[224:227], v[208:211], v[70:73]
	v_mfma_f32_16x16x32_bf16 v[114:117], v[220:223], v[168:171], v[114:117]
	v_mfma_f32_16x16x32_bf16 v[118:121], v[228:231], v[168:171], v[118:121]
	v_mfma_f32_16x16x32_bf16 v[98:101], v[220:223], v[176:179], v[98:101]
	v_mfma_f32_16x16x32_bf16 v[102:105], v[228:231], v[176:179], v[102:105]
	v_mfma_f32_16x16x32_bf16 v[82:85], v[220:223], v[204:207], v[82:85]
	v_mfma_f32_16x16x32_bf16 v[86:89], v[228:231], v[204:207], v[86:89]
	v_mfma_f32_16x16x32_bf16 v[66:69], v[220:223], v[212:215], v[66:69]
	v_mfma_f32_16x16x32_bf16 v[70:73], v[228:231], v[212:215], v[70:73]
	s_mov_b32 m0, s35
	v_lshl_add_u64 v[142:143], v[232:233], 0, s[6:7]
	s_barrier
	ds_read_b128 v[164:167], v146 offset:49152
	ds_read_b128 v[168:171], v146 offset:50176
	ds_read_b128 v[172:175], v146 offset:51200
	ds_read_b128 v[176:179], v146 offset:52224
	ds_read_b128 v[180:183], v146 offset:53248
	ds_read_b128 v[204:207], v146 offset:54272
	ds_read_b128 v[208:211], v146 offset:55296
	ds_read_b128 v[212:215], v146 offset:56320
	global_load_lds_dwordx4 v[142:143], off
	v_lshl_add_u64 v[142:143], v[234:235], 0, s[6:7]
	s_mov_b32 m0, s40
	s_nop 0
	global_load_lds_dwordx4 v[142:143], off
	s_barrier
	s_waitcnt lgkmcnt(0)
	s_waitcnt lgkmcnt(0)
	v_mfma_f32_16x16x32_bf16 v[62:65], v[148:151], v[164:167], v[62:65]
	v_mfma_f32_16x16x32_bf16 v[58:61], v[156:159], v[164:167], v[58:61]
	v_mfma_f32_16x16x32_bf16 v[46:49], v[148:151], v[172:175], v[46:49]
	v_mfma_f32_16x16x32_bf16 v[42:45], v[156:159], v[172:175], v[42:45]
	v_mfma_f32_16x16x32_bf16 v[30:33], v[148:151], v[180:183], v[30:33]
	v_mfma_f32_16x16x32_bf16 v[26:29], v[156:159], v[180:183], v[26:29]
	v_mfma_f32_16x16x32_bf16 v[14:17], v[148:151], v[208:211], v[14:17]
	v_mfma_f32_16x16x32_bf16 v[10:13], v[156:159], v[208:211], v[10:13]
	v_mfma_f32_16x16x32_bf16 v[62:65], v[152:155], v[168:171], v[62:65]
	v_mfma_f32_16x16x32_bf16 v[58:61], v[160:163], v[168:171], v[58:61]
	v_mfma_f32_16x16x32_bf16 v[46:49], v[152:155], v[176:179], v[46:49]
	v_mfma_f32_16x16x32_bf16 v[42:45], v[160:163], v[176:179], v[42:45]
	v_mfma_f32_16x16x32_bf16 v[30:33], v[152:155], v[204:207], v[30:33]
	v_mfma_f32_16x16x32_bf16 v[26:29], v[160:163], v[204:207], v[26:29]
	v_mfma_f32_16x16x32_bf16 v[14:17], v[152:155], v[212:215], v[14:17]
	v_mfma_f32_16x16x32_bf16 v[10:13], v[160:163], v[212:215], v[10:13]
	s_barrier
	s_add_i32 s4, s4, s24
	v_lshl_add_u64 v[142:143], v[236:237], 0, s[6:7]
	s_mov_b32 m0, s4
	s_nop 0
	global_load_lds_dwordx4 v[142:143], off
	v_lshl_add_u64 v[142:143], v[238:239], 0, s[6:7]
	s_add_i32 m0, s4, 0x2000
	s_nop 0
	global_load_lds_dwordx4 v[142:143], off
	s_waitcnt vmcnt(6)
	s_barrier
	v_mfma_f32_16x16x32_bf16 v[50:53], v[216:219], v[164:167], v[50:53]
	v_mfma_f32_16x16x32_bf16 v[54:57], v[224:227], v[164:167], v[54:57]
	v_mfma_f32_16x16x32_bf16 v[34:37], v[216:219], v[172:175], v[34:37]
	v_mfma_f32_16x16x32_bf16 v[38:41], v[224:227], v[172:175], v[38:41]
	v_mfma_f32_16x16x32_bf16 v[18:21], v[216:219], v[180:183], v[18:21]
	v_mfma_f32_16x16x32_bf16 v[22:25], v[224:227], v[180:183], v[22:25]
	v_mfma_f32_16x16x32_bf16 v[6:9], v[216:219], v[208:211], v[6:9]
	v_mfma_f32_16x16x32_bf16 v[2:5], v[224:227], v[208:211], v[2:5]
	v_mfma_f32_16x16x32_bf16 v[50:53], v[220:223], v[168:171], v[50:53]
	v_mfma_f32_16x16x32_bf16 v[54:57], v[228:231], v[168:171], v[54:57]
	v_mfma_f32_16x16x32_bf16 v[34:37], v[220:223], v[176:179], v[34:37]
	v_mfma_f32_16x16x32_bf16 v[38:41], v[228:231], v[176:179], v[38:41]
	v_mfma_f32_16x16x32_bf16 v[18:21], v[220:223], v[204:207], v[18:21]
	v_mfma_f32_16x16x32_bf16 v[22:25], v[228:231], v[204:207], v[22:25]
	v_mfma_f32_16x16x32_bf16 v[6:9], v[220:223], v[212:215], v[6:9]
	v_mfma_f32_16x16x32_bf16 v[2:5], v[228:231], v[212:215], v[2:5]
	s_add_u32 s0, s0, 0x100
	s_addc_u32 s1, s1, 0
	s_add_u32 s47, s47, 0x100
	s_addc_u32 s48, s48, 0
	s_cmp_ge_u32 s49, s30
	s_mov_b32 s4, s49
	s_barrier
	s_cbranch_scc0 .LBB0_253

.LBB0_266:
	s_andn2_b64 vcc, exec, s[0:1]
	s_cbranch_vccnz .LBB0_322
	s_waitcnt lgkmcnt(0)
	v_bfe_i32 v3, v20, 27, 1
	v_lshlrev_b32_e32 v1, 4, v20
	v_lshrrev_b32_e32 v3, 22, v3
	v_add_u32_e32 v3, v1, v3
	v_and_b32_e32 v3, 0xfffffc00, v3
	v_ashrrev_i32_e32 v2, 31, v20
	v_sub_u32_e32 v3, v1, v3
	v_lshrrev_b32_e32 v2, 26, v2
	v_lshrrev_b32_e32 v4, 4, v3
	v_add_u32_e32 v2, v20, v2
	v_bitop3_b32 v4, v4, v3, 32 bitop3:0x6c
	v_ashrrev_i32_e32 v3, 31, v3
	v_ashrrev_i32_e32 v2, 6, v2
	v_lshrrev_b32_e32 v3, 26, v3
	v_lshlrev_b32_e32 v5, 3, v2
	v_add_u32_e32 v3, v4, v3
	v_and_b32_e32 v5, -16, v5
	v_ashrrev_i32_e32 v3, 6, v3
	v_lshlrev_b32_e32 v2, 5, v2
	v_add_u32_e32 v5, v3, v5
	v_and_b32_e32 v14, 32, v2
	v_mul_i32_i24_e32 v2, 64, v3
	v_sub_u32_e32 v2, v4, v2
	v_lshlrev_b32_e32 v4, 1, v5
	v_lshrrev_b32_e32 v6, 2, v5
	v_and_b32_e32 v3, 3, v3
	s_mov_b32 s0, 0x7fffffe0
	v_ashrrev_i16_sdwa v2, v190, sext(v2) dst_sel:DWORD dst_unused:UNUSED_PAD src0_sel:DWORD src1_sel:BYTE_0
	v_and_b32_e32 v4, 24, v4
	v_and_b32_e32 v6, 4, v6
	v_and_or_b32 v3, v5, s0, v3
	v_bfe_i32 v15, v2, 0, 16
	v_or3_b32 v3, v3, v6, v4
	v_add_u32_e32 v2, v14, v15
	v_mul_lo_u32 v16, v5, s64
	v_mul_lo_u32 v3, v3, s64
	v_add_u32_e32 v1, 0x2000, v1
	v_add_lshl_u32 v130, v2, v16, 1
	v_add_lshl_u32 v132, v3, v2, 1
	v_ashrrev_i32_e32 v2, 31, v1
	v_lshrrev_b32_e32 v2, 22, v2
	v_add_u32_e32 v2, v1, v2
	v_ashrrev_i32_e32 v2, 10, v2
	v_mul_i32_i24_e32 v3, 0x400, v2
	v_sub_u32_e32 v1, v1, v3
	v_lshrrev_b32_e32 v3, 4, v1
	v_bitop3_b32 v1, v3, v1, 32 bitop3:0x6c
	v_ashrrev_i32_e32 v4, 31, v1
	v_lshrrev_b32_e32 v4, 26, v4
	v_lshlrev_b32_e32 v3, 3, v2
	v_add_u32_e32 v4, v1, v4
	v_and_b32_e32 v3, -16, v3
	v_ashrrev_i32_e32 v5, 6, v4
	v_add_u32_e32 v3, v5, v3
	v_and_b32_e32 v5, 3, v5
	s_lshl_b32 s92, s64, 8
	v_and_or_b32 v5, v3, s0, v5
	s_lshl_b64 s[14:15], s[92:93], 1
	s_ashr_i32 s0, s27, 31
	s_mul_i32 s0, s14, s0
	s_mul_hi_u32 s1, s14, s27
	s_add_i32 s0, s1, s0
	s_bfe_u32 s1, s64, 0x10017
	s_mul_i32 s4, s1, s27
	s_add_i32 s10, s0, s4
	s_ashr_i32 s4, s18, 31
	s_mul_i32 s4, s14, s4
	s_mul_hi_u32 s5, s14, s18
	s_ashr_i32 s9, s26, 6
	v_lshlrev_b32_e32 v2, 5, v2
	s_add_i32 s4, s5, s4
	s_mul_i32 s1, s1, s18
	v_and_b32_e32 v17, 32, v2
	v_and_b32_e32 v2, 0xc0, v4
	s_ashr_i32 s8, s26, 8
	s_lshl_b32 s28, s9, 10
	s_add_i32 s1, s4, s1
	s_mul_i32 s4, s14, s18
	v_sub_u32_e32 v1, v1, v2
	v_lshlrev_b32_e32 v2, 1, v3
	v_lshrrev_b32_e32 v4, 2, v3
	s_add_u32 s4, s36, s4
	v_ashrrev_i16_sdwa v1, v190, sext(v1) dst_sel:DWORD dst_unused:UNUSED_PAD src0_sel:DWORD src1_sel:BYTE_0
	v_and_b32_e32 v2, 24, v2
	v_and_b32_e32 v4, 4, v4
	s_addc_u32 s5, s37, s1
	s_add_i32 s29, s28, 0
	v_bfe_i32 v18, v1, 0, 16
	v_or3_b32 v2, v5, v4, v2
	s_add_i32 m0, s29, 0x10000
	v_add_u32_e32 v1, v17, v18
	v_mul_lo_u32 v2, v2, s64
	s_mul_i32 s0, s14, s27
	global_load_lds_dwordx4 v132, s[4:5]
	s_add_i32 m0, s29, 0x12000
	v_add_lshl_u32 v136, v2, v1, 1
	s_add_u32 s0, s56, s0
	v_mul_lo_u32 v19, v3, s64
	global_load_lds_dwordx4 v136, s[4:5]
	s_addc_u32 s1, s52, s10
	s_mov_b32 m0, s29
	s_add_i32 s30, s29, 0x2000
	v_add_lshl_u32 v134, v1, v19, 1
	global_load_lds_dwordx4 v130, s[0:1]
	s_mov_b32 m0, s30
	s_add_u32 s10, s4, s92
	global_load_lds_dwordx4 v134, s[0:1]
	s_addc_u32 s11, s5, 0
	s_add_i32 m0, s29, 0x14000
	v_mov_b32_e32 v133, v0
	v_mov_b32_e32 v137, v0
	global_load_lds_dwordx4 v132, s[10:11]
	s_add_i32 m0, s29, 0x16000
	v_lshl_add_u64 v[10:11], s[10:11], 0, v[132:133]
	v_lshl_add_u64 v[12:13], s[10:11], 0, v[136:137]
	global_load_lds_dwordx4 v136, s[10:11]
	s_add_u32 s10, s0, s92
	s_addc_u32 s11, s1, 0
	s_add_i32 s31, s29, 0x4000
	s_mov_b32 m0, s31
	s_add_i32 s34, s29, 0x6000
	global_load_lds_dwordx4 v130, s[10:11]
	s_mov_b32 m0, s34
	v_mov_b32_e32 v131, v0
	global_load_lds_dwordx4 v134, s[10:11]
	v_mov_b32_e32 v135, v0
	v_lshl_add_u64 v[2:3], s[4:5], 0, v[132:133]
	v_lshl_add_u64 v[4:5], s[4:5], 0, v[136:137]
	v_lshl_add_u64 v[6:7], s[0:1], 0, v[130:131]
	v_lshl_add_u64 v[8:9], s[0:1], 0, v[134:135]
	s_cmp_lg_u32 s8, 1
	s_cbranch_scc1 .LBB0_269
	s_barrier
	s_setprio 1

.LBB0_281:
	s_add_u32 s0, s0, 0x80
	s_addc_u32 s1, s1, 0
	s_add_u32 s20, s4, 0x100
	s_addc_u32 s21, s5, 0
	s_mov_b32 s4, 0
	s_waitcnt lgkmcnt(0)
	s_add_i32 s22, s4, 2
	s_add_u32 s10, s0, 0x80
	s_addc_u32 s5, s1, 0
	s_add_i32 s23, 0, 0x10000
	v_add_u32_e32 v154, s23, v165
	ds_read_b128 v[142:145], v154
	ds_read_b128 v[146:149], v154 offset:1024
	ds_read_b128 v[150:153], v154 offset:2048
	ds_read_b128 v[154:157], v154 offset:3072
	s_cmp_eq_u32 s44, s4
	s_cselect_b32 s4, s16, s10
	s_cselect_b32 s5, s17, s5
	s_cselect_b32 s11, s13, s21
	s_cselect_b32 s10, s12, s20
	v_lshl_add_u64 v[162:163], s[0:1], 0, v[138:139]
	s_add_i32 m0, s29, 0xc000
	ds_read_b128 v[158:161], v166
	ds_read_b128 v[168:171], v166 offset:1024
	ds_read_b128 v[172:175], v166 offset:2048
	ds_read_b128 v[176:179], v166 offset:3072
	ds_read_b128 v[180:183], v166 offset:4096
	ds_read_b128 v[204:207], v166 offset:5120
	ds_read_b128 v[208:211], v166 offset:6144
	ds_read_b128 v[212:215], v166 offset:7168
	global_load_lds_dwordx4 v[162:163], off
	v_lshl_add_u64 v[162:163], s[0:1], 0, v[140:141]
	s_add_i32 m0, s29, 0xe000
	s_nop 0
	global_load_lds_dwordx4 v[162:163], off
	s_waitcnt lgkmcnt(8)
	s_barrier
	s_waitcnt lgkmcnt(0)
	s_waitcnt lgkmcnt(0)
	v_mfma_f32_16x16x32_bf16 v[126:129], v[142:145], v[158:161], 0
	v_mfma_f32_16x16x32_bf16 v[122:125], v[150:153], v[158:161], 0
	v_mfma_f32_16x16x32_bf16 v[110:113], v[142:145], v[172:175], 0
	v_mfma_f32_16x16x32_bf16 v[106:109], v[150:153], v[172:175], 0
	v_mfma_f32_16x16x32_bf16 v[94:97], v[142:145], v[180:183], 0
	v_mfma_f32_16x16x32_bf16 v[90:93], v[150:153], v[180:183], 0
	v_mfma_f32_16x16x32_bf16 v[78:81], v[142:145], v[208:211], 0
	v_mfma_f32_16x16x32_bf16 v[74:77], v[150:153], v[208:211], 0
	v_mfma_f32_16x16x32_bf16 v[126:129], v[146:149], v[168:171], v[126:129]
	v_mfma_f32_16x16x32_bf16 v[122:125], v[154:157], v[168:171], v[122:125]
	v_mfma_f32_16x16x32_bf16 v[110:113], v[146:149], v[176:179], v[110:113]
	v_mfma_f32_16x16x32_bf16 v[106:109], v[154:157], v[176:179], v[106:109]
	v_mfma_f32_16x16x32_bf16 v[94:97], v[146:149], v[204:207], v[94:97]
	v_mfma_f32_16x16x32_bf16 v[90:93], v[154:157], v[204:207], v[90:93]
	v_mfma_f32_16x16x32_bf16 v[78:81], v[146:149], v[212:215], v[78:81]
	v_mfma_f32_16x16x32_bf16 v[74:77], v[154:157], v[212:215], v[74:77]
	s_barrier
	s_add_i32 s24, 0, 0x14000
	v_add_u32_e32 v162, s24, v165
	s_add_i32 s23, s23, s28
	ds_read_b128 v[216:219], v162
	ds_read_b128 v[220:223], v162 offset:1024
	ds_read_b128 v[224:227], v162 offset:2048
	ds_read_b128 v[228:231], v162 offset:3072
	v_lshl_add_u64 v[162:163], s[10:11], 0, v[132:133]
	s_mov_b32 m0, s23
	v_lshl_add_u64 v[184:185], s[10:11], 0, v[136:137]
	global_load_lds_dwordx4 v[162:163], off
	s_add_i32 m0, s23, 0x2000
	s_nop 0
	global_load_lds_dwordx4 v[184:185], off
	s_barrier
	s_waitcnt lgkmcnt(0)
	s_waitcnt lgkmcnt(0)
	v_mfma_f32_16x16x32_bf16 v[118:121], v[216:219], v[158:161], 0
	v_mfma_f32_16x16x32_bf16 v[114:117], v[224:227], v[158:161], 0
	v_mfma_f32_16x16x32_bf16 v[102:105], v[216:219], v[172:175], 0
	v_mfma_f32_16x16x32_bf16 v[98:101], v[224:227], v[172:175], 0
	v_mfma_f32_16x16x32_bf16 v[86:89], v[216:219], v[180:183], 0
	v_mfma_f32_16x16x32_bf16 v[82:85], v[224:227], v[180:183], 0
	v_mfma_f32_16x16x32_bf16 v[70:73], v[216:219], v[208:211], 0
	v_mfma_f32_16x16x32_bf16 v[66:69], v[224:227], v[208:211], 0
	v_mfma_f32_16x16x32_bf16 v[118:121], v[220:223], v[168:171], v[118:121]
	v_mfma_f32_16x16x32_bf16 v[114:117], v[228:231], v[168:171], v[114:117]
	v_mfma_f32_16x16x32_bf16 v[102:105], v[220:223], v[176:179], v[102:105]
	v_mfma_f32_16x16x32_bf16 v[98:101], v[228:231], v[176:179], v[98:101]
	v_mfma_f32_16x16x32_bf16 v[86:89], v[220:223], v[204:207], v[86:89]
	v_mfma_f32_16x16x32_bf16 v[82:85], v[228:231], v[204:207], v[82:85]
	v_mfma_f32_16x16x32_bf16 v[70:73], v[220:223], v[212:215], v[70:73]
	v_mfma_f32_16x16x32_bf16 v[66:69], v[228:231], v[212:215], v[66:69]
	s_mov_b32 m0, s29
	v_lshl_add_u64 v[232:233], s[4:5], 0, v[130:131]
	s_barrier
	ds_read_b128 v[158:161], v166 offset:16384
	ds_read_b128 v[168:171], v166 offset:17408
	ds_read_b128 v[172:175], v166 offset:18432
	ds_read_b128 v[176:179], v166 offset:19456
	ds_read_b128 v[180:183], v166 offset:20480
	ds_read_b128 v[204:207], v166 offset:21504
	ds_read_b128 v[208:211], v166 offset:22528
	ds_read_b128 v[212:215], v166 offset:23552
	global_load_lds_dwordx4 v[232:233], off
	v_lshl_add_u64 v[234:235], s[4:5], 0, v[134:135]
	s_mov_b32 m0, s30
	s_nop 0
	global_load_lds_dwordx4 v[234:235], off
	s_barrier
	s_waitcnt lgkmcnt(0)
	s_waitcnt lgkmcnt(0)
	v_mfma_f32_16x16x32_bf16 v[62:65], v[142:145], v[158:161], 0
	v_mfma_f32_16x16x32_bf16 v[58:61], v[150:153], v[158:161], 0
	v_mfma_f32_16x16x32_bf16 v[46:49], v[142:145], v[172:175], 0
	v_mfma_f32_16x16x32_bf16 v[42:45], v[150:153], v[172:175], 0
	v_mfma_f32_16x16x32_bf16 v[30:33], v[142:145], v[180:183], 0
	v_mfma_f32_16x16x32_bf16 v[26:29], v[150:153], v[180:183], 0
	v_mfma_f32_16x16x32_bf16 v[14:17], v[142:145], v[208:211], 0
	v_mfma_f32_16x16x32_bf16 v[10:13], v[150:153], v[208:211], 0
	v_mfma_f32_16x16x32_bf16 v[62:65], v[146:149], v[168:171], v[62:65]
	v_mfma_f32_16x16x32_bf16 v[58:61], v[154:157], v[168:171], v[58:61]
	v_mfma_f32_16x16x32_bf16 v[46:49], v[146:149], v[176:179], v[46:49]
	v_mfma_f32_16x16x32_bf16 v[42:45], v[154:157], v[176:179], v[42:45]
	v_mfma_f32_16x16x32_bf16 v[30:33], v[146:149], v[204:207], v[30:33]
	v_mfma_f32_16x16x32_bf16 v[26:29], v[154:157], v[204:207], v[26:29]
	v_mfma_f32_16x16x32_bf16 v[14:17], v[146:149], v[212:215], v[14:17]
	v_mfma_f32_16x16x32_bf16 v[10:13], v[154:157], v[212:215], v[10:13]
	s_barrier
	s_add_u32 s10, s10, s92
	s_addc_u32 s11, s11, 0
	s_add_i32 s23, s24, s28
	v_lshl_add_u64 v[236:237], s[10:11], 0, v[132:133]
	s_mov_b32 m0, s23
	v_lshl_add_u64 v[238:239], s[10:11], 0, v[136:137]
	global_load_lds_dwordx4 v[236:237], off
	s_add_i32 m0, s23, 0x2000
	s_nop 0
	global_load_lds_dwordx4 v[238:239], off
	s_waitcnt vmcnt(6)
	s_barrier
	v_mfma_f32_16x16x32_bf16 v[54:57], v[216:219], v[158:161], 0
	v_mfma_f32_16x16x32_bf16 v[50:53], v[224:227], v[158:161], 0
	v_mfma_f32_16x16x32_bf16 v[38:41], v[216:219], v[172:175], 0
	v_mfma_f32_16x16x32_bf16 v[34:37], v[224:227], v[172:175], 0
	v_mfma_f32_16x16x32_bf16 v[22:25], v[216:219], v[180:183], 0
	v_mfma_f32_16x16x32_bf16 v[18:21], v[224:227], v[180:183], 0
	v_mfma_f32_16x16x32_bf16 v[6:9], v[216:219], v[208:211], 0
	v_mfma_f32_16x16x32_bf16 v[2:5], v[224:227], v[208:211], 0
	v_mfma_f32_16x16x32_bf16 v[54:57], v[220:223], v[168:171], v[54:57]
	v_mfma_f32_16x16x32_bf16 v[50:53], v[228:231], v[168:171], v[50:53]
	v_mfma_f32_16x16x32_bf16 v[38:41], v[220:223], v[176:179], v[38:41]
	v_mfma_f32_16x16x32_bf16 v[34:37], v[228:231], v[176:179], v[34:37]
	v_mfma_f32_16x16x32_bf16 v[22:25], v[220:223], v[204:207], v[22:25]
	v_mfma_f32_16x16x32_bf16 v[18:21], v[228:231], v[204:207], v[18:21]
	v_mfma_f32_16x16x32_bf16 v[6:9], v[220:223], v[212:215], v[6:9]
	v_mfma_f32_16x16x32_bf16 v[2:5], v[228:231], v[212:215], v[2:5]
	s_add_i32 s10, 0, 0x18000
	v_add_u32_e32 v154, s10, v165
	s_barrier
	ds_read_b128 v[142:145], v154
	ds_read_b128 v[146:149], v154 offset:1024
	ds_read_b128 v[150:153], v154 offset:2048
	ds_read_b128 v[154:157], v154 offset:3072
	s_add_u32 s4, s4, s92
	s_addc_u32 s5, s5, 0
	s_mov_b32 m0, s31
	v_lshl_add_u64 v[216:217], s[4:5], 0, v[130:131]
	ds_read_b128 v[158:161], v166 offset:32768
	ds_read_b128 v[168:171], v166 offset:33792
	ds_read_b128 v[172:175], v166 offset:34816
	ds_read_b128 v[176:179], v166 offset:35840
	ds_read_b128 v[180:183], v166 offset:36864
	ds_read_b128 v[204:207], v166 offset:37888
	ds_read_b128 v[208:211], v166 offset:38912
	ds_read_b128 v[212:215], v166 offset:39936
	global_load_lds_dwordx4 v[216:217], off
	v_lshl_add_u64 v[216:217], s[4:5], 0, v[134:135]
	s_mov_b32 m0, s34
	s_nop 0
	global_load_lds_dwordx4 v[216:217], off
	s_waitcnt lgkmcnt(8)
	s_barrier
	s_waitcnt lgkmcnt(0)
	s_waitcnt lgkmcnt(0)
	v_mfma_f32_16x16x32_bf16 v[126:129], v[142:145], v[158:161], v[126:129]
	v_mfma_f32_16x16x32_bf16 v[122:125], v[150:153], v[158:161], v[122:125]
	v_mfma_f32_16x16x32_bf16 v[110:113], v[142:145], v[172:175], v[110:113]
	v_mfma_f32_16x16x32_bf16 v[106:109], v[150:153], v[172:175], v[106:109]
	v_mfma_f32_16x16x32_bf16 v[94:97], v[142:145], v[180:183], v[94:97]
	v_mfma_f32_16x16x32_bf16 v[90:93], v[150:153], v[180:183], v[90:93]
	v_mfma_f32_16x16x32_bf16 v[78:81], v[142:145], v[208:211], v[78:81]
	v_mfma_f32_16x16x32_bf16 v[74:77], v[150:153], v[208:211], v[74:77]
	v_mfma_f32_16x16x32_bf16 v[126:129], v[146:149], v[168:171], v[126:129]
	v_mfma_f32_16x16x32_bf16 v[122:125], v[154:157], v[168:171], v[122:125]
	v_mfma_f32_16x16x32_bf16 v[110:113], v[146:149], v[176:179], v[110:113]
	v_mfma_f32_16x16x32_bf16 v[106:109], v[154:157], v[176:179], v[106:109]
	v_mfma_f32_16x16x32_bf16 v[94:97], v[146:149], v[204:207], v[94:97]
	v_mfma_f32_16x16x32_bf16 v[90:93], v[154:157], v[204:207], v[90:93]
	v_mfma_f32_16x16x32_bf16 v[78:81], v[146:149], v[212:215], v[78:81]
	v_mfma_f32_16x16x32_bf16 v[74:77], v[154:157], v[212:215], v[74:77]
	s_barrier
	s_add_i32 s4, 0, 0x1c000
	s_add_i32 s5, s10, s28
	v_add_u32_e32 v167, s4, v165
	v_lshl_add_u64 v[162:163], v[162:163], 0, s[6:7]
	s_mov_b32 m0, s5
	ds_read_b128 v[216:219], v167
	ds_read_b128 v[220:223], v167 offset:1024
	ds_read_b128 v[224:227], v167 offset:2048
	ds_read_b128 v[228:231], v167 offset:3072
	global_load_lds_dwordx4 v[162:163], off
	v_lshl_add_u64 v[162:163], v[184:185], 0, s[6:7]
	s_add_i32 m0, s5, 0x2000
	s_nop 0
	global_load_lds_dwordx4 v[162:163], off
	s_barrier
	s_waitcnt lgkmcnt(0)
	s_waitcnt lgkmcnt(0)
	v_mfma_f32_16x16x32_bf16 v[118:121], v[216:219], v[158:161], v[118:121]
	v_mfma_f32_16x16x32_bf16 v[114:117], v[224:227], v[158:161], v[114:117]
	v_mfma_f32_16x16x32_bf16 v[102:105], v[216:219], v[172:175], v[102:105]
	v_mfma_f32_16x16x32_bf16 v[98:101], v[224:227], v[172:175], v[98:101]
	v_mfma_f32_16x16x32_bf16 v[86:89], v[216:219], v[180:183], v[86:89]
	v_mfma_f32_16x16x32_bf16 v[82:85], v[224:227], v[180:183], v[82:85]
	v_mfma_f32_16x16x32_bf16 v[70:73], v[216:219], v[208:211], v[70:73]
	v_mfma_f32_16x16x32_bf16 v[66:69], v[224:227], v[208:211], v[66:69]
	v_mfma_f32_16x16x32_bf16 v[118:121], v[220:223], v[168:171], v[118:121]
	v_mfma_f32_16x16x32_bf16 v[114:117], v[228:231], v[168:171], v[114:117]
	v_mfma_f32_16x16x32_bf16 v[102:105], v[220:223], v[176:179], v[102:105]
	v_mfma_f32_16x16x32_bf16 v[98:101], v[228:231], v[176:179], v[98:101]
	v_mfma_f32_16x16x32_bf16 v[86:89], v[220:223], v[204:207], v[86:89]
	v_mfma_f32_16x16x32_bf16 v[82:85], v[228:231], v[204:207], v[82:85]
	v_mfma_f32_16x16x32_bf16 v[70:73], v[220:223], v[212:215], v[70:73]
	v_mfma_f32_16x16x32_bf16 v[66:69], v[228:231], v[212:215], v[66:69]
	s_mov_b32 m0, s42
	v_lshl_add_u64 v[162:163], v[232:233], 0, s[6:7]
	s_barrier
	ds_read_b128 v[158:161], v166 offset:49152
	ds_read_b128 v[168:171], v166 offset:50176
	ds_read_b128 v[172:175], v166 offset:51200
	ds_read_b128 v[176:179], v166 offset:52224
	ds_read_b128 v[180:183], v166 offset:53248
	ds_read_b128 v[204:207], v166 offset:54272
	ds_read_b128 v[208:211], v166 offset:55296
	ds_read_b128 v[212:215], v166 offset:56320
	global_load_lds_dwordx4 v[162:163], off
	v_lshl_add_u64 v[162:163], v[234:235], 0, s[6:7]
	s_mov_b32 m0, s43
	s_nop 0
	global_load_lds_dwordx4 v[162:163], off
	s_barrier
	s_waitcnt lgkmcnt(0)
	s_waitcnt lgkmcnt(0)
	v_mfma_f32_16x16x32_bf16 v[62:65], v[142:145], v[158:161], v[62:65]
	v_mfma_f32_16x16x32_bf16 v[58:61], v[150:153], v[158:161], v[58:61]
	v_mfma_f32_16x16x32_bf16 v[46:49], v[142:145], v[172:175], v[46:49]
	v_mfma_f32_16x16x32_bf16 v[42:45], v[150:153], v[172:175], v[42:45]
	v_mfma_f32_16x16x32_bf16 v[30:33], v[142:145], v[180:183], v[30:33]
	v_mfma_f32_16x16x32_bf16 v[26:29], v[150:153], v[180:183], v[26:29]
	v_mfma_f32_16x16x32_bf16 v[14:17], v[142:145], v[208:211], v[14:17]
	v_mfma_f32_16x16x32_bf16 v[10:13], v[150:153], v[208:211], v[10:13]
	v_mfma_f32_16x16x32_bf16 v[62:65], v[146:149], v[168:171], v[62:65]
	v_mfma_f32_16x16x32_bf16 v[58:61], v[154:157], v[168:171], v[58:61]
	v_mfma_f32_16x16x32_bf16 v[46:49], v[146:149], v[176:179], v[46:49]
	v_mfma_f32_16x16x32_bf16 v[42:45], v[154:157], v[176:179], v[42:45]
	v_mfma_f32_16x16x32_bf16 v[30:33], v[146:149], v[204:207], v[30:33]
	v_mfma_f32_16x16x32_bf16 v[26:29], v[154:157], v[204:207], v[26:29]
	v_mfma_f32_16x16x32_bf16 v[14:17], v[146:149], v[212:215], v[14:17]
	v_mfma_f32_16x16x32_bf16 v[10:13], v[154:157], v[212:215], v[10:13]
	s_barrier
	s_add_i32 s4, s4, s28
	v_lshl_add_u64 v[142:143], v[236:237], 0, s[6:7]
	s_mov_b32 m0, s4
	s_nop 0
	global_load_lds_dwordx4 v[142:143], off
	v_lshl_add_u64 v[142:143], v[238:239], 0, s[6:7]
	s_add_i32 m0, s4, 0x2000
	s_nop 0
	global_load_lds_dwordx4 v[142:143], off
	s_waitcnt vmcnt(6)
	s_barrier
	v_mfma_f32_16x16x32_bf16 v[54:57], v[216:219], v[158:161], v[54:57]
	v_mfma_f32_16x16x32_bf16 v[50:53], v[224:227], v[158:161], v[50:53]
	v_mfma_f32_16x16x32_bf16 v[38:41], v[216:219], v[172:175], v[38:41]
	v_mfma_f32_16x16x32_bf16 v[34:37], v[224:227], v[172:175], v[34:37]
	v_mfma_f32_16x16x32_bf16 v[22:25], v[216:219], v[180:183], v[22:25]
	v_mfma_f32_16x16x32_bf16 v[18:21], v[224:227], v[180:183], v[18:21]
	v_mfma_f32_16x16x32_bf16 v[6:9], v[216:219], v[208:211], v[6:9]
	v_mfma_f32_16x16x32_bf16 v[2:5], v[224:227], v[208:211], v[2:5]
	v_mfma_f32_16x16x32_bf16 v[54:57], v[220:223], v[168:171], v[54:57]
	v_mfma_f32_16x16x32_bf16 v[50:53], v[228:231], v[168:171], v[50:53]
	v_mfma_f32_16x16x32_bf16 v[38:41], v[220:223], v[176:179], v[38:41]
	v_mfma_f32_16x16x32_bf16 v[34:37], v[228:231], v[176:179], v[34:37]
	v_mfma_f32_16x16x32_bf16 v[22:25], v[220:223], v[204:207], v[22:25]
	v_mfma_f32_16x16x32_bf16 v[18:21], v[228:231], v[204:207], v[18:21]
	v_mfma_f32_16x16x32_bf16 v[6:9], v[220:223], v[212:215], v[6:9]
	v_mfma_f32_16x16x32_bf16 v[2:5], v[228:231], v[212:215], v[2:5]
	s_add_u32 s0, s0, 0x100
	s_addc_u32 s1, s1, 0
	s_add_u32 s20, s20, 0x100
	s_addc_u32 s21, s21, 0
	s_cmp_ge_u32 s22, s35
	s_mov_b32 s4, s22
	s_barrier
	s_cbranch_scc1 .Lkexit_282
.LBB0_282:
	s_add_i32 s22, s4, 2
	s_add_u32 s10, s0, 0x80
	s_addc_u32 s5, s1, 0
	s_add_i32 s23, 0, 0x10000
	v_add_u32_e32 v154, s23, v165
	ds_read_b128 v[142:145], v154
	ds_read_b128 v[146:149], v154 offset:1024
	ds_read_b128 v[150:153], v154 offset:2048
	ds_read_b128 v[154:157], v154 offset:3072
	s_cmp_eq_u32 s44, s4
	s_cselect_b32 s4, s16, s10
	s_cselect_b32 s5, s17, s5
	s_cselect_b32 s11, s13, s21
	s_cselect_b32 s10, s12, s20
	v_lshl_add_u64 v[162:163], s[0:1], 0, v[138:139]
	s_add_i32 m0, s29, 0xc000
	ds_read_b128 v[158:161], v166
	ds_read_b128 v[168:171], v166 offset:1024
	ds_read_b128 v[172:175], v166 offset:2048
	ds_read_b128 v[176:179], v166 offset:3072
	ds_read_b128 v[180:183], v166 offset:4096
	ds_read_b128 v[204:207], v166 offset:5120
	ds_read_b128 v[208:211], v166 offset:6144
	ds_read_b128 v[212:215], v166 offset:7168
	global_load_lds_dwordx4 v[162:163], off
	v_lshl_add_u64 v[162:163], s[0:1], 0, v[140:141]
	s_add_i32 m0, s29, 0xe000
	s_nop 0
	global_load_lds_dwordx4 v[162:163], off
	s_waitcnt lgkmcnt(8)
	s_barrier
	s_waitcnt lgkmcnt(0)
	s_waitcnt lgkmcnt(0)
	v_mfma_f32_16x16x32_bf16 v[126:129], v[142:145], v[158:161], v[126:129]
	v_mfma_f32_16x16x32_bf16 v[122:125], v[150:153], v[158:161], v[122:125]
	v_mfma_f32_16x16x32_bf16 v[110:113], v[142:145], v[172:175], v[110:113]
	v_mfma_f32_16x16x32_bf16 v[106:109], v[150:153], v[172:175], v[106:109]
	v_mfma_f32_16x16x32_bf16 v[94:97], v[142:145], v[180:183], v[94:97]
	v_mfma_f32_16x16x32_bf16 v[90:93], v[150:153], v[180:183], v[90:93]
	v_mfma_f32_16x16x32_bf16 v[78:81], v[142:145], v[208:211], v[78:81]
	v_mfma_f32_16x16x32_bf16 v[74:77], v[150:153], v[208:211], v[74:77]
	v_mfma_f32_16x16x32_bf16 v[126:129], v[146:149], v[168:171], v[126:129]
	v_mfma_f32_16x16x32_bf16 v[122:125], v[154:157], v[168:171], v[122:125]
	v_mfma_f32_16x16x32_bf16 v[110:113], v[146:149], v[176:179], v[110:113]
	v_mfma_f32_16x16x32_bf16 v[106:109], v[154:157], v[176:179], v[106:109]
	v_mfma_f32_16x16x32_bf16 v[94:97], v[146:149], v[204:207], v[94:97]
	v_mfma_f32_16x16x32_bf16 v[90:93], v[154:157], v[204:207], v[90:93]
	v_mfma_f32_16x16x32_bf16 v[78:81], v[146:149], v[212:215], v[78:81]
	v_mfma_f32_16x16x32_bf16 v[74:77], v[154:157], v[212:215], v[74:77]
	s_barrier
	s_add_i32 s24, 0, 0x14000
	v_add_u32_e32 v162, s24, v165
	s_add_i32 s23, s23, s28
	ds_read_b128 v[216:219], v162
	ds_read_b128 v[220:223], v162 offset:1024
	ds_read_b128 v[224:227], v162 offset:2048
	ds_read_b128 v[228:231], v162 offset:3072
	v_lshl_add_u64 v[162:163], s[10:11], 0, v[132:133]
	s_mov_b32 m0, s23
	v_lshl_add_u64 v[184:185], s[10:11], 0, v[136:137]
	global_load_lds_dwordx4 v[162:163], off
	s_add_i32 m0, s23, 0x2000
	s_nop 0
	global_load_lds_dwordx4 v[184:185], off
	s_barrier
	s_waitcnt lgkmcnt(0)
	s_waitcnt lgkmcnt(0)
	v_mfma_f32_16x16x32_bf16 v[118:121], v[216:219], v[158:161], v[118:121]
	v_mfma_f32_16x16x32_bf16 v[114:117], v[224:227], v[158:161], v[114:117]
	v_mfma_f32_16x16x32_bf16 v[102:105], v[216:219], v[172:175], v[102:105]
	v_mfma_f32_16x16x32_bf16 v[98:101], v[224:227], v[172:175], v[98:101]
	v_mfma_f32_16x16x32_bf16 v[86:89], v[216:219], v[180:183], v[86:89]
	v_mfma_f32_16x16x32_bf16 v[82:85], v[224:227], v[180:183], v[82:85]
	v_mfma_f32_16x16x32_bf16 v[70:73], v[216:219], v[208:211], v[70:73]
	v_mfma_f32_16x16x32_bf16 v[66:69], v[224:227], v[208:211], v[66:69]
	v_mfma_f32_16x16x32_bf16 v[118:121], v[220:223], v[168:171], v[118:121]
	v_mfma_f32_16x16x32_bf16 v[114:117], v[228:231], v[168:171], v[114:117]
	v_mfma_f32_16x16x32_bf16 v[102:105], v[220:223], v[176:179], v[102:105]
	v_mfma_f32_16x16x32_bf16 v[98:101], v[228:231], v[176:179], v[98:101]
	v_mfma_f32_16x16x32_bf16 v[86:89], v[220:223], v[204:207], v[86:89]
	v_mfma_f32_16x16x32_bf16 v[82:85], v[228:231], v[204:207], v[82:85]
	v_mfma_f32_16x16x32_bf16 v[70:73], v[220:223], v[212:215], v[70:73]
	v_mfma_f32_16x16x32_bf16 v[66:69], v[228:231], v[212:215], v[66:69]
	s_mov_b32 m0, s29
	v_lshl_add_u64 v[232:233], s[4:5], 0, v[130:131]
	s_barrier
	ds_read_b128 v[158:161], v166 offset:16384
	ds_read_b128 v[168:171], v166 offset:17408
	ds_read_b128 v[172:175], v166 offset:18432
	ds_read_b128 v[176:179], v166 offset:19456
	ds_read_b128 v[180:183], v166 offset:20480
	ds_read_b128 v[204:207], v166 offset:21504
	ds_read_b128 v[208:211], v166 offset:22528
	ds_read_b128 v[212:215], v166 offset:23552
	global_load_lds_dwordx4 v[232:233], off
	v_lshl_add_u64 v[234:235], s[4:5], 0, v[134:135]
	s_mov_b32 m0, s30
	s_nop 0
	global_load_lds_dwordx4 v[234:235], off
	s_barrier
	s_waitcnt lgkmcnt(0)
	s_waitcnt lgkmcnt(0)
	v_mfma_f32_16x16x32_bf16 v[62:65], v[142:145], v[158:161], v[62:65]
	v_mfma_f32_16x16x32_bf16 v[58:61], v[150:153], v[158:161], v[58:61]
	v_mfma_f32_16x16x32_bf16 v[46:49], v[142:145], v[172:175], v[46:49]
	v_mfma_f32_16x16x32_bf16 v[42:45], v[150:153], v[172:175], v[42:45]
	v_mfma_f32_16x16x32_bf16 v[30:33], v[142:145], v[180:183], v[30:33]
	v_mfma_f32_16x16x32_bf16 v[26:29], v[150:153], v[180:183], v[26:29]
	v_mfma_f32_16x16x32_bf16 v[14:17], v[142:145], v[208:211], v[14:17]
	v_mfma_f32_16x16x32_bf16 v[10:13], v[150:153], v[208:211], v[10:13]
	v_mfma_f32_16x16x32_bf16 v[62:65], v[146:149], v[168:171], v[62:65]
	v_mfma_f32_16x16x32_bf16 v[58:61], v[154:157], v[168:171], v[58:61]
	v_mfma_f32_16x16x32_bf16 v[46:49], v[146:149], v[176:179], v[46:49]
	v_mfma_f32_16x16x32_bf16 v[42:45], v[154:157], v[176:179], v[42:45]
	v_mfma_f32_16x16x32_bf16 v[30:33], v[146:149], v[204:207], v[30:33]
	v_mfma_f32_16x16x32_bf16 v[26:29], v[154:157], v[204:207], v[26:29]
	v_mfma_f32_16x16x32_bf16 v[14:17], v[146:149], v[212:215], v[14:17]
	v_mfma_f32_16x16x32_bf16 v[10:13], v[154:157], v[212:215], v[10:13]
	s_barrier
	s_add_u32 s10, s10, s92
	s_addc_u32 s11, s11, 0
	s_add_i32 s23, s24, s28
	v_lshl_add_u64 v[236:237], s[10:11], 0, v[132:133]
	s_mov_b32 m0, s23
	v_lshl_add_u64 v[238:239], s[10:11], 0, v[136:137]
	global_load_lds_dwordx4 v[236:237], off
	s_add_i32 m0, s23, 0x2000
	s_nop 0
	global_load_lds_dwordx4 v[238:239], off
	s_waitcnt vmcnt(6)
	s_barrier
	v_mfma_f32_16x16x32_bf16 v[54:57], v[216:219], v[158:161], v[54:57]
	v_mfma_f32_16x16x32_bf16 v[50:53], v[224:227], v[158:161], v[50:53]
	v_mfma_f32_16x16x32_bf16 v[38:41], v[216:219], v[172:175], v[38:41]
	v_mfma_f32_16x16x32_bf16 v[34:37], v[224:227], v[172:175], v[34:37]
	v_mfma_f32_16x16x32_bf16 v[22:25], v[216:219], v[180:183], v[22:25]
	v_mfma_f32_16x16x32_bf16 v[18:21], v[224:227], v[180:183], v[18:21]
	v_mfma_f32_16x16x32_bf16 v[6:9], v[216:219], v[208:211], v[6:9]
	v_mfma_f32_16x16x32_bf16 v[2:5], v[224:227], v[208:211], v[2:5]
	v_mfma_f32_16x16x32_bf16 v[54:57], v[220:223], v[168:171], v[54:57]
	v_mfma_f32_16x16x32_bf16 v[50:53], v[228:231], v[168:171], v[50:53]
	v_mfma_f32_16x16x32_bf16 v[38:41], v[220:223], v[176:179], v[38:41]
	v_mfma_f32_16x16x32_bf16 v[34:37], v[228:231], v[176:179], v[34:37]
	v_mfma_f32_16x16x32_bf16 v[22:25], v[220:223], v[204:207], v[22:25]
	v_mfma_f32_16x16x32_bf16 v[18:21], v[228:231], v[204:207], v[18:21]
	v_mfma_f32_16x16x32_bf16 v[6:9], v[220:223], v[212:215], v[6:9]
	v_mfma_f32_16x16x32_bf16 v[2:5], v[228:231], v[212:215], v[2:5]
	s_add_i32 s10, 0, 0x18000
	v_add_u32_e32 v154, s10, v165
	s_barrier
	ds_read_b128 v[142:145], v154
	ds_read_b128 v[146:149], v154 offset:1024
	ds_read_b128 v[150:153], v154 offset:2048
	ds_read_b128 v[154:157], v154 offset:3072
	s_add_u32 s4, s4, s92
	s_addc_u32 s5, s5, 0
	s_mov_b32 m0, s31
	v_lshl_add_u64 v[216:217], s[4:5], 0, v[130:131]
	ds_read_b128 v[158:161], v166 offset:32768
	ds_read_b128 v[168:171], v166 offset:33792
	ds_read_b128 v[172:175], v166 offset:34816
	ds_read_b128 v[176:179], v166 offset:35840
	ds_read_b128 v[180:183], v166 offset:36864
	ds_read_b128 v[204:207], v166 offset:37888
	ds_read_b128 v[208:211], v166 offset:38912
	ds_read_b128 v[212:215], v166 offset:39936
	global_load_lds_dwordx4 v[216:217], off
	v_lshl_add_u64 v[216:217], s[4:5], 0, v[134:135]
	s_mov_b32 m0, s34
	s_nop 0
	global_load_lds_dwordx4 v[216:217], off
	s_waitcnt lgkmcnt(8)
	s_barrier
	s_waitcnt lgkmcnt(0)
	s_waitcnt lgkmcnt(0)
	v_mfma_f32_16x16x32_bf16 v[126:129], v[142:145], v[158:161], v[126:129]
	v_mfma_f32_16x16x32_bf16 v[122:125], v[150:153], v[158:161], v[122:125]
	v_mfma_f32_16x16x32_bf16 v[110:113], v[142:145], v[172:175], v[110:113]
	v_mfma_f32_16x16x32_bf16 v[106:109], v[150:153], v[172:175], v[106:109]
	v_mfma_f32_16x16x32_bf16 v[94:97], v[142:145], v[180:183], v[94:97]
	v_mfma_f32_16x16x32_bf16 v[90:93], v[150:153], v[180:183], v[90:93]
	v_mfma_f32_16x16x32_bf16 v[78:81], v[142:145], v[208:211], v[78:81]
	v_mfma_f32_16x16x32_bf16 v[74:77], v[150:153], v[208:211], v[74:77]
	v_mfma_f32_16x16x32_bf16 v[126:129], v[146:149], v[168:171], v[126:129]
	v_mfma_f32_16x16x32_bf16 v[122:125], v[154:157], v[168:171], v[122:125]
	v_mfma_f32_16x16x32_bf16 v[110:113], v[146:149], v[176:179], v[110:113]
	v_mfma_f32_16x16x32_bf16 v[106:109], v[154:157], v[176:179], v[106:109]
	v_mfma_f32_16x16x32_bf16 v[94:97], v[146:149], v[204:207], v[94:97]
	v_mfma_f32_16x16x32_bf16 v[90:93], v[154:157], v[204:207], v[90:93]
	v_mfma_f32_16x16x32_bf16 v[78:81], v[146:149], v[212:215], v[78:81]
	v_mfma_f32_16x16x32_bf16 v[74:77], v[154:157], v[212:215], v[74:77]
	s_barrier
	s_add_i32 s4, 0, 0x1c000
	s_add_i32 s5, s10, s28
	v_add_u32_e32 v167, s4, v165
	v_lshl_add_u64 v[162:163], v[162:163], 0, s[6:7]
	s_mov_b32 m0, s5
	ds_read_b128 v[216:219], v167
	ds_read_b128 v[220:223], v167 offset:1024
	ds_read_b128 v[224:227], v167 offset:2048
	ds_read_b128 v[228:231], v167 offset:3072
	global_load_lds_dwordx4 v[162:163], off
	v_lshl_add_u64 v[162:163], v[184:185], 0, s[6:7]
	s_add_i32 m0, s5, 0x2000
	s_nop 0
	global_load_lds_dwordx4 v[162:163], off
	s_barrier
	s_waitcnt lgkmcnt(0)
	s_waitcnt lgkmcnt(0)
	v_mfma_f32_16x16x32_bf16 v[118:121], v[216:219], v[158:161], v[118:121]
	v_mfma_f32_16x16x32_bf16 v[114:117], v[224:227], v[158:161], v[114:117]
	v_mfma_f32_16x16x32_bf16 v[102:105], v[216:219], v[172:175], v[102:105]
	v_mfma_f32_16x16x32_bf16 v[98:101], v[224:227], v[172:175], v[98:101]
	v_mfma_f32_16x16x32_bf16 v[86:89], v[216:219], v[180:183], v[86:89]
	v_mfma_f32_16x16x32_bf16 v[82:85], v[224:227], v[180:183], v[82:85]
	v_mfma_f32_16x16x32_bf16 v[70:73], v[216:219], v[208:211], v[70:73]
	v_mfma_f32_16x16x32_bf16 v[66:69], v[224:227], v[208:211], v[66:69]
	v_mfma_f32_16x16x32_bf16 v[118:121], v[220:223], v[168:171], v[118:121]
	v_mfma_f32_16x16x32_bf16 v[114:117], v[228:231], v[168:171], v[114:117]
	v_mfma_f32_16x16x32_bf16 v[102:105], v[220:223], v[176:179], v[102:105]
	v_mfma_f32_16x16x32_bf16 v[98:101], v[228:231], v[176:179], v[98:101]
	v_mfma_f32_16x16x32_bf16 v[86:89], v[220:223], v[204:207], v[86:89]
	v_mfma_f32_16x16x32_bf16 v[82:85], v[228:231], v[204:207], v[82:85]
	v_mfma_f32_16x16x32_bf16 v[70:73], v[220:223], v[212:215], v[70:73]
	v_mfma_f32_16x16x32_bf16 v[66:69], v[228:231], v[212:215], v[66:69]
	s_mov_b32 m0, s42
	v_lshl_add_u64 v[162:163], v[232:233], 0, s[6:7]
	s_barrier
	ds_read_b128 v[158:161], v166 offset:49152
	ds_read_b128 v[168:171], v166 offset:50176
	ds_read_b128 v[172:175], v166 offset:51200
	ds_read_b128 v[176:179], v166 offset:52224
	ds_read_b128 v[180:183], v166 offset:53248
	ds_read_b128 v[204:207], v166 offset:54272
	ds_read_b128 v[208:211], v166 offset:55296
	ds_read_b128 v[212:215], v166 offset:56320
	global_load_lds_dwordx4 v[162:163], off
	v_lshl_add_u64 v[162:163], v[234:235], 0, s[6:7]
	s_mov_b32 m0, s43
	s_nop 0
	global_load_lds_dwordx4 v[162:163], off
	s_barrier
	s_waitcnt lgkmcnt(0)
	s_waitcnt lgkmcnt(0)
	v_mfma_f32_16x16x32_bf16 v[62:65], v[142:145], v[158:161], v[62:65]
	v_mfma_f32_16x16x32_bf16 v[58:61], v[150:153], v[158:161], v[58:61]
	v_mfma_f32_16x16x32_bf16 v[46:49], v[142:145], v[172:175], v[46:49]
	v_mfma_f32_16x16x32_bf16 v[42:45], v[150:153], v[172:175], v[42:45]
	v_mfma_f32_16x16x32_bf16 v[30:33], v[142:145], v[180:183], v[30:33]
	v_mfma_f32_16x16x32_bf16 v[26:29], v[150:153], v[180:183], v[26:29]
	v_mfma_f32_16x16x32_bf16 v[14:17], v[142:145], v[208:211], v[14:17]
	v_mfma_f32_16x16x32_bf16 v[10:13], v[150:153], v[208:211], v[10:13]
	v_mfma_f32_16x16x32_bf16 v[62:65], v[146:149], v[168:171], v[62:65]
	v_mfma_f32_16x16x32_bf16 v[58:61], v[154:157], v[168:171], v[58:61]
	v_mfma_f32_16x16x32_bf16 v[46:49], v[146:149], v[176:179], v[46:49]
	v_mfma_f32_16x16x32_bf16 v[42:45], v[154:157], v[176:179], v[42:45]
	v_mfma_f32_16x16x32_bf16 v[30:33], v[146:149], v[204:207], v[30:33]
	v_mfma_f32_16x16x32_bf16 v[26:29], v[154:157], v[204:207], v[26:29]
	v_mfma_f32_16x16x32_bf16 v[14:17], v[146:149], v[212:215], v[14:17]
	v_mfma_f32_16x16x32_bf16 v[10:13], v[154:157], v[212:215], v[10:13]
	s_barrier
	s_add_i32 s4, s4, s28
	v_lshl_add_u64 v[142:143], v[236:237], 0, s[6:7]
	s_mov_b32 m0, s4
	s_nop 0
	global_load_lds_dwordx4 v[142:143], off
	v_lshl_add_u64 v[142:143], v[238:239], 0, s[6:7]
	s_add_i32 m0, s4, 0x2000
	s_nop 0
	global_load_lds_dwordx4 v[142:143], off
	s_waitcnt vmcnt(6)
	s_barrier
	v_mfma_f32_16x16x32_bf16 v[54:57], v[216:219], v[158:161], v[54:57]
	v_mfma_f32_16x16x32_bf16 v[50:53], v[224:227], v[158:161], v[50:53]
	v_mfma_f32_16x16x32_bf16 v[38:41], v[216:219], v[172:175], v[38:41]
	v_mfma_f32_16x16x32_bf16 v[34:37], v[224:227], v[172:175], v[34:37]
	v_mfma_f32_16x16x32_bf16 v[22:25], v[216:219], v[180:183], v[22:25]
	v_mfma_f32_16x16x32_bf16 v[18:21], v[224:227], v[180:183], v[18:21]
	v_mfma_f32_16x16x32_bf16 v[6:9], v[216:219], v[208:211], v[6:9]
	v_mfma_f32_16x16x32_bf16 v[2:5], v[224:227], v[208:211], v[2:5]
	v_mfma_f32_16x16x32_bf16 v[54:57], v[220:223], v[168:171], v[54:57]
	v_mfma_f32_16x16x32_bf16 v[50:53], v[228:231], v[168:171], v[50:53]
	v_mfma_f32_16x16x32_bf16 v[38:41], v[220:223], v[176:179], v[38:41]
	v_mfma_f32_16x16x32_bf16 v[34:37], v[228:231], v[176:179], v[34:37]
	v_mfma_f32_16x16x32_bf16 v[22:25], v[220:223], v[204:207], v[22:25]
	v_mfma_f32_16x16x32_bf16 v[18:21], v[228:231], v[204:207], v[18:21]
	v_mfma_f32_16x16x32_bf16 v[6:9], v[220:223], v[212:215], v[6:9]
	v_mfma_f32_16x16x32_bf16 v[2:5], v[228:231], v[212:215], v[2:5]
	s_add_u32 s0, s0, 0x100
	s_addc_u32 s1, s1, 0
	s_add_u32 s20, s20, 0x100
	s_addc_u32 s21, s21, 0
	s_cmp_ge_u32 s22, s35
	s_mov_b32 s4, s22
	s_barrier
	s_cbranch_scc0 .LBB0_282

.LBB0_330:
	s_andn2_b64 vcc, exec, s[0:1]
	s_cbranch_vccnz .LBB0_642
	s_waitcnt lgkmcnt(0)
	v_bfe_i32 v3, v20, 27, 1
	v_lshlrev_b32_e32 v1, 4, v20
	v_lshrrev_b32_e32 v3, 22, v3
	v_add_u32_e32 v3, v1, v3
	v_and_b32_e32 v3, 0xfffffc00, v3
	v_ashrrev_i32_e32 v2, 31, v20
	v_sub_u32_e32 v3, v1, v3
	v_lshrrev_b32_e32 v2, 26, v2
	v_lshrrev_b32_e32 v4, 4, v3
	v_add_u32_e32 v2, v20, v2
	v_bitop3_b32 v4, v4, v3, 32 bitop3:0x6c
	v_ashrrev_i32_e32 v3, 31, v3
	v_ashrrev_i32_e32 v2, 6, v2
	v_lshrrev_b32_e32 v3, 26, v3
	v_lshlrev_b32_e32 v5, 3, v2
	v_add_u32_e32 v3, v4, v3
	v_and_b32_e32 v5, -16, v5
	v_ashrrev_i32_e32 v3, 6, v3
	v_lshlrev_b32_e32 v2, 5, v2
	v_add_u32_e32 v5, v3, v5
	v_and_b32_e32 v14, 32, v2
	v_mul_i32_i24_e32 v2, 64, v3
	v_sub_u32_e32 v2, v4, v2
	v_lshlrev_b32_e32 v4, 1, v5
	v_lshrrev_b32_e32 v6, 2, v5
	v_and_b32_e32 v3, 3, v3
	s_mov_b32 s0, 0x7fffffe0
	v_ashrrev_i16_sdwa v2, v190, sext(v2) dst_sel:DWORD dst_unused:UNUSED_PAD src0_sel:DWORD src1_sel:BYTE_0
	v_and_b32_e32 v4, 24, v4
	v_and_b32_e32 v6, 4, v6
	v_and_or_b32 v3, v5, s0, v3
	v_bfe_i32 v15, v2, 0, 16
	v_or3_b32 v3, v3, v6, v4
	v_add_u32_e32 v2, v14, v15
	v_mul_lo_u32 v16, v5, s64
	v_mul_lo_u32 v3, v3, s64
	v_add_u32_e32 v1, 0x2000, v1
	v_add_lshl_u32 v146, v2, v16, 1
	v_add_lshl_u32 v148, v3, v2, 1
	v_ashrrev_i32_e32 v2, 31, v1
	v_lshrrev_b32_e32 v2, 22, v2
	v_add_u32_e32 v2, v1, v2
	v_ashrrev_i32_e32 v2, 10, v2
	v_mul_i32_i24_e32 v3, 0x400, v2
	v_sub_u32_e32 v1, v1, v3
	v_lshrrev_b32_e32 v3, 4, v1
	v_bitop3_b32 v1, v3, v1, 32 bitop3:0x6c
	v_ashrrev_i32_e32 v4, 31, v1
	v_lshrrev_b32_e32 v4, 26, v4
	v_lshlrev_b32_e32 v3, 3, v2
	v_add_u32_e32 v4, v1, v4
	v_and_b32_e32 v3, -16, v3
	v_ashrrev_i32_e32 v5, 6, v4
	v_add_u32_e32 v3, v5, v3
	v_and_b32_e32 v5, 3, v5
	s_lshl_b32 s92, s64, 8
	v_and_or_b32 v5, v3, s0, v5
	s_lshl_b64 s[40:41], s[92:93], 1
	s_ashr_i32 s0, s65, 31
	s_mul_i32 s0, s40, s0
	s_mul_hi_u32 s1, s40, s65
	s_add_i32 s0, s1, s0
	s_bfe_u32 s1, s64, 0x10017
	s_mul_i32 s4, s1, s65
	s_add_i32 s10, s0, s4
	s_ashr_i32 s4, s26, 31
	s_mul_i32 s4, s40, s4
	s_mul_hi_u32 s5, s40, s26
	s_ashr_i32 s9, s13, 6
	v_lshlrev_b32_e32 v2, 5, v2
	s_add_i32 s4, s5, s4
	s_mul_i32 s1, s1, s26
	v_and_b32_e32 v17, 32, v2
	v_and_b32_e32 v2, 0xc0, v4
	s_ashr_i32 s8, s13, 8
	s_lshl_b32 s70, s9, 10
	s_add_i32 s1, s4, s1
	s_mul_i32 s4, s40, s26
	v_sub_u32_e32 v1, v1, v2
	v_lshlrev_b32_e32 v2, 1, v3
	v_lshrrev_b32_e32 v4, 2, v3
	s_add_u32 s4, s36, s4
	v_ashrrev_i16_sdwa v1, v190, sext(v1) dst_sel:DWORD dst_unused:UNUSED_PAD src0_sel:DWORD src1_sel:BYTE_0
	v_and_b32_e32 v2, 24, v2
	v_and_b32_e32 v4, 4, v4
	s_addc_u32 s5, s37, s1
	s_add_i32 s71, s70, 0
	v_bfe_i32 v18, v1, 0, 16
	v_or3_b32 v2, v5, v4, v2
	s_add_i32 m0, s71, 0x10000
	v_add_u32_e32 v1, v17, v18
	v_mul_lo_u32 v2, v2, s64
	s_mul_i32 s0, s40, s65
	global_load_lds_dwordx4 v148, s[4:5]
	s_add_i32 m0, s71, 0x12000
	v_add_lshl_u32 v152, v2, v1, 1
	s_add_u32 s0, s56, s0
	v_mul_lo_u32 v19, v3, s64
	global_load_lds_dwordx4 v152, s[4:5]
	s_addc_u32 s1, s52, s10
	s_mov_b32 m0, s71
	s_add_i32 s72, s71, 0x2000
	v_add_lshl_u32 v150, v1, v19, 1
	global_load_lds_dwordx4 v146, s[0:1]
	s_mov_b32 m0, s72
	s_add_u32 s10, s4, s92
	global_load_lds_dwordx4 v150, s[0:1]
	s_addc_u32 s11, s5, 0
	s_add_i32 m0, s71, 0x14000
	v_mov_b32_e32 v149, v0
	v_mov_b32_e32 v153, v0
	global_load_lds_dwordx4 v148, s[10:11]
	s_add_i32 m0, s71, 0x16000
	v_lshl_add_u64 v[10:11], s[10:11], 0, v[148:149]
	v_lshl_add_u64 v[12:13], s[10:11], 0, v[152:153]
	global_load_lds_dwordx4 v152, s[10:11]
	s_add_u32 s10, s0, s92
	s_addc_u32 s11, s1, 0
	s_add_i32 s73, s71, 0x4000
	s_mov_b32 m0, s73
	s_add_i32 s74, s71, 0x6000
	global_load_lds_dwordx4 v146, s[10:11]
	s_mov_b32 m0, s74
	v_writelane_b32 v240, s59, 25
	global_load_lds_dwordx4 v150, s[10:11]
	v_mov_b32_e32 v147, v0
	v_mov_b32_e32 v151, v0
	v_writelane_b32 v240, s58, 26
	v_lshl_add_u64 v[2:3], s[4:5], 0, v[148:149]
	v_lshl_add_u64 v[4:5], s[4:5], 0, v[152:153]
	s_mov_b32 s63, s56
	v_lshl_add_u64 v[6:7], s[0:1], 0, v[146:147]
	v_lshl_add_u64 v[8:9], s[0:1], 0, v[150:151]
	s_cmp_lg_u32 s8, 1
	v_writelane_b32 v240, s13, 27
	s_cbranch_scc1 .LBB0_333
	s_barrier
	s_setprio 1

.LBB0_346:
	s_add_u32 s0, s0, 0x80
	s_addc_u32 s1, s1, 0
	s_add_u32 s12, s4, 0x100
	s_addc_u32 s13, s5, 0
	s_mov_b32 s4, 0
	s_waitcnt lgkmcnt(0)
	s_waitcnt vmcnt(0)
	s_add_i32 s15, s4, 2
	s_add_u32 s10, s0, 0x80
	s_addc_u32 s5, s1, 0
	s_add_i32 s16, 0, 0x10000
	v_add_u32_e32 v142, s16, v205
	ds_read_b128 v[130:133], v142
	ds_read_b128 v[134:137], v142 offset:1024
	ds_read_b128 v[138:141], v142 offset:2048
	ds_read_b128 v[142:145], v142 offset:3072
	s_cmp_eq_u32 s79, s4
	s_cselect_b32 s4, s44, s10
	s_cselect_b32 s5, s45, s5
	s_cselect_b32 s11, s47, s13
	s_cselect_b32 s10, s46, s12
	v_lshl_add_u64 v[212:213], s[0:1], 0, v[154:155]
	s_add_i32 m0, s71, 0xc000
	ds_read_b128 v[158:161], v206
	ds_read_b128 v[162:165], v206 offset:1024
	ds_read_b128 v[166:169], v206 offset:2048
	ds_read_b128 v[170:173], v206 offset:3072
	ds_read_b128 v[174:177], v206 offset:4096
	ds_read_b128 v[178:181], v206 offset:5120
	ds_read_b128 v[182:185], v206 offset:6144
	ds_read_b128 v[208:211], v206 offset:7168
	global_load_lds_dwordx4 v[212:213], off
	v_lshl_add_u64 v[212:213], s[0:1], 0, v[156:157]
	s_add_i32 m0, s71, 0xe000
	s_nop 0
	global_load_lds_dwordx4 v[212:213], off
	s_waitcnt lgkmcnt(8)
	s_barrier
	s_waitcnt lgkmcnt(0)
	s_waitcnt lgkmcnt(0)
	v_mfma_f32_16x16x32_bf16 v[126:129], v[130:133], v[158:161], 0
	v_mfma_f32_16x16x32_bf16 v[122:125], v[138:141], v[158:161], 0
	v_mfma_f32_16x16x32_bf16 v[110:113], v[130:133], v[166:169], 0
	v_mfma_f32_16x16x32_bf16 v[106:109], v[138:141], v[166:169], 0
	v_mfma_f32_16x16x32_bf16 v[94:97], v[130:133], v[174:177], 0
	v_mfma_f32_16x16x32_bf16 v[90:93], v[138:141], v[174:177], 0
	v_mfma_f32_16x16x32_bf16 v[78:81], v[130:133], v[182:185], 0
	v_mfma_f32_16x16x32_bf16 v[74:77], v[138:141], v[182:185], 0
	v_mfma_f32_16x16x32_bf16 v[126:129], v[134:137], v[162:165], v[126:129]
	v_mfma_f32_16x16x32_bf16 v[122:125], v[142:145], v[162:165], v[122:125]
	v_mfma_f32_16x16x32_bf16 v[110:113], v[134:137], v[170:173], v[110:113]
	v_mfma_f32_16x16x32_bf16 v[106:109], v[142:145], v[170:173], v[106:109]
	v_mfma_f32_16x16x32_bf16 v[94:97], v[134:137], v[178:181], v[94:97]
	v_mfma_f32_16x16x32_bf16 v[90:93], v[142:145], v[178:181], v[90:93]
	v_mfma_f32_16x16x32_bf16 v[78:81], v[134:137], v[208:211], v[78:81]
	v_mfma_f32_16x16x32_bf16 v[74:77], v[142:145], v[208:211], v[74:77]
	s_barrier
	s_add_i32 s17, 0, 0x14000
	s_add_i32 s16, s16, s70
	v_add_u32_e32 v207, s17, v205
	v_lshl_add_u64 v[228:229], s[10:11], 0, v[148:149]
	s_mov_b32 m0, s16
	ds_read_b128 v[212:215], v207
	ds_read_b128 v[216:219], v207 offset:1024
	ds_read_b128 v[220:223], v207 offset:2048
	ds_read_b128 v[224:227], v207 offset:3072
	global_load_lds_dwordx4 v[228:229], off
	v_lshl_add_u64 v[230:231], s[10:11], 0, v[152:153]
	s_add_i32 m0, s16, 0x2000
	s_nop 0
	global_load_lds_dwordx4 v[230:231], off
	s_barrier
	s_waitcnt lgkmcnt(0)
	s_waitcnt lgkmcnt(0)
	v_mfma_f32_16x16x32_bf16 v[118:121], v[212:215], v[158:161], 0
	v_mfma_f32_16x16x32_bf16 v[114:117], v[220:223], v[158:161], 0
	v_mfma_f32_16x16x32_bf16 v[102:105], v[212:215], v[166:169], 0
	v_mfma_f32_16x16x32_bf16 v[98:101], v[220:223], v[166:169], 0
	v_mfma_f32_16x16x32_bf16 v[86:89], v[212:215], v[174:177], 0
	v_mfma_f32_16x16x32_bf16 v[82:85], v[220:223], v[174:177], 0
	v_mfma_f32_16x16x32_bf16 v[70:73], v[212:215], v[182:185], 0
	v_mfma_f32_16x16x32_bf16 v[66:69], v[220:223], v[182:185], 0
	v_mfma_f32_16x16x32_bf16 v[118:121], v[216:219], v[162:165], v[118:121]
	v_mfma_f32_16x16x32_bf16 v[114:117], v[224:227], v[162:165], v[114:117]
	v_mfma_f32_16x16x32_bf16 v[102:105], v[216:219], v[170:173], v[102:105]
	v_mfma_f32_16x16x32_bf16 v[98:101], v[224:227], v[170:173], v[98:101]
	v_mfma_f32_16x16x32_bf16 v[86:89], v[216:219], v[178:181], v[86:89]
	v_mfma_f32_16x16x32_bf16 v[82:85], v[224:227], v[178:181], v[82:85]
	v_mfma_f32_16x16x32_bf16 v[70:73], v[216:219], v[208:211], v[70:73]
	v_mfma_f32_16x16x32_bf16 v[66:69], v[224:227], v[208:211], v[66:69]
	s_mov_b32 m0, s71
	v_lshl_add_u64 v[232:233], s[4:5], 0, v[146:147]
	s_barrier
	ds_read_b128 v[158:161], v206 offset:16384
	ds_read_b128 v[162:165], v206 offset:17408
	ds_read_b128 v[166:169], v206 offset:18432
	ds_read_b128 v[170:173], v206 offset:19456
	ds_read_b128 v[174:177], v206 offset:20480
	ds_read_b128 v[178:181], v206 offset:21504
	ds_read_b128 v[182:185], v206 offset:22528
	ds_read_b128 v[208:211], v206 offset:23552
	global_load_lds_dwordx4 v[232:233], off
	v_lshl_add_u64 v[234:235], s[4:5], 0, v[150:151]
	s_mov_b32 m0, s72
	s_nop 0
	global_load_lds_dwordx4 v[234:235], off
	s_barrier
	s_waitcnt lgkmcnt(0)
	s_waitcnt lgkmcnt(0)
	v_mfma_f32_16x16x32_bf16 v[62:65], v[130:133], v[158:161], 0
	v_mfma_f32_16x16x32_bf16 v[58:61], v[138:141], v[158:161], 0
	v_mfma_f32_16x16x32_bf16 v[46:49], v[130:133], v[166:169], 0
	v_mfma_f32_16x16x32_bf16 v[42:45], v[138:141], v[166:169], 0
	v_mfma_f32_16x16x32_bf16 v[30:33], v[130:133], v[174:177], 0
	v_mfma_f32_16x16x32_bf16 v[26:29], v[138:141], v[174:177], 0
	v_mfma_f32_16x16x32_bf16 v[14:17], v[130:133], v[182:185], 0
	v_mfma_f32_16x16x32_bf16 v[10:13], v[138:141], v[182:185], 0
	v_mfma_f32_16x16x32_bf16 v[62:65], v[134:137], v[162:165], v[62:65]
	v_mfma_f32_16x16x32_bf16 v[58:61], v[142:145], v[162:165], v[58:61]
	v_mfma_f32_16x16x32_bf16 v[46:49], v[134:137], v[170:173], v[46:49]
	v_mfma_f32_16x16x32_bf16 v[42:45], v[142:145], v[170:173], v[42:45]
	v_mfma_f32_16x16x32_bf16 v[30:33], v[134:137], v[178:181], v[30:33]
	v_mfma_f32_16x16x32_bf16 v[26:29], v[142:145], v[178:181], v[26:29]
	v_mfma_f32_16x16x32_bf16 v[14:17], v[134:137], v[208:211], v[14:17]
	v_mfma_f32_16x16x32_bf16 v[10:13], v[142:145], v[208:211], v[10:13]
	s_barrier
	s_add_u32 s10, s10, s92
	s_addc_u32 s11, s11, 0
	s_add_i32 s16, s17, s70
	v_lshl_add_u64 v[236:237], s[10:11], 0, v[148:149]
	s_mov_b32 m0, s16
	v_lshl_add_u64 v[238:239], s[10:11], 0, v[152:153]
	global_load_lds_dwordx4 v[236:237], off
	s_add_i32 m0, s16, 0x2000
	s_nop 0
	global_load_lds_dwordx4 v[238:239], off
	s_waitcnt vmcnt(6)
	s_barrier
	v_mfma_f32_16x16x32_bf16 v[54:57], v[212:215], v[158:161], 0
	v_mfma_f32_16x16x32_bf16 v[50:53], v[220:223], v[158:161], 0
	v_mfma_f32_16x16x32_bf16 v[38:41], v[212:215], v[166:169], 0
	v_mfma_f32_16x16x32_bf16 v[34:37], v[220:223], v[166:169], 0
	v_mfma_f32_16x16x32_bf16 v[22:25], v[212:215], v[174:177], 0
	v_mfma_f32_16x16x32_bf16 v[18:21], v[220:223], v[174:177], 0
	v_mfma_f32_16x16x32_bf16 v[6:9], v[212:215], v[182:185], 0
	v_mfma_f32_16x16x32_bf16 v[2:5], v[220:223], v[182:185], 0
	v_mfma_f32_16x16x32_bf16 v[54:57], v[216:219], v[162:165], v[54:57]
	v_mfma_f32_16x16x32_bf16 v[50:53], v[224:227], v[162:165], v[50:53]
	v_mfma_f32_16x16x32_bf16 v[38:41], v[216:219], v[170:173], v[38:41]
	v_mfma_f32_16x16x32_bf16 v[34:37], v[224:227], v[170:173], v[34:37]
	v_mfma_f32_16x16x32_bf16 v[22:25], v[216:219], v[178:181], v[22:25]
	v_mfma_f32_16x16x32_bf16 v[18:21], v[224:227], v[178:181], v[18:21]
	v_mfma_f32_16x16x32_bf16 v[6:9], v[216:219], v[208:211], v[6:9]
	v_mfma_f32_16x16x32_bf16 v[2:5], v[224:227], v[208:211], v[2:5]
	s_add_i32 s10, 0, 0x18000
	v_add_u32_e32 v142, s10, v205
	s_barrier
	ds_read_b128 v[130:133], v142
	ds_read_b128 v[134:137], v142 offset:1024
	ds_read_b128 v[138:141], v142 offset:2048
	ds_read_b128 v[142:145], v142 offset:3072
	s_add_u32 s4, s4, s92
	s_addc_u32 s5, s5, 0
	s_mov_b32 m0, s73
	v_lshl_add_u64 v[212:213], s[4:5], 0, v[146:147]
	ds_read_b128 v[158:161], v206 offset:32768
	ds_read_b128 v[162:165], v206 offset:33792
	ds_read_b128 v[166:169], v206 offset:34816
	ds_read_b128 v[170:173], v206 offset:35840
	ds_read_b128 v[174:177], v206 offset:36864
	ds_read_b128 v[178:181], v206 offset:37888
	ds_read_b128 v[182:185], v206 offset:38912
	ds_read_b128 v[208:211], v206 offset:39936
	global_load_lds_dwordx4 v[212:213], off
	v_lshl_add_u64 v[212:213], s[4:5], 0, v[150:151]
	s_mov_b32 m0, s74
	s_nop 0
	global_load_lds_dwordx4 v[212:213], off
	s_waitcnt lgkmcnt(8)
	s_barrier
	s_waitcnt lgkmcnt(0)
	s_waitcnt lgkmcnt(0)
	v_mfma_f32_16x16x32_bf16 v[126:129], v[130:133], v[158:161], v[126:129]
	v_mfma_f32_16x16x32_bf16 v[122:125], v[138:141], v[158:161], v[122:125]
	v_mfma_f32_16x16x32_bf16 v[110:113], v[130:133], v[166:169], v[110:113]
	v_mfma_f32_16x16x32_bf16 v[106:109], v[138:141], v[166:169], v[106:109]
	v_mfma_f32_16x16x32_bf16 v[94:97], v[130:133], v[174:177], v[94:97]
	v_mfma_f32_16x16x32_bf16 v[90:93], v[138:141], v[174:177], v[90:93]
	v_mfma_f32_16x16x32_bf16 v[78:81], v[130:133], v[182:185], v[78:81]
	v_mfma_f32_16x16x32_bf16 v[74:77], v[138:141], v[182:185], v[74:77]
	v_mfma_f32_16x16x32_bf16 v[126:129], v[134:137], v[162:165], v[126:129]
	v_mfma_f32_16x16x32_bf16 v[122:125], v[142:145], v[162:165], v[122:125]
	v_mfma_f32_16x16x32_bf16 v[110:113], v[134:137], v[170:173], v[110:113]
	v_mfma_f32_16x16x32_bf16 v[106:109], v[142:145], v[170:173], v[106:109]
	v_mfma_f32_16x16x32_bf16 v[94:97], v[134:137], v[178:181], v[94:97]
	v_mfma_f32_16x16x32_bf16 v[90:93], v[142:145], v[178:181], v[90:93]
	v_mfma_f32_16x16x32_bf16 v[78:81], v[134:137], v[208:211], v[78:81]
	v_mfma_f32_16x16x32_bf16 v[74:77], v[142:145], v[208:211], v[74:77]
	s_barrier
	s_add_i32 s4, 0, 0x1c000
	s_add_i32 s5, s10, s70
	v_add_u32_e32 v207, s4, v205
	v_lshl_add_u64 v[228:229], v[228:229], 0, s[6:7]
	s_mov_b32 m0, s5
	ds_read_b128 v[212:215], v207
	ds_read_b128 v[216:219], v207 offset:1024
	ds_read_b128 v[220:223], v207 offset:2048
	ds_read_b128 v[224:227], v207 offset:3072
	global_load_lds_dwordx4 v[228:229], off
	v_lshl_add_u64 v[228:229], v[230:231], 0, s[6:7]
	s_add_i32 m0, s5, 0x2000
	s_nop 0
	global_load_lds_dwordx4 v[228:229], off
	s_barrier
	s_waitcnt lgkmcnt(0)
	s_waitcnt lgkmcnt(0)
	v_mfma_f32_16x16x32_bf16 v[118:121], v[212:215], v[158:161], v[118:121]
	v_mfma_f32_16x16x32_bf16 v[114:117], v[220:223], v[158:161], v[114:117]
	v_mfma_f32_16x16x32_bf16 v[102:105], v[212:215], v[166:169], v[102:105]
	v_mfma_f32_16x16x32_bf16 v[98:101], v[220:223], v[166:169], v[98:101]
	v_mfma_f32_16x16x32_bf16 v[86:89], v[212:215], v[174:177], v[86:89]
	v_mfma_f32_16x16x32_bf16 v[82:85], v[220:223], v[174:177], v[82:85]
	v_mfma_f32_16x16x32_bf16 v[70:73], v[212:215], v[182:185], v[70:73]
	v_mfma_f32_16x16x32_bf16 v[66:69], v[220:223], v[182:185], v[66:69]
	v_mfma_f32_16x16x32_bf16 v[118:121], v[216:219], v[162:165], v[118:121]
	v_mfma_f32_16x16x32_bf16 v[114:117], v[224:227], v[162:165], v[114:117]
	v_mfma_f32_16x16x32_bf16 v[102:105], v[216:219], v[170:173], v[102:105]
	v_mfma_f32_16x16x32_bf16 v[98:101], v[224:227], v[170:173], v[98:101]
	v_mfma_f32_16x16x32_bf16 v[86:89], v[216:219], v[178:181], v[86:89]
	v_mfma_f32_16x16x32_bf16 v[82:85], v[224:227], v[178:181], v[82:85]
	v_mfma_f32_16x16x32_bf16 v[70:73], v[216:219], v[208:211], v[70:73]
	v_mfma_f32_16x16x32_bf16 v[66:69], v[224:227], v[208:211], v[66:69]
	s_mov_b32 m0, s77
	v_lshl_add_u64 v[228:229], v[232:233], 0, s[6:7]
	s_barrier
	ds_read_b128 v[158:161], v206 offset:49152
	ds_read_b128 v[162:165], v206 offset:50176
	ds_read_b128 v[166:169], v206 offset:51200
	ds_read_b128 v[170:173], v206 offset:52224
	ds_read_b128 v[174:177], v206 offset:53248
	ds_read_b128 v[178:181], v206 offset:54272
	ds_read_b128 v[182:185], v206 offset:55296
	ds_read_b128 v[208:211], v206 offset:56320
	global_load_lds_dwordx4 v[228:229], off
	v_lshl_add_u64 v[228:229], v[234:235], 0, s[6:7]
	s_mov_b32 m0, s78
	s_nop 0
	global_load_lds_dwordx4 v[228:229], off
	s_barrier
	s_waitcnt lgkmcnt(0)
	s_waitcnt lgkmcnt(0)
	v_mfma_f32_16x16x32_bf16 v[62:65], v[130:133], v[158:161], v[62:65]
	v_mfma_f32_16x16x32_bf16 v[58:61], v[138:141], v[158:161], v[58:61]
	v_mfma_f32_16x16x32_bf16 v[46:49], v[130:133], v[166:169], v[46:49]
	v_mfma_f32_16x16x32_bf16 v[42:45], v[138:141], v[166:169], v[42:45]
	v_mfma_f32_16x16x32_bf16 v[30:33], v[130:133], v[174:177], v[30:33]
	v_mfma_f32_16x16x32_bf16 v[26:29], v[138:141], v[174:177], v[26:29]
	v_mfma_f32_16x16x32_bf16 v[14:17], v[130:133], v[182:185], v[14:17]
	v_mfma_f32_16x16x32_bf16 v[10:13], v[138:141], v[182:185], v[10:13]
	v_mfma_f32_16x16x32_bf16 v[62:65], v[134:137], v[162:165], v[62:65]
	v_mfma_f32_16x16x32_bf16 v[58:61], v[142:145], v[162:165], v[58:61]
	v_mfma_f32_16x16x32_bf16 v[46:49], v[134:137], v[170:173], v[46:49]
	v_mfma_f32_16x16x32_bf16 v[42:45], v[142:145], v[170:173], v[42:45]
	v_mfma_f32_16x16x32_bf16 v[30:33], v[134:137], v[178:181], v[30:33]
	v_mfma_f32_16x16x32_bf16 v[26:29], v[142:145], v[178:181], v[26:29]
	v_mfma_f32_16x16x32_bf16 v[14:17], v[134:137], v[208:211], v[14:17]
	v_mfma_f32_16x16x32_bf16 v[10:13], v[142:145], v[208:211], v[10:13]
	s_barrier
	s_add_i32 s4, s4, s70
	v_lshl_add_u64 v[130:131], v[236:237], 0, s[6:7]
	s_mov_b32 m0, s4
	s_nop 0
	global_load_lds_dwordx4 v[130:131], off
	v_lshl_add_u64 v[130:131], v[238:239], 0, s[6:7]
	s_add_i32 m0, s4, 0x2000
	s_nop 0
	global_load_lds_dwordx4 v[130:131], off
	s_waitcnt vmcnt(6)
	s_barrier
	v_mfma_f32_16x16x32_bf16 v[54:57], v[212:215], v[158:161], v[54:57]
	v_mfma_f32_16x16x32_bf16 v[50:53], v[220:223], v[158:161], v[50:53]
	v_mfma_f32_16x16x32_bf16 v[38:41], v[212:215], v[166:169], v[38:41]
	v_mfma_f32_16x16x32_bf16 v[34:37], v[220:223], v[166:169], v[34:37]
	v_mfma_f32_16x16x32_bf16 v[22:25], v[212:215], v[174:177], v[22:25]
	v_mfma_f32_16x16x32_bf16 v[18:21], v[220:223], v[174:177], v[18:21]
	v_mfma_f32_16x16x32_bf16 v[6:9], v[212:215], v[182:185], v[6:9]
	v_mfma_f32_16x16x32_bf16 v[2:5], v[220:223], v[182:185], v[2:5]
	v_mfma_f32_16x16x32_bf16 v[54:57], v[216:219], v[162:165], v[54:57]
	v_mfma_f32_16x16x32_bf16 v[50:53], v[224:227], v[162:165], v[50:53]
	v_mfma_f32_16x16x32_bf16 v[38:41], v[216:219], v[170:173], v[38:41]
	v_mfma_f32_16x16x32_bf16 v[34:37], v[224:227], v[170:173], v[34:37]
	v_mfma_f32_16x16x32_bf16 v[22:25], v[216:219], v[178:181], v[22:25]
	v_mfma_f32_16x16x32_bf16 v[18:21], v[224:227], v[178:181], v[18:21]
	v_mfma_f32_16x16x32_bf16 v[6:9], v[216:219], v[208:211], v[6:9]
	v_mfma_f32_16x16x32_bf16 v[2:5], v[224:227], v[208:211], v[2:5]
	s_add_u32 s0, s0, 0x100
	s_addc_u32 s1, s1, 0
	s_add_u32 s12, s12, 0x100
	s_addc_u32 s13, s13, 0
	s_cmp_ge_u32 s15, s75
	s_mov_b32 s4, s15
	s_barrier
	s_cbranch_scc1 .Lkexit_347
.LBB0_347:
	s_add_i32 s15, s4, 2
	s_add_u32 s10, s0, 0x80
	s_addc_u32 s5, s1, 0
	s_add_i32 s16, 0, 0x10000
	v_add_u32_e32 v142, s16, v205
	ds_read_b128 v[130:133], v142
	ds_read_b128 v[134:137], v142 offset:1024
	ds_read_b128 v[138:141], v142 offset:2048
	ds_read_b128 v[142:145], v142 offset:3072
	s_cmp_eq_u32 s79, s4
	s_cselect_b32 s4, s44, s10
	s_cselect_b32 s5, s45, s5
	s_cselect_b32 s11, s47, s13
	s_cselect_b32 s10, s46, s12
	v_lshl_add_u64 v[212:213], s[0:1], 0, v[154:155]
	s_add_i32 m0, s71, 0xc000
	ds_read_b128 v[158:161], v206
	ds_read_b128 v[162:165], v206 offset:1024
	ds_read_b128 v[166:169], v206 offset:2048
	ds_read_b128 v[170:173], v206 offset:3072
	ds_read_b128 v[174:177], v206 offset:4096
	ds_read_b128 v[178:181], v206 offset:5120
	ds_read_b128 v[182:185], v206 offset:6144
	ds_read_b128 v[208:211], v206 offset:7168
	global_load_lds_dwordx4 v[212:213], off
	v_lshl_add_u64 v[212:213], s[0:1], 0, v[156:157]
	s_add_i32 m0, s71, 0xe000
	s_nop 0
	global_load_lds_dwordx4 v[212:213], off
	s_waitcnt lgkmcnt(8)
	s_barrier
	s_waitcnt lgkmcnt(0)
	s_waitcnt lgkmcnt(0)
	v_mfma_f32_16x16x32_bf16 v[126:129], v[130:133], v[158:161], v[126:129]
	v_mfma_f32_16x16x32_bf16 v[122:125], v[138:141], v[158:161], v[122:125]
	v_mfma_f32_16x16x32_bf16 v[110:113], v[130:133], v[166:169], v[110:113]
	v_mfma_f32_16x16x32_bf16 v[106:109], v[138:141], v[166:169], v[106:109]
	v_mfma_f32_16x16x32_bf16 v[94:97], v[130:133], v[174:177], v[94:97]
	v_mfma_f32_16x16x32_bf16 v[90:93], v[138:141], v[174:177], v[90:93]
	v_mfma_f32_16x16x32_bf16 v[78:81], v[130:133], v[182:185], v[78:81]
	v_mfma_f32_16x16x32_bf16 v[74:77], v[138:141], v[182:185], v[74:77]
	v_mfma_f32_16x16x32_bf16 v[126:129], v[134:137], v[162:165], v[126:129]
	v_mfma_f32_16x16x32_bf16 v[122:125], v[142:145], v[162:165], v[122:125]
	v_mfma_f32_16x16x32_bf16 v[110:113], v[134:137], v[170:173], v[110:113]
	v_mfma_f32_16x16x32_bf16 v[106:109], v[142:145], v[170:173], v[106:109]
	v_mfma_f32_16x16x32_bf16 v[94:97], v[134:137], v[178:181], v[94:97]
	v_mfma_f32_16x16x32_bf16 v[90:93], v[142:145], v[178:181], v[90:93]
	v_mfma_f32_16x16x32_bf16 v[78:81], v[134:137], v[208:211], v[78:81]
	v_mfma_f32_16x16x32_bf16 v[74:77], v[142:145], v[208:211], v[74:77]
	s_barrier
	s_add_i32 s17, 0, 0x14000
	s_add_i32 s16, s16, s70
	v_add_u32_e32 v207, s17, v205
	v_lshl_add_u64 v[228:229], s[10:11], 0, v[148:149]
	s_mov_b32 m0, s16
	ds_read_b128 v[212:215], v207
	ds_read_b128 v[216:219], v207 offset:1024
	ds_read_b128 v[220:223], v207 offset:2048
	ds_read_b128 v[224:227], v207 offset:3072
	global_load_lds_dwordx4 v[228:229], off
	v_lshl_add_u64 v[230:231], s[10:11], 0, v[152:153]
	s_add_i32 m0, s16, 0x2000
	s_nop 0
	global_load_lds_dwordx4 v[230:231], off
	s_barrier
	s_waitcnt lgkmcnt(0)
	s_waitcnt lgkmcnt(0)
	v_mfma_f32_16x16x32_bf16 v[118:121], v[212:215], v[158:161], v[118:121]
	v_mfma_f32_16x16x32_bf16 v[114:117], v[220:223], v[158:161], v[114:117]
	v_mfma_f32_16x16x32_bf16 v[102:105], v[212:215], v[166:169], v[102:105]
	v_mfma_f32_16x16x32_bf16 v[98:101], v[220:223], v[166:169], v[98:101]
	v_mfma_f32_16x16x32_bf16 v[86:89], v[212:215], v[174:177], v[86:89]
	v_mfma_f32_16x16x32_bf16 v[82:85], v[220:223], v[174:177], v[82:85]
	v_mfma_f32_16x16x32_bf16 v[70:73], v[212:215], v[182:185], v[70:73]
	v_mfma_f32_16x16x32_bf16 v[66:69], v[220:223], v[182:185], v[66:69]
	v_mfma_f32_16x16x32_bf16 v[118:121], v[216:219], v[162:165], v[118:121]
	v_mfma_f32_16x16x32_bf16 v[114:117], v[224:227], v[162:165], v[114:117]
	v_mfma_f32_16x16x32_bf16 v[102:105], v[216:219], v[170:173], v[102:105]
	v_mfma_f32_16x16x32_bf16 v[98:101], v[224:227], v[170:173], v[98:101]
	v_mfma_f32_16x16x32_bf16 v[86:89], v[216:219], v[178:181], v[86:89]
	v_mfma_f32_16x16x32_bf16 v[82:85], v[224:227], v[178:181], v[82:85]
	v_mfma_f32_16x16x32_bf16 v[70:73], v[216:219], v[208:211], v[70:73]
	v_mfma_f32_16x16x32_bf16 v[66:69], v[224:227], v[208:211], v[66:69]
	s_mov_b32 m0, s71
	v_lshl_add_u64 v[232:233], s[4:5], 0, v[146:147]
	s_barrier
	ds_read_b128 v[158:161], v206 offset:16384
	ds_read_b128 v[162:165], v206 offset:17408
	ds_read_b128 v[166:169], v206 offset:18432
	ds_read_b128 v[170:173], v206 offset:19456
	ds_read_b128 v[174:177], v206 offset:20480
	ds_read_b128 v[178:181], v206 offset:21504
	ds_read_b128 v[182:185], v206 offset:22528
	ds_read_b128 v[208:211], v206 offset:23552
	global_load_lds_dwordx4 v[232:233], off
	v_lshl_add_u64 v[234:235], s[4:5], 0, v[150:151]
	s_mov_b32 m0, s72
	s_nop 0
	global_load_lds_dwordx4 v[234:235], off
	s_barrier
	s_waitcnt lgkmcnt(0)
	s_waitcnt lgkmcnt(0)
	v_mfma_f32_16x16x32_bf16 v[62:65], v[130:133], v[158:161], v[62:65]
	v_mfma_f32_16x16x32_bf16 v[58:61], v[138:141], v[158:161], v[58:61]
	v_mfma_f32_16x16x32_bf16 v[46:49], v[130:133], v[166:169], v[46:49]
	v_mfma_f32_16x16x32_bf16 v[42:45], v[138:141], v[166:169], v[42:45]
	v_mfma_f32_16x16x32_bf16 v[30:33], v[130:133], v[174:177], v[30:33]
	v_mfma_f32_16x16x32_bf16 v[26:29], v[138:141], v[174:177], v[26:29]
	v_mfma_f32_16x16x32_bf16 v[14:17], v[130:133], v[182:185], v[14:17]
	v_mfma_f32_16x16x32_bf16 v[10:13], v[138:141], v[182:185], v[10:13]
	v_mfma_f32_16x16x32_bf16 v[62:65], v[134:137], v[162:165], v[62:65]
	v_mfma_f32_16x16x32_bf16 v[58:61], v[142:145], v[162:165], v[58:61]
	v_mfma_f32_16x16x32_bf16 v[46:49], v[134:137], v[170:173], v[46:49]
	v_mfma_f32_16x16x32_bf16 v[42:45], v[142:145], v[170:173], v[42:45]
	v_mfma_f32_16x16x32_bf16 v[30:33], v[134:137], v[178:181], v[30:33]
	v_mfma_f32_16x16x32_bf16 v[26:29], v[142:145], v[178:181], v[26:29]
	v_mfma_f32_16x16x32_bf16 v[14:17], v[134:137], v[208:211], v[14:17]
	v_mfma_f32_16x16x32_bf16 v[10:13], v[142:145], v[208:211], v[10:13]
	s_barrier
	s_add_u32 s10, s10, s92
	s_addc_u32 s11, s11, 0
	s_add_i32 s16, s17, s70
	v_lshl_add_u64 v[236:237], s[10:11], 0, v[148:149]
	s_mov_b32 m0, s16
	v_lshl_add_u64 v[238:239], s[10:11], 0, v[152:153]
	global_load_lds_dwordx4 v[236:237], off
	s_add_i32 m0, s16, 0x2000
	s_nop 0
	global_load_lds_dwordx4 v[238:239], off
	s_waitcnt vmcnt(6)
	s_barrier
	v_mfma_f32_16x16x32_bf16 v[54:57], v[212:215], v[158:161], v[54:57]
	v_mfma_f32_16x16x32_bf16 v[50:53], v[220:223], v[158:161], v[50:53]
	v_mfma_f32_16x16x32_bf16 v[38:41], v[212:215], v[166:169], v[38:41]
	v_mfma_f32_16x16x32_bf16 v[34:37], v[220:223], v[166:169], v[34:37]
	v_mfma_f32_16x16x32_bf16 v[22:25], v[212:215], v[174:177], v[22:25]
	v_mfma_f32_16x16x32_bf16 v[18:21], v[220:223], v[174:177], v[18:21]
	v_mfma_f32_16x16x32_bf16 v[6:9], v[212:215], v[182:185], v[6:9]
	v_mfma_f32_16x16x32_bf16 v[2:5], v[220:223], v[182:185], v[2:5]
	v_mfma_f32_16x16x32_bf16 v[54:57], v[216:219], v[162:165], v[54:57]
	v_mfma_f32_16x16x32_bf16 v[50:53], v[224:227], v[162:165], v[50:53]
	v_mfma_f32_16x16x32_bf16 v[38:41], v[216:219], v[170:173], v[38:41]
	v_mfma_f32_16x16x32_bf16 v[34:37], v[224:227], v[170:173], v[34:37]
	v_mfma_f32_16x16x32_bf16 v[22:25], v[216:219], v[178:181], v[22:25]
	v_mfma_f32_16x16x32_bf16 v[18:21], v[224:227], v[178:181], v[18:21]
	v_mfma_f32_16x16x32_bf16 v[6:9], v[216:219], v[208:211], v[6:9]
	v_mfma_f32_16x16x32_bf16 v[2:5], v[224:227], v[208:211], v[2:5]
	s_add_i32 s10, 0, 0x18000
	v_add_u32_e32 v142, s10, v205
	s_barrier
	ds_read_b128 v[130:133], v142
	ds_read_b128 v[134:137], v142 offset:1024
	ds_read_b128 v[138:141], v142 offset:2048
	ds_read_b128 v[142:145], v142 offset:3072
	s_add_u32 s4, s4, s92
	s_addc_u32 s5, s5, 0
	s_mov_b32 m0, s73
	v_lshl_add_u64 v[212:213], s[4:5], 0, v[146:147]
	ds_read_b128 v[158:161], v206 offset:32768
	ds_read_b128 v[162:165], v206 offset:33792
	ds_read_b128 v[166:169], v206 offset:34816
	ds_read_b128 v[170:173], v206 offset:35840
	ds_read_b128 v[174:177], v206 offset:36864
	ds_read_b128 v[178:181], v206 offset:37888
	ds_read_b128 v[182:185], v206 offset:38912
	ds_read_b128 v[208:211], v206 offset:39936
	global_load_lds_dwordx4 v[212:213], off
	v_lshl_add_u64 v[212:213], s[4:5], 0, v[150:151]
	s_mov_b32 m0, s74
	s_nop 0
	global_load_lds_dwordx4 v[212:213], off
	s_waitcnt lgkmcnt(8)
	s_barrier
	s_waitcnt lgkmcnt(0)
	s_waitcnt lgkmcnt(0)
	v_mfma_f32_16x16x32_bf16 v[126:129], v[130:133], v[158:161], v[126:129]
	v_mfma_f32_16x16x32_bf16 v[122:125], v[138:141], v[158:161], v[122:125]
	v_mfma_f32_16x16x32_bf16 v[110:113], v[130:133], v[166:169], v[110:113]
	v_mfma_f32_16x16x32_bf16 v[106:109], v[138:141], v[166:169], v[106:109]
	v_mfma_f32_16x16x32_bf16 v[94:97], v[130:133], v[174:177], v[94:97]
	v_mfma_f32_16x16x32_bf16 v[90:93], v[138:141], v[174:177], v[90:93]
	v_mfma_f32_16x16x32_bf16 v[78:81], v[130:133], v[182:185], v[78:81]
	v_mfma_f32_16x16x32_bf16 v[74:77], v[138:141], v[182:185], v[74:77]
	v_mfma_f32_16x16x32_bf16 v[126:129], v[134:137], v[162:165], v[126:129]
	v_mfma_f32_16x16x32_bf16 v[122:125], v[142:145], v[162:165], v[122:125]
	v_mfma_f32_16x16x32_bf16 v[110:113], v[134:137], v[170:173], v[110:113]
	v_mfma_f32_16x16x32_bf16 v[106:109], v[142:145], v[170:173], v[106:109]
	v_mfma_f32_16x16x32_bf16 v[94:97], v[134:137], v[178:181], v[94:97]
	v_mfma_f32_16x16x32_bf16 v[90:93], v[142:145], v[178:181], v[90:93]
	v_mfma_f32_16x16x32_bf16 v[78:81], v[134:137], v[208:211], v[78:81]
	v_mfma_f32_16x16x32_bf16 v[74:77], v[142:145], v[208:211], v[74:77]
	s_barrier
	s_add_i32 s4, 0, 0x1c000
	s_add_i32 s5, s10, s70
	v_add_u32_e32 v207, s4, v205
	v_lshl_add_u64 v[228:229], v[228:229], 0, s[6:7]
	s_mov_b32 m0, s5
	ds_read_b128 v[212:215], v207
	ds_read_b128 v[216:219], v207 offset:1024
	ds_read_b128 v[220:223], v207 offset:2048
	ds_read_b128 v[224:227], v207 offset:3072
	global_load_lds_dwordx4 v[228:229], off
	v_lshl_add_u64 v[228:229], v[230:231], 0, s[6:7]
	s_add_i32 m0, s5, 0x2000
	s_nop 0
	global_load_lds_dwordx4 v[228:229], off
	s_barrier
	s_waitcnt lgkmcnt(0)
	s_waitcnt lgkmcnt(0)
	v_mfma_f32_16x16x32_bf16 v[118:121], v[212:215], v[158:161], v[118:121]
	v_mfma_f32_16x16x32_bf16 v[114:117], v[220:223], v[158:161], v[114:117]
	v_mfma_f32_16x16x32_bf16 v[102:105], v[212:215], v[166:169], v[102:105]
	v_mfma_f32_16x16x32_bf16 v[98:101], v[220:223], v[166:169], v[98:101]
	v_mfma_f32_16x16x32_bf16 v[86:89], v[212:215], v[174:177], v[86:89]
	v_mfma_f32_16x16x32_bf16 v[82:85], v[220:223], v[174:177], v[82:85]
	v_mfma_f32_16x16x32_bf16 v[70:73], v[212:215], v[182:185], v[70:73]
	v_mfma_f32_16x16x32_bf16 v[66:69], v[220:223], v[182:185], v[66:69]
	v_mfma_f32_16x16x32_bf16 v[118:121], v[216:219], v[162:165], v[118:121]
	v_mfma_f32_16x16x32_bf16 v[114:117], v[224:227], v[162:165], v[114:117]
	v_mfma_f32_16x16x32_bf16 v[102:105], v[216:219], v[170:173], v[102:105]
	v_mfma_f32_16x16x32_bf16 v[98:101], v[224:227], v[170:173], v[98:101]
	v_mfma_f32_16x16x32_bf16 v[86:89], v[216:219], v[178:181], v[86:89]
	v_mfma_f32_16x16x32_bf16 v[82:85], v[224:227], v[178:181], v[82:85]
	v_mfma_f32_16x16x32_bf16 v[70:73], v[216:219], v[208:211], v[70:73]
	v_mfma_f32_16x16x32_bf16 v[66:69], v[224:227], v[208:211], v[66:69]
	s_mov_b32 m0, s77
	v_lshl_add_u64 v[228:229], v[232:233], 0, s[6:7]
	s_barrier
	ds_read_b128 v[158:161], v206 offset:49152
	ds_read_b128 v[162:165], v206 offset:50176
	ds_read_b128 v[166:169], v206 offset:51200
	ds_read_b128 v[170:173], v206 offset:52224
	ds_read_b128 v[174:177], v206 offset:53248
	ds_read_b128 v[178:181], v206 offset:54272
	ds_read_b128 v[182:185], v206 offset:55296
	ds_read_b128 v[208:211], v206 offset:56320
	global_load_lds_dwordx4 v[228:229], off
	v_lshl_add_u64 v[228:229], v[234:235], 0, s[6:7]
	s_mov_b32 m0, s78
	s_nop 0
	global_load_lds_dwordx4 v[228:229], off
	s_barrier
	s_waitcnt lgkmcnt(0)
	s_waitcnt lgkmcnt(0)
	v_mfma_f32_16x16x32_bf16 v[62:65], v[130:133], v[158:161], v[62:65]
	v_mfma_f32_16x16x32_bf16 v[58:61], v[138:141], v[158:161], v[58:61]
	v_mfma_f32_16x16x32_bf16 v[46:49], v[130:133], v[166:169], v[46:49]
	v_mfma_f32_16x16x32_bf16 v[42:45], v[138:141], v[166:169], v[42:45]
	v_mfma_f32_16x16x32_bf16 v[30:33], v[130:133], v[174:177], v[30:33]
	v_mfma_f32_16x16x32_bf16 v[26:29], v[138:141], v[174:177], v[26:29]
	v_mfma_f32_16x16x32_bf16 v[14:17], v[130:133], v[182:185], v[14:17]
	v_mfma_f32_16x16x32_bf16 v[10:13], v[138:141], v[182:185], v[10:13]
	v_mfma_f32_16x16x32_bf16 v[62:65], v[134:137], v[162:165], v[62:65]
	v_mfma_f32_16x16x32_bf16 v[58:61], v[142:145], v[162:165], v[58:61]
	v_mfma_f32_16x16x32_bf16 v[46:49], v[134:137], v[170:173], v[46:49]
	v_mfma_f32_16x16x32_bf16 v[42:45], v[142:145], v[170:173], v[42:45]
	v_mfma_f32_16x16x32_bf16 v[30:33], v[134:137], v[178:181], v[30:33]
	v_mfma_f32_16x16x32_bf16 v[26:29], v[142:145], v[178:181], v[26:29]
	v_mfma_f32_16x16x32_bf16 v[14:17], v[134:137], v[208:211], v[14:17]
	v_mfma_f32_16x16x32_bf16 v[10:13], v[142:145], v[208:211], v[10:13]
	s_barrier
	s_add_i32 s4, s4, s70
	v_lshl_add_u64 v[130:131], v[236:237], 0, s[6:7]
	s_mov_b32 m0, s4
	s_nop 0
	global_load_lds_dwordx4 v[130:131], off
	v_lshl_add_u64 v[130:131], v[238:239], 0, s[6:7]
	s_add_i32 m0, s4, 0x2000
	s_nop 0
	global_load_lds_dwordx4 v[130:131], off
	s_waitcnt vmcnt(6)
	s_barrier
	v_mfma_f32_16x16x32_bf16 v[54:57], v[212:215], v[158:161], v[54:57]
	v_mfma_f32_16x16x32_bf16 v[50:53], v[220:223], v[158:161], v[50:53]
	v_mfma_f32_16x16x32_bf16 v[38:41], v[212:215], v[166:169], v[38:41]
	v_mfma_f32_16x16x32_bf16 v[34:37], v[220:223], v[166:169], v[34:37]
	v_mfma_f32_16x16x32_bf16 v[22:25], v[212:215], v[174:177], v[22:25]
	v_mfma_f32_16x16x32_bf16 v[18:21], v[220:223], v[174:177], v[18:21]
	v_mfma_f32_16x16x32_bf16 v[6:9], v[212:215], v[182:185], v[6:9]
	v_mfma_f32_16x16x32_bf16 v[2:5], v[220:223], v[182:185], v[2:5]
	v_mfma_f32_16x16x32_bf16 v[54:57], v[216:219], v[162:165], v[54:57]
	v_mfma_f32_16x16x32_bf16 v[50:53], v[224:227], v[162:165], v[50:53]
	v_mfma_f32_16x16x32_bf16 v[38:41], v[216:219], v[170:173], v[38:41]
	v_mfma_f32_16x16x32_bf16 v[34:37], v[224:227], v[170:173], v[34:37]
	v_mfma_f32_16x16x32_bf16 v[22:25], v[216:219], v[178:181], v[22:25]
	v_mfma_f32_16x16x32_bf16 v[18:21], v[224:227], v[178:181], v[18:21]
	v_mfma_f32_16x16x32_bf16 v[6:9], v[216:219], v[208:211], v[6:9]
	v_mfma_f32_16x16x32_bf16 v[2:5], v[224:227], v[208:211], v[2:5]
	s_add_u32 s0, s0, 0x100
	s_addc_u32 s1, s1, 0
	s_add_u32 s12, s12, 0x100
	s_addc_u32 s13, s13, 0
	s_cmp_ge_u32 s15, s75
	s_mov_b32 s4, s15
	s_barrier
	s_cbranch_scc0 .LBB0_347

.LBB0_682:
	s_andn2_b64 vcc, exec, s[0:1]
	s_cbranch_vccnz .LBB0_718
	s_waitcnt lgkmcnt(0)
	v_bfe_i32 v3, v8, 27, 1
	v_lshlrev_b32_e32 v1, 4, v8
	v_lshrrev_b32_e32 v3, 22, v3
	v_add_u32_e32 v3, v1, v3
	v_and_b32_e32 v3, 0xfffffc00, v3
	v_ashrrev_i32_e32 v2, 31, v8
	v_sub_u32_e32 v3, v1, v3
	v_lshrrev_b32_e32 v2, 26, v2
	v_lshrrev_b32_e32 v4, 4, v3
	v_add_u32_e32 v2, v8, v2
	v_bitop3_b32 v4, v4, v3, 32 bitop3:0x6c
	v_ashrrev_i32_e32 v3, 31, v3
	v_ashrrev_i32_e32 v2, 6, v2
	v_lshrrev_b32_e32 v3, 26, v3
	v_lshlrev_b32_e32 v5, 3, v2
	v_add_u32_e32 v3, v4, v3
	v_and_b32_e32 v5, -16, v5
	v_ashrrev_i32_e32 v6, 6, v3
	v_add_u32_e32 v5, v6, v5
	v_mul_i32_i24_e32 v3, 64, v6
	v_sub_u32_e32 v3, v4, v3
	v_lshlrev_b32_e32 v4, 1, v5
	v_lshrrev_b32_e32 v9, 2, v5
	v_and_b32_e32 v6, 3, v6
	s_mov_b32 s0, 0x7fffffe0
	v_lshlrev_b32_e32 v2, 5, v2
	v_ashrrev_i16_sdwa v3, v190, sext(v3) dst_sel:DWORD dst_unused:UNUSED_PAD src0_sel:DWORD src1_sel:BYTE_0
	v_and_b32_e32 v4, 24, v4
	v_and_b32_e32 v9, 4, v9
	v_and_or_b32 v6, v5, s0, v6
	v_and_b32_e32 v2, 32, v2
	v_bfe_i32 v3, v3, 0, 16
	v_or3_b32 v6, v6, v9, v4
	v_add_u32_e32 v7, v2, v3
	v_mul_lo_u32 v4, v5, s64
	v_mul_lo_u32 v5, v6, s64
	v_add_u32_e32 v1, 0x2000, v1
	v_add_lshl_u32 v132, v5, v7, 1
	v_ashrrev_i32_e32 v5, 31, v1
	v_lshrrev_b32_e32 v5, 22, v5
	v_add_u32_e32 v5, v1, v5
	v_ashrrev_i32_e32 v5, 10, v5
	v_mul_i32_i24_e32 v6, 0x400, v5
	v_sub_u32_e32 v1, v1, v6
	v_lshrrev_b32_e32 v6, 4, v1
	v_bitop3_b32 v1, v6, v1, 32 bitop3:0x6c
	v_add_lshl_u32 v130, v7, v4, 1
	v_ashrrev_i32_e32 v7, 31, v1
	v_lshrrev_b32_e32 v7, 26, v7
	v_lshlrev_b32_e32 v6, 3, v5
	v_add_u32_e32 v7, v1, v7
	v_and_b32_e32 v6, -16, v6
	v_ashrrev_i32_e32 v9, 6, v7
	v_add_u32_e32 v10, v9, v6
	v_and_b32_e32 v9, 3, v9
	s_lshl_b32 s2, s64, 8
	s_mov_b32 s3, s93
	v_and_or_b32 v9, v10, s0, v9
	s_lshl_b64 s[16:17], s[2:3], 1
	s_ashr_i32 s0, s47, 31
	s_mul_i32 s0, s16, s0
	s_mul_hi_u32 s1, s16, s47
	s_add_i32 s0, s1, s0
	s_bfe_u32 s1, s64, 0x10017
	s_mul_i32 s4, s1, s47
	s_add_i32 s8, s0, s4
	s_ashr_i32 s4, s46, 31
	s_mul_i32 s4, s16, s4
	s_mul_hi_u32 s5, s16, s46
	s_ashr_i32 s10, s20, 6
	s_add_i32 s4, s5, s4
	s_mul_i32 s1, s1, s46
	v_and_b32_e32 v6, 0xc0, v7
	s_ashr_i32 s11, s20, 8
	s_lshl_b32 s21, s10, 10
	s_add_i32 s1, s4, s1
	s_mul_i32 s4, s16, s46
	v_sub_u32_e32 v1, v1, v6
	v_lshlrev_b32_e32 v7, 1, v10
	v_lshrrev_b32_e32 v11, 2, v10
	s_add_u32 s4, s36, s4
	v_lshlrev_b32_e32 v5, 5, v5
	v_ashrrev_i16_sdwa v1, v190, sext(v1) dst_sel:DWORD dst_unused:UNUSED_PAD src0_sel:DWORD src1_sel:BYTE_0
	v_and_b32_e32 v7, 24, v7
	v_and_b32_e32 v11, 4, v11
	s_addc_u32 s5, s37, s1
	s_add_i32 s22, s21, 0
	v_and_b32_e32 v5, 32, v5
	v_bfe_i32 v6, v1, 0, 16
	v_or3_b32 v9, v9, v11, v7
	s_add_i32 m0, s22, 0x10000
	v_add_u32_e32 v1, v5, v6
	v_mul_lo_u32 v9, v9, s64
	s_mul_i32 s0, s16, s47
	global_load_lds_dwordx4 v132, s[4:5]
	s_add_i32 m0, s22, 0x12000
	v_add_lshl_u32 v136, v9, v1, 1
	s_add_u32 s0, s56, s0
	v_mul_lo_u32 v7, v10, s64
	global_load_lds_dwordx4 v136, s[4:5]
	s_addc_u32 s1, s52, s8
	s_mov_b32 m0, s22
	s_add_i32 s23, s22, 0x2000
	v_add_lshl_u32 v134, v1, v7, 1
	global_load_lds_dwordx4 v130, s[0:1]
	s_mov_b32 m0, s23
	s_add_u32 s8, s4, s2
	global_load_lds_dwordx4 v134, s[0:1]
	s_addc_u32 s9, s5, 0
	s_add_i32 m0, s22, 0x14000
	s_nop 0
	global_load_lds_dwordx4 v132, s[8:9]
	s_add_i32 m0, s22, 0x16000
	s_add_u32 s12, s0, s2
	s_addc_u32 s13, s1, 0
	s_add_i32 s24, s22, 0x4000
	global_load_lds_dwordx4 v136, s[8:9]
	s_mov_b32 m0, s24
	s_add_i32 s25, s22, 0x6000
	global_load_lds_dwordx4 v130, s[12:13]
	s_mov_b32 m0, s25
	s_cmp_lg_u32 s11, 1
	global_load_lds_dwordx4 v134, s[12:13]
	s_cbranch_scc1 .LBB0_685
	s_barrier
	s_setprio 1

.LBB0_697:
	s_add_u32 s0, s0, 0x80
	s_addc_u32 s1, s1, 0
	s_add_u32 s48, s4, 0x100
	s_addc_u32 s49, s5, 0
	s_mov_b32 s4, 0
	s_waitcnt lgkmcnt(0)
	s_waitcnt vmcnt(0)
	s_add_i32 s65, s4, 2
	s_add_u32 s18, s0, 0x80
	s_addc_u32 s5, s1, 0
	s_add_i32 s66, 0, 0x10000
	v_add_u32_e32 v146, s66, v149
	ds_read_b128 v[142:145], v146
	ds_read_b128 v[152:155], v146 offset:1024
	ds_read_b128 v[156:159], v146 offset:2048
	ds_read_b128 v[160:163], v146 offset:3072
	s_cmp_eq_u32 s34, s4
	s_cselect_b32 s4, s10, s18
	s_cselect_b32 s5, s11, s5
	s_cselect_b32 s19, s13, s49
	s_cselect_b32 s18, s12, s48
	v_lshl_add_u64 v[146:147], s[0:1], 0, v[138:139]
	s_add_i32 m0, s22, 0xc000
	ds_read_b128 v[164:167], v150
	ds_read_b128 v[168:171], v150 offset:1024
	ds_read_b128 v[172:175], v150 offset:2048
	ds_read_b128 v[176:179], v150 offset:3072
	ds_read_b128 v[180:183], v150 offset:4096
	ds_read_b128 v[204:207], v150 offset:5120
	ds_read_b128 v[208:211], v150 offset:6144
	ds_read_b128 v[212:215], v150 offset:7168
	global_load_lds_dwordx4 v[146:147], off
	v_lshl_add_u64 v[146:147], s[0:1], 0, v[140:141]
	s_add_i32 m0, s22, 0xe000
	s_nop 0
	global_load_lds_dwordx4 v[146:147], off
	s_waitcnt lgkmcnt(8)
	s_barrier
	s_waitcnt lgkmcnt(0)
	s_waitcnt lgkmcnt(0)
	v_mfma_f32_16x16x32_bf16 v[126:129], v[142:145], v[164:167], 0
	v_mfma_f32_16x16x32_bf16 v[122:125], v[156:159], v[164:167], 0
	v_mfma_f32_16x16x32_bf16 v[110:113], v[142:145], v[172:175], 0
	v_mfma_f32_16x16x32_bf16 v[106:109], v[156:159], v[172:175], 0
	v_mfma_f32_16x16x32_bf16 v[94:97], v[142:145], v[180:183], 0
	v_mfma_f32_16x16x32_bf16 v[90:93], v[156:159], v[180:183], 0
	v_mfma_f32_16x16x32_bf16 v[78:81], v[142:145], v[208:211], 0
	v_mfma_f32_16x16x32_bf16 v[74:77], v[156:159], v[208:211], 0
	v_mfma_f32_16x16x32_bf16 v[126:129], v[152:155], v[168:171], v[126:129]
	v_mfma_f32_16x16x32_bf16 v[122:125], v[160:163], v[168:171], v[122:125]
	v_mfma_f32_16x16x32_bf16 v[110:113], v[152:155], v[176:179], v[110:113]
	v_mfma_f32_16x16x32_bf16 v[106:109], v[160:163], v[176:179], v[106:109]
	v_mfma_f32_16x16x32_bf16 v[94:97], v[152:155], v[204:207], v[94:97]
	v_mfma_f32_16x16x32_bf16 v[90:93], v[160:163], v[204:207], v[90:93]
	v_mfma_f32_16x16x32_bf16 v[78:81], v[152:155], v[212:215], v[78:81]
	v_mfma_f32_16x16x32_bf16 v[74:77], v[160:163], v[212:215], v[74:77]
	s_barrier
	s_add_i32 s67, 0, 0x14000
	v_add_u32_e32 v146, s67, v149
	s_add_i32 s66, s66, s21
	ds_read_b128 v[216:219], v146
	ds_read_b128 v[220:223], v146 offset:1024
	ds_read_b128 v[224:227], v146 offset:2048
	ds_read_b128 v[228:231], v146 offset:3072
	v_lshl_add_u64 v[146:147], s[18:19], 0, v[132:133]
	s_mov_b32 m0, s66
	v_lshl_add_u64 v[184:185], s[18:19], 0, v[136:137]
	global_load_lds_dwordx4 v[146:147], off
	s_add_i32 m0, s66, 0x2000
	s_nop 0
	global_load_lds_dwordx4 v[184:185], off
	s_barrier
	s_waitcnt lgkmcnt(0)
	s_waitcnt lgkmcnt(0)
	v_mfma_f32_16x16x32_bf16 v[118:121], v[216:219], v[164:167], 0
	v_mfma_f32_16x16x32_bf16 v[114:117], v[224:227], v[164:167], 0
	v_mfma_f32_16x16x32_bf16 v[102:105], v[216:219], v[172:175], 0
	v_mfma_f32_16x16x32_bf16 v[98:101], v[224:227], v[172:175], 0
	v_mfma_f32_16x16x32_bf16 v[86:89], v[216:219], v[180:183], 0
	v_mfma_f32_16x16x32_bf16 v[82:85], v[224:227], v[180:183], 0
	v_mfma_f32_16x16x32_bf16 v[70:73], v[216:219], v[208:211], 0
	v_mfma_f32_16x16x32_bf16 v[66:69], v[224:227], v[208:211], 0
	v_mfma_f32_16x16x32_bf16 v[118:121], v[220:223], v[168:171], v[118:121]
	v_mfma_f32_16x16x32_bf16 v[114:117], v[228:231], v[168:171], v[114:117]
	v_mfma_f32_16x16x32_bf16 v[102:105], v[220:223], v[176:179], v[102:105]
	v_mfma_f32_16x16x32_bf16 v[98:101], v[228:231], v[176:179], v[98:101]
	v_mfma_f32_16x16x32_bf16 v[86:89], v[220:223], v[204:207], v[86:89]
	v_mfma_f32_16x16x32_bf16 v[82:85], v[228:231], v[204:207], v[82:85]
	v_mfma_f32_16x16x32_bf16 v[70:73], v[220:223], v[212:215], v[70:73]
	v_mfma_f32_16x16x32_bf16 v[66:69], v[228:231], v[212:215], v[66:69]
	s_mov_b32 m0, s22
	v_lshl_add_u64 v[232:233], s[4:5], 0, v[130:131]
	s_barrier
	ds_read_b128 v[164:167], v150 offset:16384
	ds_read_b128 v[168:171], v150 offset:17408
	ds_read_b128 v[172:175], v150 offset:18432
	ds_read_b128 v[176:179], v150 offset:19456
	ds_read_b128 v[180:183], v150 offset:20480
	ds_read_b128 v[204:207], v150 offset:21504
	ds_read_b128 v[208:211], v150 offset:22528
	ds_read_b128 v[212:215], v150 offset:23552
	global_load_lds_dwordx4 v[232:233], off
	v_lshl_add_u64 v[234:235], s[4:5], 0, v[134:135]
	s_mov_b32 m0, s23
	s_nop 0
	global_load_lds_dwordx4 v[234:235], off
	s_barrier
	s_waitcnt lgkmcnt(0)
	s_waitcnt lgkmcnt(0)
	v_mfma_f32_16x16x32_bf16 v[62:65], v[142:145], v[164:167], 0
	v_mfma_f32_16x16x32_bf16 v[58:61], v[156:159], v[164:167], 0
	v_mfma_f32_16x16x32_bf16 v[46:49], v[142:145], v[172:175], 0
	v_mfma_f32_16x16x32_bf16 v[42:45], v[156:159], v[172:175], 0
	v_mfma_f32_16x16x32_bf16 v[30:33], v[142:145], v[180:183], 0
	v_mfma_f32_16x16x32_bf16 v[26:29], v[156:159], v[180:183], 0
	v_mfma_f32_16x16x32_bf16 v[14:17], v[142:145], v[208:211], 0
	v_mfma_f32_16x16x32_bf16 v[10:13], v[156:159], v[208:211], 0
	v_mfma_f32_16x16x32_bf16 v[62:65], v[152:155], v[168:171], v[62:65]
	v_mfma_f32_16x16x32_bf16 v[58:61], v[160:163], v[168:171], v[58:61]
	v_mfma_f32_16x16x32_bf16 v[46:49], v[152:155], v[176:179], v[46:49]
	v_mfma_f32_16x16x32_bf16 v[42:45], v[160:163], v[176:179], v[42:45]
	v_mfma_f32_16x16x32_bf16 v[30:33], v[152:155], v[204:207], v[30:33]
	v_mfma_f32_16x16x32_bf16 v[26:29], v[160:163], v[204:207], v[26:29]
	v_mfma_f32_16x16x32_bf16 v[14:17], v[152:155], v[212:215], v[14:17]
	v_mfma_f32_16x16x32_bf16 v[10:13], v[160:163], v[212:215], v[10:13]
	s_barrier
	s_add_u32 s18, s18, s2
	s_addc_u32 s19, s19, 0
	s_add_i32 s66, s67, s21
	v_lshl_add_u64 v[236:237], s[18:19], 0, v[132:133]
	s_mov_b32 m0, s66
	v_lshl_add_u64 v[238:239], s[18:19], 0, v[136:137]
	global_load_lds_dwordx4 v[236:237], off
	s_add_i32 m0, s66, 0x2000
	s_nop 0
	global_load_lds_dwordx4 v[238:239], off
	s_waitcnt vmcnt(6)
	s_barrier
	v_mfma_f32_16x16x32_bf16 v[54:57], v[216:219], v[164:167], 0
	v_mfma_f32_16x16x32_bf16 v[50:53], v[224:227], v[164:167], 0
	v_mfma_f32_16x16x32_bf16 v[38:41], v[216:219], v[172:175], 0
	v_mfma_f32_16x16x32_bf16 v[34:37], v[224:227], v[172:175], 0
	v_mfma_f32_16x16x32_bf16 v[22:25], v[216:219], v[180:183], 0
	v_mfma_f32_16x16x32_bf16 v[18:21], v[224:227], v[180:183], 0
	v_mfma_f32_16x16x32_bf16 v[6:9], v[216:219], v[208:211], 0
	v_mfma_f32_16x16x32_bf16 v[2:5], v[224:227], v[208:211], 0
	v_mfma_f32_16x16x32_bf16 v[54:57], v[220:223], v[168:171], v[54:57]
	v_mfma_f32_16x16x32_bf16 v[50:53], v[228:231], v[168:171], v[50:53]
	v_mfma_f32_16x16x32_bf16 v[38:41], v[220:223], v[176:179], v[38:41]
	v_mfma_f32_16x16x32_bf16 v[34:37], v[228:231], v[176:179], v[34:37]
	v_mfma_f32_16x16x32_bf16 v[22:25], v[220:223], v[204:207], v[22:25]
	v_mfma_f32_16x16x32_bf16 v[18:21], v[228:231], v[204:207], v[18:21]
	v_mfma_f32_16x16x32_bf16 v[6:9], v[220:223], v[212:215], v[6:9]
	v_mfma_f32_16x16x32_bf16 v[2:5], v[228:231], v[212:215], v[2:5]
	s_add_i32 s18, 0, 0x18000
	v_add_u32_e32 v151, s18, v149
	s_barrier
	ds_read_b128 v[142:145], v151
	ds_read_b128 v[152:155], v151 offset:1024
	ds_read_b128 v[156:159], v151 offset:2048
	ds_read_b128 v[160:163], v151 offset:3072
	s_add_u32 s4, s4, s2
	s_addc_u32 s5, s5, 0
	s_mov_b32 m0, s24
	v_lshl_add_u64 v[216:217], s[4:5], 0, v[130:131]
	ds_read_b128 v[164:167], v150 offset:32768
	ds_read_b128 v[168:171], v150 offset:33792
	ds_read_b128 v[172:175], v150 offset:34816
	ds_read_b128 v[176:179], v150 offset:35840
	ds_read_b128 v[180:183], v150 offset:36864
	ds_read_b128 v[204:207], v150 offset:37888
	ds_read_b128 v[208:211], v150 offset:38912
	ds_read_b128 v[212:215], v150 offset:39936
	global_load_lds_dwordx4 v[216:217], off
	v_lshl_add_u64 v[216:217], s[4:5], 0, v[134:135]
	s_mov_b32 m0, s25
	s_nop 0
	global_load_lds_dwordx4 v[216:217], off
	s_waitcnt lgkmcnt(8)
	s_barrier
	s_waitcnt lgkmcnt(0)
	s_waitcnt lgkmcnt(0)
	v_mfma_f32_16x16x32_bf16 v[126:129], v[142:145], v[164:167], v[126:129]
	v_mfma_f32_16x16x32_bf16 v[122:125], v[156:159], v[164:167], v[122:125]
	v_mfma_f32_16x16x32_bf16 v[110:113], v[142:145], v[172:175], v[110:113]
	v_mfma_f32_16x16x32_bf16 v[106:109], v[156:159], v[172:175], v[106:109]
	v_mfma_f32_16x16x32_bf16 v[94:97], v[142:145], v[180:183], v[94:97]
	v_mfma_f32_16x16x32_bf16 v[90:93], v[156:159], v[180:183], v[90:93]
	v_mfma_f32_16x16x32_bf16 v[78:81], v[142:145], v[208:211], v[78:81]
	v_mfma_f32_16x16x32_bf16 v[74:77], v[156:159], v[208:211], v[74:77]
	v_mfma_f32_16x16x32_bf16 v[126:129], v[152:155], v[168:171], v[126:129]
	v_mfma_f32_16x16x32_bf16 v[122:125], v[160:163], v[168:171], v[122:125]
	v_mfma_f32_16x16x32_bf16 v[110:113], v[152:155], v[176:179], v[110:113]
	v_mfma_f32_16x16x32_bf16 v[106:109], v[160:163], v[176:179], v[106:109]
	v_mfma_f32_16x16x32_bf16 v[94:97], v[152:155], v[204:207], v[94:97]
	v_mfma_f32_16x16x32_bf16 v[90:93], v[160:163], v[204:207], v[90:93]
	v_mfma_f32_16x16x32_bf16 v[78:81], v[152:155], v[212:215], v[78:81]
	v_mfma_f32_16x16x32_bf16 v[74:77], v[160:163], v[212:215], v[74:77]
	s_barrier
	s_add_i32 s4, 0, 0x1c000
	s_add_i32 s5, s18, s21
	v_add_u32_e32 v151, s4, v149
	v_lshl_add_u64 v[146:147], v[146:147], 0, s[6:7]
	s_mov_b32 m0, s5
	ds_read_b128 v[216:219], v151
	ds_read_b128 v[220:223], v151 offset:1024
	ds_read_b128 v[224:227], v151 offset:2048
	ds_read_b128 v[228:231], v151 offset:3072
	global_load_lds_dwordx4 v[146:147], off
	v_lshl_add_u64 v[146:147], v[184:185], 0, s[6:7]
	s_add_i32 m0, s5, 0x2000
	s_nop 0
	global_load_lds_dwordx4 v[146:147], off
	s_barrier
	s_waitcnt lgkmcnt(0)
	s_waitcnt lgkmcnt(0)
	v_mfma_f32_16x16x32_bf16 v[118:121], v[216:219], v[164:167], v[118:121]
	v_mfma_f32_16x16x32_bf16 v[114:117], v[224:227], v[164:167], v[114:117]
	v_mfma_f32_16x16x32_bf16 v[102:105], v[216:219], v[172:175], v[102:105]
	v_mfma_f32_16x16x32_bf16 v[98:101], v[224:227], v[172:175], v[98:101]
	v_mfma_f32_16x16x32_bf16 v[86:89], v[216:219], v[180:183], v[86:89]
	v_mfma_f32_16x16x32_bf16 v[82:85], v[224:227], v[180:183], v[82:85]
	v_mfma_f32_16x16x32_bf16 v[70:73], v[216:219], v[208:211], v[70:73]
	v_mfma_f32_16x16x32_bf16 v[66:69], v[224:227], v[208:211], v[66:69]
	v_mfma_f32_16x16x32_bf16 v[118:121], v[220:223], v[168:171], v[118:121]
	v_mfma_f32_16x16x32_bf16 v[114:117], v[228:231], v[168:171], v[114:117]
	v_mfma_f32_16x16x32_bf16 v[102:105], v[220:223], v[176:179], v[102:105]
	v_mfma_f32_16x16x32_bf16 v[98:101], v[228:231], v[176:179], v[98:101]
	v_mfma_f32_16x16x32_bf16 v[86:89], v[220:223], v[204:207], v[86:89]
	v_mfma_f32_16x16x32_bf16 v[82:85], v[228:231], v[204:207], v[82:85]
	v_mfma_f32_16x16x32_bf16 v[70:73], v[220:223], v[212:215], v[70:73]
	v_mfma_f32_16x16x32_bf16 v[66:69], v[228:231], v[212:215], v[66:69]
	s_mov_b32 m0, s30
	v_lshl_add_u64 v[146:147], v[232:233], 0, s[6:7]
	s_barrier
	ds_read_b128 v[164:167], v150 offset:49152
	ds_read_b128 v[168:171], v150 offset:50176
	ds_read_b128 v[172:175], v150 offset:51200
	ds_read_b128 v[176:179], v150 offset:52224
	ds_read_b128 v[180:183], v150 offset:53248
	ds_read_b128 v[204:207], v150 offset:54272
	ds_read_b128 v[208:211], v150 offset:55296
	ds_read_b128 v[212:215], v150 offset:56320
	global_load_lds_dwordx4 v[146:147], off
	v_lshl_add_u64 v[146:147], v[234:235], 0, s[6:7]
	s_mov_b32 m0, s31
	s_nop 0
	global_load_lds_dwordx4 v[146:147], off
	s_barrier
	s_waitcnt lgkmcnt(0)
	s_waitcnt lgkmcnt(0)
	v_mfma_f32_16x16x32_bf16 v[62:65], v[142:145], v[164:167], v[62:65]
	v_mfma_f32_16x16x32_bf16 v[58:61], v[156:159], v[164:167], v[58:61]
	v_mfma_f32_16x16x32_bf16 v[46:49], v[142:145], v[172:175], v[46:49]
	v_mfma_f32_16x16x32_bf16 v[42:45], v[156:159], v[172:175], v[42:45]
	v_mfma_f32_16x16x32_bf16 v[30:33], v[142:145], v[180:183], v[30:33]
	v_mfma_f32_16x16x32_bf16 v[26:29], v[156:159], v[180:183], v[26:29]
	v_mfma_f32_16x16x32_bf16 v[14:17], v[142:145], v[208:211], v[14:17]
	v_mfma_f32_16x16x32_bf16 v[10:13], v[156:159], v[208:211], v[10:13]
	v_mfma_f32_16x16x32_bf16 v[62:65], v[152:155], v[168:171], v[62:65]
	v_mfma_f32_16x16x32_bf16 v[58:61], v[160:163], v[168:171], v[58:61]
	v_mfma_f32_16x16x32_bf16 v[46:49], v[152:155], v[176:179], v[46:49]
	v_mfma_f32_16x16x32_bf16 v[42:45], v[160:163], v[176:179], v[42:45]
	v_mfma_f32_16x16x32_bf16 v[30:33], v[152:155], v[204:207], v[30:33]
	v_mfma_f32_16x16x32_bf16 v[26:29], v[160:163], v[204:207], v[26:29]
	v_mfma_f32_16x16x32_bf16 v[14:17], v[152:155], v[212:215], v[14:17]
	v_mfma_f32_16x16x32_bf16 v[10:13], v[160:163], v[212:215], v[10:13]
	s_barrier
	s_add_i32 s4, s4, s21
	v_lshl_add_u64 v[142:143], v[236:237], 0, s[6:7]
	s_mov_b32 m0, s4
	s_nop 0
	global_load_lds_dwordx4 v[142:143], off
	v_lshl_add_u64 v[142:143], v[238:239], 0, s[6:7]
	s_add_i32 m0, s4, 0x2000
	s_nop 0
	global_load_lds_dwordx4 v[142:143], off
	s_waitcnt vmcnt(6)
	s_barrier
	v_mfma_f32_16x16x32_bf16 v[54:57], v[216:219], v[164:167], v[54:57]
	v_mfma_f32_16x16x32_bf16 v[50:53], v[224:227], v[164:167], v[50:53]
	v_mfma_f32_16x16x32_bf16 v[38:41], v[216:219], v[172:175], v[38:41]
	v_mfma_f32_16x16x32_bf16 v[34:37], v[224:227], v[172:175], v[34:37]
	v_mfma_f32_16x16x32_bf16 v[22:25], v[216:219], v[180:183], v[22:25]
	v_mfma_f32_16x16x32_bf16 v[18:21], v[224:227], v[180:183], v[18:21]
	v_mfma_f32_16x16x32_bf16 v[6:9], v[216:219], v[208:211], v[6:9]
	v_mfma_f32_16x16x32_bf16 v[2:5], v[224:227], v[208:211], v[2:5]
	v_mfma_f32_16x16x32_bf16 v[54:57], v[220:223], v[168:171], v[54:57]
	v_mfma_f32_16x16x32_bf16 v[50:53], v[228:231], v[168:171], v[50:53]
	v_mfma_f32_16x16x32_bf16 v[38:41], v[220:223], v[176:179], v[38:41]
	v_mfma_f32_16x16x32_bf16 v[34:37], v[228:231], v[176:179], v[34:37]
	v_mfma_f32_16x16x32_bf16 v[22:25], v[220:223], v[204:207], v[22:25]
	v_mfma_f32_16x16x32_bf16 v[18:21], v[228:231], v[204:207], v[18:21]
	v_mfma_f32_16x16x32_bf16 v[6:9], v[220:223], v[212:215], v[6:9]
	v_mfma_f32_16x16x32_bf16 v[2:5], v[228:231], v[212:215], v[2:5]
	s_add_u32 s0, s0, 0x100
	s_addc_u32 s1, s1, 0
	s_add_u32 s48, s48, 0x100
	s_addc_u32 s49, s49, 0
	s_cmp_ge_u32 s65, s27
	s_mov_b32 s4, s65
	s_barrier
	s_cbranch_scc1 .Lkexit_698
.LBB0_698:
	s_add_i32 s65, s4, 2
	s_add_u32 s18, s0, 0x80
	s_addc_u32 s5, s1, 0
	s_add_i32 s66, 0, 0x10000
	v_add_u32_e32 v146, s66, v149
	ds_read_b128 v[142:145], v146
	ds_read_b128 v[152:155], v146 offset:1024
	ds_read_b128 v[156:159], v146 offset:2048
	ds_read_b128 v[160:163], v146 offset:3072
	s_cmp_eq_u32 s34, s4
	s_cselect_b32 s4, s10, s18
	s_cselect_b32 s5, s11, s5
	s_cselect_b32 s19, s13, s49
	s_cselect_b32 s18, s12, s48
	v_lshl_add_u64 v[146:147], s[0:1], 0, v[138:139]
	s_add_i32 m0, s22, 0xc000
	ds_read_b128 v[164:167], v150
	ds_read_b128 v[168:171], v150 offset:1024
	ds_read_b128 v[172:175], v150 offset:2048
	ds_read_b128 v[176:179], v150 offset:3072
	ds_read_b128 v[180:183], v150 offset:4096
	ds_read_b128 v[204:207], v150 offset:5120
	ds_read_b128 v[208:211], v150 offset:6144
	ds_read_b128 v[212:215], v150 offset:7168
	global_load_lds_dwordx4 v[146:147], off
	v_lshl_add_u64 v[146:147], s[0:1], 0, v[140:141]
	s_add_i32 m0, s22, 0xe000
	s_nop 0
	global_load_lds_dwordx4 v[146:147], off
	s_waitcnt lgkmcnt(8)
	s_barrier
	s_waitcnt lgkmcnt(0)
	s_waitcnt lgkmcnt(0)
	v_mfma_f32_16x16x32_bf16 v[126:129], v[142:145], v[164:167], v[126:129]
	v_mfma_f32_16x16x32_bf16 v[122:125], v[156:159], v[164:167], v[122:125]
	v_mfma_f32_16x16x32_bf16 v[110:113], v[142:145], v[172:175], v[110:113]
	v_mfma_f32_16x16x32_bf16 v[106:109], v[156:159], v[172:175], v[106:109]
	v_mfma_f32_16x16x32_bf16 v[94:97], v[142:145], v[180:183], v[94:97]
	v_mfma_f32_16x16x32_bf16 v[90:93], v[156:159], v[180:183], v[90:93]
	v_mfma_f32_16x16x32_bf16 v[78:81], v[142:145], v[208:211], v[78:81]
	v_mfma_f32_16x16x32_bf16 v[74:77], v[156:159], v[208:211], v[74:77]
	v_mfma_f32_16x16x32_bf16 v[126:129], v[152:155], v[168:171], v[126:129]
	v_mfma_f32_16x16x32_bf16 v[122:125], v[160:163], v[168:171], v[122:125]
	v_mfma_f32_16x16x32_bf16 v[110:113], v[152:155], v[176:179], v[110:113]
	v_mfma_f32_16x16x32_bf16 v[106:109], v[160:163], v[176:179], v[106:109]
	v_mfma_f32_16x16x32_bf16 v[94:97], v[152:155], v[204:207], v[94:97]
	v_mfma_f32_16x16x32_bf16 v[90:93], v[160:163], v[204:207], v[90:93]
	v_mfma_f32_16x16x32_bf16 v[78:81], v[152:155], v[212:215], v[78:81]
	v_mfma_f32_16x16x32_bf16 v[74:77], v[160:163], v[212:215], v[74:77]
	s_barrier
	s_add_i32 s67, 0, 0x14000
	v_add_u32_e32 v146, s67, v149
	s_add_i32 s66, s66, s21
	ds_read_b128 v[216:219], v146
	ds_read_b128 v[220:223], v146 offset:1024
	ds_read_b128 v[224:227], v146 offset:2048
	ds_read_b128 v[228:231], v146 offset:3072
	v_lshl_add_u64 v[146:147], s[18:19], 0, v[132:133]
	s_mov_b32 m0, s66
	v_lshl_add_u64 v[184:185], s[18:19], 0, v[136:137]
	global_load_lds_dwordx4 v[146:147], off
	s_add_i32 m0, s66, 0x2000
	s_nop 0
	global_load_lds_dwordx4 v[184:185], off
	s_barrier
	s_waitcnt lgkmcnt(0)
	s_waitcnt lgkmcnt(0)
	v_mfma_f32_16x16x32_bf16 v[118:121], v[216:219], v[164:167], v[118:121]
	v_mfma_f32_16x16x32_bf16 v[114:117], v[224:227], v[164:167], v[114:117]
	v_mfma_f32_16x16x32_bf16 v[102:105], v[216:219], v[172:175], v[102:105]
	v_mfma_f32_16x16x32_bf16 v[98:101], v[224:227], v[172:175], v[98:101]
	v_mfma_f32_16x16x32_bf16 v[86:89], v[216:219], v[180:183], v[86:89]
	v_mfma_f32_16x16x32_bf16 v[82:85], v[224:227], v[180:183], v[82:85]
	v_mfma_f32_16x16x32_bf16 v[70:73], v[216:219], v[208:211], v[70:73]
	v_mfma_f32_16x16x32_bf16 v[66:69], v[224:227], v[208:211], v[66:69]
	v_mfma_f32_16x16x32_bf16 v[118:121], v[220:223], v[168:171], v[118:121]
	v_mfma_f32_16x16x32_bf16 v[114:117], v[228:231], v[168:171], v[114:117]
	v_mfma_f32_16x16x32_bf16 v[102:105], v[220:223], v[176:179], v[102:105]
	v_mfma_f32_16x16x32_bf16 v[98:101], v[228:231], v[176:179], v[98:101]
	v_mfma_f32_16x16x32_bf16 v[86:89], v[220:223], v[204:207], v[86:89]
	v_mfma_f32_16x16x32_bf16 v[82:85], v[228:231], v[204:207], v[82:85]
	v_mfma_f32_16x16x32_bf16 v[70:73], v[220:223], v[212:215], v[70:73]
	v_mfma_f32_16x16x32_bf16 v[66:69], v[228:231], v[212:215], v[66:69]
	s_mov_b32 m0, s22
	v_lshl_add_u64 v[232:233], s[4:5], 0, v[130:131]
	s_barrier
	ds_read_b128 v[164:167], v150 offset:16384
	ds_read_b128 v[168:171], v150 offset:17408
	ds_read_b128 v[172:175], v150 offset:18432
	ds_read_b128 v[176:179], v150 offset:19456
	ds_read_b128 v[180:183], v150 offset:20480
	ds_read_b128 v[204:207], v150 offset:21504
	ds_read_b128 v[208:211], v150 offset:22528
	ds_read_b128 v[212:215], v150 offset:23552
	global_load_lds_dwordx4 v[232:233], off
	v_lshl_add_u64 v[234:235], s[4:5], 0, v[134:135]
	s_mov_b32 m0, s23
	s_nop 0
	global_load_lds_dwordx4 v[234:235], off
	s_barrier
	s_waitcnt lgkmcnt(0)
	s_waitcnt lgkmcnt(0)
	v_mfma_f32_16x16x32_bf16 v[62:65], v[142:145], v[164:167], v[62:65]
	v_mfma_f32_16x16x32_bf16 v[58:61], v[156:159], v[164:167], v[58:61]
	v_mfma_f32_16x16x32_bf16 v[46:49], v[142:145], v[172:175], v[46:49]
	v_mfma_f32_16x16x32_bf16 v[42:45], v[156:159], v[172:175], v[42:45]
	v_mfma_f32_16x16x32_bf16 v[30:33], v[142:145], v[180:183], v[30:33]
	v_mfma_f32_16x16x32_bf16 v[26:29], v[156:159], v[180:183], v[26:29]
	v_mfma_f32_16x16x32_bf16 v[14:17], v[142:145], v[208:211], v[14:17]
	v_mfma_f32_16x16x32_bf16 v[10:13], v[156:159], v[208:211], v[10:13]
	v_mfma_f32_16x16x32_bf16 v[62:65], v[152:155], v[168:171], v[62:65]
	v_mfma_f32_16x16x32_bf16 v[58:61], v[160:163], v[168:171], v[58:61]
	v_mfma_f32_16x16x32_bf16 v[46:49], v[152:155], v[176:179], v[46:49]
	v_mfma_f32_16x16x32_bf16 v[42:45], v[160:163], v[176:179], v[42:45]
	v_mfma_f32_16x16x32_bf16 v[30:33], v[152:155], v[204:207], v[30:33]
	v_mfma_f32_16x16x32_bf16 v[26:29], v[160:163], v[204:207], v[26:29]
	v_mfma_f32_16x16x32_bf16 v[14:17], v[152:155], v[212:215], v[14:17]
	v_mfma_f32_16x16x32_bf16 v[10:13], v[160:163], v[212:215], v[10:13]
	s_barrier
	s_add_u32 s18, s18, s2
	s_addc_u32 s19, s19, 0
	s_add_i32 s66, s67, s21
	v_lshl_add_u64 v[236:237], s[18:19], 0, v[132:133]
	s_mov_b32 m0, s66
	v_lshl_add_u64 v[238:239], s[18:19], 0, v[136:137]
	global_load_lds_dwordx4 v[236:237], off
	s_add_i32 m0, s66, 0x2000
	s_nop 0
	global_load_lds_dwordx4 v[238:239], off
	s_waitcnt vmcnt(6)
	s_barrier
	v_mfma_f32_16x16x32_bf16 v[54:57], v[216:219], v[164:167], v[54:57]
	v_mfma_f32_16x16x32_bf16 v[50:53], v[224:227], v[164:167], v[50:53]
	v_mfma_f32_16x16x32_bf16 v[38:41], v[216:219], v[172:175], v[38:41]
	v_mfma_f32_16x16x32_bf16 v[34:37], v[224:227], v[172:175], v[34:37]
	v_mfma_f32_16x16x32_bf16 v[22:25], v[216:219], v[180:183], v[22:25]
	v_mfma_f32_16x16x32_bf16 v[18:21], v[224:227], v[180:183], v[18:21]
	v_mfma_f32_16x16x32_bf16 v[6:9], v[216:219], v[208:211], v[6:9]
	v_mfma_f32_16x16x32_bf16 v[2:5], v[224:227], v[208:211], v[2:5]
	v_mfma_f32_16x16x32_bf16 v[54:57], v[220:223], v[168:171], v[54:57]
	v_mfma_f32_16x16x32_bf16 v[50:53], v[228:231], v[168:171], v[50:53]
	v_mfma_f32_16x16x32_bf16 v[38:41], v[220:223], v[176:179], v[38:41]
	v_mfma_f32_16x16x32_bf16 v[34:37], v[228:231], v[176:179], v[34:37]
	v_mfma_f32_16x16x32_bf16 v[22:25], v[220:223], v[204:207], v[22:25]
	v_mfma_f32_16x16x32_bf16 v[18:21], v[228:231], v[204:207], v[18:21]
	v_mfma_f32_16x16x32_bf16 v[6:9], v[220:223], v[212:215], v[6:9]
	v_mfma_f32_16x16x32_bf16 v[2:5], v[228:231], v[212:215], v[2:5]
	s_add_i32 s18, 0, 0x18000
	v_add_u32_e32 v151, s18, v149
	s_barrier
	ds_read_b128 v[142:145], v151
	ds_read_b128 v[152:155], v151 offset:1024
	ds_read_b128 v[156:159], v151 offset:2048
	ds_read_b128 v[160:163], v151 offset:3072
	s_add_u32 s4, s4, s2
	s_addc_u32 s5, s5, 0
	s_mov_b32 m0, s24
	v_lshl_add_u64 v[216:217], s[4:5], 0, v[130:131]
	ds_read_b128 v[164:167], v150 offset:32768
	ds_read_b128 v[168:171], v150 offset:33792
	ds_read_b128 v[172:175], v150 offset:34816
	ds_read_b128 v[176:179], v150 offset:35840
	ds_read_b128 v[180:183], v150 offset:36864
	ds_read_b128 v[204:207], v150 offset:37888
	ds_read_b128 v[208:211], v150 offset:38912
	ds_read_b128 v[212:215], v150 offset:39936
	global_load_lds_dwordx4 v[216:217], off
	v_lshl_add_u64 v[216:217], s[4:5], 0, v[134:135]
	s_mov_b32 m0, s25
	s_nop 0
	global_load_lds_dwordx4 v[216:217], off
	s_waitcnt lgkmcnt(8)
	s_barrier
	s_waitcnt lgkmcnt(0)
	s_waitcnt lgkmcnt(0)
	v_mfma_f32_16x16x32_bf16 v[126:129], v[142:145], v[164:167], v[126:129]
	v_mfma_f32_16x16x32_bf16 v[122:125], v[156:159], v[164:167], v[122:125]
	v_mfma_f32_16x16x32_bf16 v[110:113], v[142:145], v[172:175], v[110:113]
	v_mfma_f32_16x16x32_bf16 v[106:109], v[156:159], v[172:175], v[106:109]
	v_mfma_f32_16x16x32_bf16 v[94:97], v[142:145], v[180:183], v[94:97]
	v_mfma_f32_16x16x32_bf16 v[90:93], v[156:159], v[180:183], v[90:93]
	v_mfma_f32_16x16x32_bf16 v[78:81], v[142:145], v[208:211], v[78:81]
	v_mfma_f32_16x16x32_bf16 v[74:77], v[156:159], v[208:211], v[74:77]
	v_mfma_f32_16x16x32_bf16 v[126:129], v[152:155], v[168:171], v[126:129]
	v_mfma_f32_16x16x32_bf16 v[122:125], v[160:163], v[168:171], v[122:125]
	v_mfma_f32_16x16x32_bf16 v[110:113], v[152:155], v[176:179], v[110:113]
	v_mfma_f32_16x16x32_bf16 v[106:109], v[160:163], v[176:179], v[106:109]
	v_mfma_f32_16x16x32_bf16 v[94:97], v[152:155], v[204:207], v[94:97]
	v_mfma_f32_16x16x32_bf16 v[90:93], v[160:163], v[204:207], v[90:93]
	v_mfma_f32_16x16x32_bf16 v[78:81], v[152:155], v[212:215], v[78:81]
	v_mfma_f32_16x16x32_bf16 v[74:77], v[160:163], v[212:215], v[74:77]
	s_barrier
	s_add_i32 s4, 0, 0x1c000
	s_add_i32 s5, s18, s21
	v_add_u32_e32 v151, s4, v149
	v_lshl_add_u64 v[146:147], v[146:147], 0, s[6:7]
	s_mov_b32 m0, s5
	ds_read_b128 v[216:219], v151
	ds_read_b128 v[220:223], v151 offset:1024
	ds_read_b128 v[224:227], v151 offset:2048
	ds_read_b128 v[228:231], v151 offset:3072
	global_load_lds_dwordx4 v[146:147], off
	v_lshl_add_u64 v[146:147], v[184:185], 0, s[6:7]
	s_add_i32 m0, s5, 0x2000
	s_nop 0
	global_load_lds_dwordx4 v[146:147], off
	s_barrier
	s_waitcnt lgkmcnt(0)
	s_waitcnt lgkmcnt(0)
	v_mfma_f32_16x16x32_bf16 v[118:121], v[216:219], v[164:167], v[118:121]
	v_mfma_f32_16x16x32_bf16 v[114:117], v[224:227], v[164:167], v[114:117]
	v_mfma_f32_16x16x32_bf16 v[102:105], v[216:219], v[172:175], v[102:105]
	v_mfma_f32_16x16x32_bf16 v[98:101], v[224:227], v[172:175], v[98:101]
	v_mfma_f32_16x16x32_bf16 v[86:89], v[216:219], v[180:183], v[86:89]
	v_mfma_f32_16x16x32_bf16 v[82:85], v[224:227], v[180:183], v[82:85]
	v_mfma_f32_16x16x32_bf16 v[70:73], v[216:219], v[208:211], v[70:73]
	v_mfma_f32_16x16x32_bf16 v[66:69], v[224:227], v[208:211], v[66:69]
	v_mfma_f32_16x16x32_bf16 v[118:121], v[220:223], v[168:171], v[118:121]
	v_mfma_f32_16x16x32_bf16 v[114:117], v[228:231], v[168:171], v[114:117]
	v_mfma_f32_16x16x32_bf16 v[102:105], v[220:223], v[176:179], v[102:105]
	v_mfma_f32_16x16x32_bf16 v[98:101], v[228:231], v[176:179], v[98:101]
	v_mfma_f32_16x16x32_bf16 v[86:89], v[220:223], v[204:207], v[86:89]
	v_mfma_f32_16x16x32_bf16 v[82:85], v[228:231], v[204:207], v[82:85]
	v_mfma_f32_16x16x32_bf16 v[70:73], v[220:223], v[212:215], v[70:73]
	v_mfma_f32_16x16x32_bf16 v[66:69], v[228:231], v[212:215], v[66:69]
	s_mov_b32 m0, s30
	v_lshl_add_u64 v[146:147], v[232:233], 0, s[6:7]
	s_barrier
	ds_read_b128 v[164:167], v150 offset:49152
	ds_read_b128 v[168:171], v150 offset:50176
	ds_read_b128 v[172:175], v150 offset:51200
	ds_read_b128 v[176:179], v150 offset:52224
	ds_read_b128 v[180:183], v150 offset:53248
	ds_read_b128 v[204:207], v150 offset:54272
	ds_read_b128 v[208:211], v150 offset:55296
	ds_read_b128 v[212:215], v150 offset:56320
	global_load_lds_dwordx4 v[146:147], off
	v_lshl_add_u64 v[146:147], v[234:235], 0, s[6:7]
	s_mov_b32 m0, s31
	s_nop 0
	global_load_lds_dwordx4 v[146:147], off
	s_barrier
	s_waitcnt lgkmcnt(0)
	s_waitcnt lgkmcnt(0)
	v_mfma_f32_16x16x32_bf16 v[62:65], v[142:145], v[164:167], v[62:65]
	v_mfma_f32_16x16x32_bf16 v[58:61], v[156:159], v[164:167], v[58:61]
	v_mfma_f32_16x16x32_bf16 v[46:49], v[142:145], v[172:175], v[46:49]
	v_mfma_f32_16x16x32_bf16 v[42:45], v[156:159], v[172:175], v[42:45]
	v_mfma_f32_16x16x32_bf16 v[30:33], v[142:145], v[180:183], v[30:33]
	v_mfma_f32_16x16x32_bf16 v[26:29], v[156:159], v[180:183], v[26:29]
	v_mfma_f32_16x16x32_bf16 v[14:17], v[142:145], v[208:211], v[14:17]
	v_mfma_f32_16x16x32_bf16 v[10:13], v[156:159], v[208:211], v[10:13]
	v_mfma_f32_16x16x32_bf16 v[62:65], v[152:155], v[168:171], v[62:65]
	v_mfma_f32_16x16x32_bf16 v[58:61], v[160:163], v[168:171], v[58:61]
	v_mfma_f32_16x16x32_bf16 v[46:49], v[152:155], v[176:179], v[46:49]
	v_mfma_f32_16x16x32_bf16 v[42:45], v[160:163], v[176:179], v[42:45]
	v_mfma_f32_16x16x32_bf16 v[30:33], v[152:155], v[204:207], v[30:33]
	v_mfma_f32_16x16x32_bf16 v[26:29], v[160:163], v[204:207], v[26:29]
	v_mfma_f32_16x16x32_bf16 v[14:17], v[152:155], v[212:215], v[14:17]
	v_mfma_f32_16x16x32_bf16 v[10:13], v[160:163], v[212:215], v[10:13]
	s_barrier
	s_add_i32 s4, s4, s21
	v_lshl_add_u64 v[142:143], v[236:237], 0, s[6:7]
	s_mov_b32 m0, s4
	s_nop 0
	global_load_lds_dwordx4 v[142:143], off
	v_lshl_add_u64 v[142:143], v[238:239], 0, s[6:7]
	s_add_i32 m0, s4, 0x2000
	s_nop 0
	global_load_lds_dwordx4 v[142:143], off
	s_waitcnt vmcnt(6)
	s_barrier
	v_mfma_f32_16x16x32_bf16 v[54:57], v[216:219], v[164:167], v[54:57]
	v_mfma_f32_16x16x32_bf16 v[50:53], v[224:227], v[164:167], v[50:53]
	v_mfma_f32_16x16x32_bf16 v[38:41], v[216:219], v[172:175], v[38:41]
	v_mfma_f32_16x16x32_bf16 v[34:37], v[224:227], v[172:175], v[34:37]
	v_mfma_f32_16x16x32_bf16 v[22:25], v[216:219], v[180:183], v[22:25]
	v_mfma_f32_16x16x32_bf16 v[18:21], v[224:227], v[180:183], v[18:21]
	v_mfma_f32_16x16x32_bf16 v[6:9], v[216:219], v[208:211], v[6:9]
	v_mfma_f32_16x16x32_bf16 v[2:5], v[224:227], v[208:211], v[2:5]
	v_mfma_f32_16x16x32_bf16 v[54:57], v[220:223], v[168:171], v[54:57]
	v_mfma_f32_16x16x32_bf16 v[50:53], v[228:231], v[168:171], v[50:53]
	v_mfma_f32_16x16x32_bf16 v[38:41], v[220:223], v[176:179], v[38:41]
	v_mfma_f32_16x16x32_bf16 v[34:37], v[228:231], v[176:179], v[34:37]
	v_mfma_f32_16x16x32_bf16 v[22:25], v[220:223], v[204:207], v[22:25]
	v_mfma_f32_16x16x32_bf16 v[18:21], v[228:231], v[204:207], v[18:21]
	v_mfma_f32_16x16x32_bf16 v[6:9], v[220:223], v[212:215], v[6:9]
	v_mfma_f32_16x16x32_bf16 v[2:5], v[228:231], v[212:215], v[2:5]
	s_add_u32 s0, s0, 0x100
	s_addc_u32 s1, s1, 0
	s_add_u32 s48, s48, 0x100
	s_addc_u32 s49, s49, 0
	s_cmp_ge_u32 s65, s27
	s_mov_b32 s4, s65
	s_barrier
	s_cbranch_scc0 .LBB0_698

.LBB0_726:
	v_readlane_b32 s2, v240, 14
	s_lshl_b32 s8, s2, 6
	s_andn2_b64 vcc, exec, s[0:1]
	s_cbranch_vccnz .LBB0_782
	s_waitcnt lgkmcnt(0)
	v_bfe_i32 v3, v19, 27, 1
	v_lshlrev_b32_e32 v1, 4, v19
	v_lshrrev_b32_e32 v3, 22, v3
	v_add_u32_e32 v3, v1, v3
	v_and_b32_e32 v3, 0xfffffc00, v3
	v_ashrrev_i32_e32 v2, 31, v19
	v_sub_u32_e32 v3, v1, v3
	v_lshrrev_b32_e32 v2, 26, v2
	v_lshrrev_b32_e32 v4, 4, v3
	v_add_u32_e32 v2, v19, v2
	v_bitop3_b32 v4, v4, v3, 32 bitop3:0x6c
	v_ashrrev_i32_e32 v3, 31, v3
	v_ashrrev_i32_e32 v2, 6, v2
	v_lshrrev_b32_e32 v3, 26, v3
	v_lshlrev_b32_e32 v5, 3, v2
	v_add_u32_e32 v3, v4, v3
	v_and_b32_e32 v5, -16, v5
	v_ashrrev_i32_e32 v3, 6, v3
	v_lshlrev_b32_e32 v2, 5, v2
	v_add_u32_e32 v5, v3, v5
	v_and_b32_e32 v14, 32, v2
	v_mul_i32_i24_e32 v2, 64, v3
	v_sub_u32_e32 v2, v4, v2
	v_lshlrev_b32_e32 v4, 1, v5
	v_lshrrev_b32_e32 v6, 2, v5
	v_and_b32_e32 v3, 3, v3
	s_mov_b32 s0, 0x7fffffe0
	v_ashrrev_i16_sdwa v2, v190, sext(v2) dst_sel:DWORD dst_unused:UNUSED_PAD src0_sel:DWORD src1_sel:BYTE_0
	v_and_b32_e32 v4, 24, v4
	v_and_b32_e32 v6, 4, v6
	v_and_or_b32 v3, v5, s0, v3
	v_bfe_i32 v15, v2, 0, 16
	v_or3_b32 v3, v3, v6, v4
	v_add_u32_e32 v2, v14, v15
	v_mul_lo_u32 v16, v5, s64
	v_mul_lo_u32 v3, v3, s64
	v_add_u32_e32 v1, 0x2000, v1
	v_add_lshl_u32 v130, v2, v16, 1
	v_add_lshl_u32 v132, v3, v2, 1
	v_ashrrev_i32_e32 v2, 31, v1
	v_lshrrev_b32_e32 v2, 22, v2
	v_add_u32_e32 v2, v1, v2
	v_ashrrev_i32_e32 v2, 10, v2
	v_mul_i32_i24_e32 v3, 0x400, v2
	v_sub_u32_e32 v1, v1, v3
	v_lshrrev_b32_e32 v3, 4, v1
	v_bitop3_b32 v1, v3, v1, 32 bitop3:0x6c
	v_ashrrev_i32_e32 v4, 31, v1
	v_lshrrev_b32_e32 v4, 26, v4
	v_lshlrev_b32_e32 v3, 3, v2
	v_add_u32_e32 v4, v1, v4
	v_and_b32_e32 v3, -16, v3
	v_ashrrev_i32_e32 v5, 6, v4
	v_add_u32_e32 v3, v5, v3
	v_and_b32_e32 v5, 3, v5
	s_lshl_b32 s2, s64, 8
	s_mov_b32 s3, s93
	v_and_or_b32 v5, v3, s0, v5
	s_lshl_b64 s[16:17], s[2:3], 1
	s_ashr_i32 s0, s27, 31
	s_mul_i32 s0, s16, s0
	s_mul_hi_u32 s1, s16, s27
	s_add_i32 s0, s1, s0
	s_bfe_u32 s1, s64, 0x10017
	s_mul_i32 s4, s1, s27
	s_add_i32 s11, s0, s4
	s_ashr_i32 s4, s24, 31
	s_mul_i32 s4, s16, s4
	s_mul_hi_u32 s5, s16, s24
	s_ashr_i32 s10, s26, 6
	v_lshlrev_b32_e32 v2, 5, v2
	s_add_i32 s4, s5, s4
	s_mul_i32 s1, s1, s24
	v_and_b32_e32 v17, 32, v2
	v_and_b32_e32 v2, 0xc0, v4
	s_ashr_i32 s9, s26, 8
	s_lshl_b32 s28, s10, 10
	s_add_i32 s1, s4, s1
	s_mul_i32 s4, s16, s24
	v_sub_u32_e32 v1, v1, v2
	v_lshlrev_b32_e32 v2, 1, v3
	v_lshrrev_b32_e32 v4, 2, v3
	s_add_u32 s4, s36, s4
	v_ashrrev_i16_sdwa v1, v190, sext(v1) dst_sel:DWORD dst_unused:UNUSED_PAD src0_sel:DWORD src1_sel:BYTE_0
	v_and_b32_e32 v2, 24, v2
	v_and_b32_e32 v4, 4, v4
	s_addc_u32 s5, s37, s1
	s_add_i32 s29, s28, 0
	v_bfe_i32 v18, v1, 0, 16
	v_or3_b32 v2, v5, v4, v2
	s_add_i32 m0, s29, 0x10000
	v_add_u32_e32 v1, v17, v18
	v_mul_lo_u32 v2, v2, s64
	s_mul_i32 s0, s16, s27
	global_load_lds_dwordx4 v132, s[4:5]
	s_add_i32 m0, s29, 0x12000
	v_add_lshl_u32 v136, v2, v1, 1
	s_add_u32 s0, s56, s0
	v_mul_lo_u32 v20, v3, s64
	global_load_lds_dwordx4 v136, s[4:5]
	s_addc_u32 s1, s52, s11
	s_mov_b32 m0, s29
	s_add_i32 s30, s29, 0x2000
	v_add_lshl_u32 v134, v1, v20, 1
	global_load_lds_dwordx4 v130, s[0:1]
	s_mov_b32 m0, s30
	s_add_u32 s12, s4, s2
	global_load_lds_dwordx4 v134, s[0:1]
	s_addc_u32 s13, s5, 0
	s_add_i32 m0, s29, 0x14000
	v_mov_b32_e32 v133, v0
	v_mov_b32_e32 v137, v0
	global_load_lds_dwordx4 v132, s[12:13]
	s_add_i32 m0, s29, 0x16000
	v_lshl_add_u64 v[10:11], s[12:13], 0, v[132:133]
	v_lshl_add_u64 v[12:13], s[12:13], 0, v[136:137]
	global_load_lds_dwordx4 v136, s[12:13]
	s_add_u32 s12, s0, s2
	s_addc_u32 s13, s1, 0
	s_add_i32 s31, s29, 0x4000
	s_mov_b32 m0, s31
	s_add_i32 s34, s29, 0x6000
	global_load_lds_dwordx4 v130, s[12:13]
	s_mov_b32 m0, s34
	v_mov_b32_e32 v131, v0
	global_load_lds_dwordx4 v134, s[12:13]
	v_mov_b32_e32 v135, v0
	v_lshl_add_u64 v[2:3], s[4:5], 0, v[132:133]
	v_lshl_add_u64 v[4:5], s[4:5], 0, v[136:137]
	v_lshl_add_u64 v[6:7], s[0:1], 0, v[130:131]
	v_lshl_add_u64 v[8:9], s[0:1], 0, v[134:135]
	s_cmp_lg_u32 s9, 1
	s_cbranch_scc1 .LBB0_729
	s_barrier
	s_setprio 1

.LBB0_741:
	s_add_u32 s0, s0, 0x80
	s_addc_u32 s1, s1, 0
	s_add_u32 s65, s4, 0x100
	s_addc_u32 s66, s5, 0
	s_mov_b32 s4, 0
	s_add_i32 s70, s4, 2
	s_add_u32 s10, s0, 0x80
	s_addc_u32 s5, s1, 0
	s_add_i32 s71, 0, 0x10000
	v_add_u32_e32 v154, s71, v165
	ds_read_b128 v[142:145], v154
	ds_read_b128 v[146:149], v154 offset:1024
	ds_read_b128 v[150:153], v154 offset:2048
	ds_read_b128 v[154:157], v154 offset:3072
	s_cmp_eq_u32 s43, s4
	s_cselect_b32 s4, s22, s10
	s_cselect_b32 s5, s23, s5
	s_cselect_b32 s11, s13, s66
	s_cselect_b32 s10, s12, s65
	v_lshl_add_u64 v[162:163], s[0:1], 0, v[138:139]
	s_add_i32 m0, s29, 0xc000
	ds_read_b128 v[158:161], v166
	ds_read_b128 v[168:171], v166 offset:1024
	ds_read_b128 v[172:175], v166 offset:2048
	ds_read_b128 v[176:179], v166 offset:3072
	ds_read_b128 v[180:183], v166 offset:4096
	ds_read_b128 v[204:207], v166 offset:5120
	ds_read_b128 v[208:211], v166 offset:6144
	ds_read_b128 v[212:215], v166 offset:7168
	global_load_lds_dwordx4 v[162:163], off
	v_lshl_add_u64 v[162:163], s[0:1], 0, v[140:141]
	s_add_i32 m0, s29, 0xe000
	s_nop 0
	global_load_lds_dwordx4 v[162:163], off
	s_waitcnt lgkmcnt(8)
	s_barrier
	s_waitcnt lgkmcnt(0)
	s_waitcnt lgkmcnt(0)
	v_mfma_f32_16x16x32_bf16 v[126:129], v[142:145], v[158:161], 0
	v_mfma_f32_16x16x32_bf16 v[122:125], v[150:153], v[158:161], 0
	v_mfma_f32_16x16x32_bf16 v[110:113], v[142:145], v[172:175], 0
	v_mfma_f32_16x16x32_bf16 v[106:109], v[150:153], v[172:175], 0
	v_mfma_f32_16x16x32_bf16 v[94:97], v[142:145], v[180:183], 0
	v_mfma_f32_16x16x32_bf16 v[90:93], v[150:153], v[180:183], 0
	v_mfma_f32_16x16x32_bf16 v[78:81], v[142:145], v[208:211], 0
	v_mfma_f32_16x16x32_bf16 v[74:77], v[150:153], v[208:211], 0
	v_mfma_f32_16x16x32_bf16 v[126:129], v[146:149], v[168:171], v[126:129]
	v_mfma_f32_16x16x32_bf16 v[122:125], v[154:157], v[168:171], v[122:125]
	v_mfma_f32_16x16x32_bf16 v[110:113], v[146:149], v[176:179], v[110:113]
	v_mfma_f32_16x16x32_bf16 v[106:109], v[154:157], v[176:179], v[106:109]
	v_mfma_f32_16x16x32_bf16 v[94:97], v[146:149], v[204:207], v[94:97]
	v_mfma_f32_16x16x32_bf16 v[90:93], v[154:157], v[204:207], v[90:93]
	v_mfma_f32_16x16x32_bf16 v[78:81], v[146:149], v[212:215], v[78:81]
	v_mfma_f32_16x16x32_bf16 v[74:77], v[154:157], v[212:215], v[74:77]
	s_barrier
	s_add_i32 s72, 0, 0x14000
	v_add_u32_e32 v162, s72, v165
	s_add_i32 s71, s71, s28
	ds_read_b128 v[216:219], v162
	ds_read_b128 v[220:223], v162 offset:1024
	ds_read_b128 v[224:227], v162 offset:2048
	ds_read_b128 v[228:231], v162 offset:3072
	v_lshl_add_u64 v[162:163], s[10:11], 0, v[132:133]
	s_mov_b32 m0, s71
	v_lshl_add_u64 v[184:185], s[10:11], 0, v[136:137]
	global_load_lds_dwordx4 v[162:163], off
	s_add_i32 m0, s71, 0x2000
	s_nop 0
	global_load_lds_dwordx4 v[184:185], off
	s_barrier
	s_waitcnt lgkmcnt(0)
	s_waitcnt lgkmcnt(0)
	v_mfma_f32_16x16x32_bf16 v[118:121], v[216:219], v[158:161], 0
	v_mfma_f32_16x16x32_bf16 v[114:117], v[224:227], v[158:161], 0
	v_mfma_f32_16x16x32_bf16 v[102:105], v[216:219], v[172:175], 0
	v_mfma_f32_16x16x32_bf16 v[98:101], v[224:227], v[172:175], 0
	v_mfma_f32_16x16x32_bf16 v[86:89], v[216:219], v[180:183], 0
	v_mfma_f32_16x16x32_bf16 v[82:85], v[224:227], v[180:183], 0
	v_mfma_f32_16x16x32_bf16 v[70:73], v[216:219], v[208:211], 0
	v_mfma_f32_16x16x32_bf16 v[66:69], v[224:227], v[208:211], 0
	v_mfma_f32_16x16x32_bf16 v[118:121], v[220:223], v[168:171], v[118:121]
	v_mfma_f32_16x16x32_bf16 v[114:117], v[228:231], v[168:171], v[114:117]
	v_mfma_f32_16x16x32_bf16 v[102:105], v[220:223], v[176:179], v[102:105]
	v_mfma_f32_16x16x32_bf16 v[98:101], v[228:231], v[176:179], v[98:101]
	v_mfma_f32_16x16x32_bf16 v[86:89], v[220:223], v[204:207], v[86:89]
	v_mfma_f32_16x16x32_bf16 v[82:85], v[228:231], v[204:207], v[82:85]
	v_mfma_f32_16x16x32_bf16 v[70:73], v[220:223], v[212:215], v[70:73]
	v_mfma_f32_16x16x32_bf16 v[66:69], v[228:231], v[212:215], v[66:69]
	s_mov_b32 m0, s29
	v_lshl_add_u64 v[232:233], s[4:5], 0, v[130:131]
	s_barrier
	ds_read_b128 v[158:161], v166 offset:16384
	ds_read_b128 v[168:171], v166 offset:17408
	ds_read_b128 v[172:175], v166 offset:18432
	ds_read_b128 v[176:179], v166 offset:19456
	ds_read_b128 v[180:183], v166 offset:20480
	ds_read_b128 v[204:207], v166 offset:21504
	ds_read_b128 v[208:211], v166 offset:22528
	ds_read_b128 v[212:215], v166 offset:23552
	global_load_lds_dwordx4 v[232:233], off
	v_lshl_add_u64 v[234:235], s[4:5], 0, v[134:135]
	s_mov_b32 m0, s30
	s_nop 0
	global_load_lds_dwordx4 v[234:235], off
	s_barrier
	s_waitcnt lgkmcnt(0)
	s_waitcnt lgkmcnt(0)
	v_mfma_f32_16x16x32_bf16 v[62:65], v[142:145], v[158:161], 0
	v_mfma_f32_16x16x32_bf16 v[58:61], v[150:153], v[158:161], 0
	v_mfma_f32_16x16x32_bf16 v[46:49], v[142:145], v[172:175], 0
	v_mfma_f32_16x16x32_bf16 v[42:45], v[150:153], v[172:175], 0
	v_mfma_f32_16x16x32_bf16 v[30:33], v[142:145], v[180:183], 0
	v_mfma_f32_16x16x32_bf16 v[26:29], v[150:153], v[180:183], 0
	v_mfma_f32_16x16x32_bf16 v[14:17], v[142:145], v[208:211], 0
	v_mfma_f32_16x16x32_bf16 v[10:13], v[150:153], v[208:211], 0
	v_mfma_f32_16x16x32_bf16 v[62:65], v[146:149], v[168:171], v[62:65]
	v_mfma_f32_16x16x32_bf16 v[58:61], v[154:157], v[168:171], v[58:61]
	v_mfma_f32_16x16x32_bf16 v[46:49], v[146:149], v[176:179], v[46:49]
	v_mfma_f32_16x16x32_bf16 v[42:45], v[154:157], v[176:179], v[42:45]
	v_mfma_f32_16x16x32_bf16 v[30:33], v[146:149], v[204:207], v[30:33]
	v_mfma_f32_16x16x32_bf16 v[26:29], v[154:157], v[204:207], v[26:29]
	v_mfma_f32_16x16x32_bf16 v[14:17], v[146:149], v[212:215], v[14:17]
	v_mfma_f32_16x16x32_bf16 v[10:13], v[154:157], v[212:215], v[10:13]
	s_barrier
	s_add_u32 s10, s10, s2
	s_addc_u32 s11, s11, 0
	s_add_i32 s71, s72, s28
	v_lshl_add_u64 v[236:237], s[10:11], 0, v[132:133]
	s_mov_b32 m0, s71
	v_lshl_add_u64 v[238:239], s[10:11], 0, v[136:137]
	global_load_lds_dwordx4 v[236:237], off
	s_add_i32 m0, s71, 0x2000
	s_nop 0
	global_load_lds_dwordx4 v[238:239], off
	s_waitcnt vmcnt(6)
	s_barrier
	v_mfma_f32_16x16x32_bf16 v[54:57], v[216:219], v[158:161], 0
	v_mfma_f32_16x16x32_bf16 v[50:53], v[224:227], v[158:161], 0
	v_mfma_f32_16x16x32_bf16 v[38:41], v[216:219], v[172:175], 0
	v_mfma_f32_16x16x32_bf16 v[34:37], v[224:227], v[172:175], 0
	v_mfma_f32_16x16x32_bf16 v[22:25], v[216:219], v[180:183], 0
	v_mfma_f32_16x16x32_bf16 v[18:21], v[224:227], v[180:183], 0
	v_mfma_f32_16x16x32_bf16 v[6:9], v[216:219], v[208:211], 0
	v_mfma_f32_16x16x32_bf16 v[2:5], v[224:227], v[208:211], 0
	v_mfma_f32_16x16x32_bf16 v[54:57], v[220:223], v[168:171], v[54:57]
	v_mfma_f32_16x16x32_bf16 v[50:53], v[228:231], v[168:171], v[50:53]
	v_mfma_f32_16x16x32_bf16 v[38:41], v[220:223], v[176:179], v[38:41]
	v_mfma_f32_16x16x32_bf16 v[34:37], v[228:231], v[176:179], v[34:37]
	v_mfma_f32_16x16x32_bf16 v[22:25], v[220:223], v[204:207], v[22:25]
	v_mfma_f32_16x16x32_bf16 v[18:21], v[228:231], v[204:207], v[18:21]
	v_mfma_f32_16x16x32_bf16 v[6:9], v[220:223], v[212:215], v[6:9]
	v_mfma_f32_16x16x32_bf16 v[2:5], v[228:231], v[212:215], v[2:5]
	s_add_i32 s10, 0, 0x18000
	v_add_u32_e32 v154, s10, v165
	s_barrier
	ds_read_b128 v[142:145], v154
	ds_read_b128 v[146:149], v154 offset:1024
	ds_read_b128 v[150:153], v154 offset:2048
	ds_read_b128 v[154:157], v154 offset:3072
	s_add_u32 s4, s4, s2
	s_addc_u32 s5, s5, 0
	s_mov_b32 m0, s31
	v_lshl_add_u64 v[216:217], s[4:5], 0, v[130:131]
	ds_read_b128 v[158:161], v166 offset:32768
	ds_read_b128 v[168:171], v166 offset:33792
	ds_read_b128 v[172:175], v166 offset:34816
	ds_read_b128 v[176:179], v166 offset:35840
	ds_read_b128 v[180:183], v166 offset:36864
	ds_read_b128 v[204:207], v166 offset:37888
	ds_read_b128 v[208:211], v166 offset:38912
	ds_read_b128 v[212:215], v166 offset:39936
	global_load_lds_dwordx4 v[216:217], off
	v_lshl_add_u64 v[216:217], s[4:5], 0, v[134:135]
	s_mov_b32 m0, s34
	s_nop 0
	global_load_lds_dwordx4 v[216:217], off
	s_waitcnt lgkmcnt(8)
	s_barrier
	s_waitcnt lgkmcnt(0)
	s_waitcnt lgkmcnt(0)
	v_mfma_f32_16x16x32_bf16 v[126:129], v[142:145], v[158:161], v[126:129]
	v_mfma_f32_16x16x32_bf16 v[122:125], v[150:153], v[158:161], v[122:125]
	v_mfma_f32_16x16x32_bf16 v[110:113], v[142:145], v[172:175], v[110:113]
	v_mfma_f32_16x16x32_bf16 v[106:109], v[150:153], v[172:175], v[106:109]
	v_mfma_f32_16x16x32_bf16 v[94:97], v[142:145], v[180:183], v[94:97]
	v_mfma_f32_16x16x32_bf16 v[90:93], v[150:153], v[180:183], v[90:93]
	v_mfma_f32_16x16x32_bf16 v[78:81], v[142:145], v[208:211], v[78:81]
	v_mfma_f32_16x16x32_bf16 v[74:77], v[150:153], v[208:211], v[74:77]
	v_mfma_f32_16x16x32_bf16 v[126:129], v[146:149], v[168:171], v[126:129]
	v_mfma_f32_16x16x32_bf16 v[122:125], v[154:157], v[168:171], v[122:125]
	v_mfma_f32_16x16x32_bf16 v[110:113], v[146:149], v[176:179], v[110:113]
	v_mfma_f32_16x16x32_bf16 v[106:109], v[154:157], v[176:179], v[106:109]
	v_mfma_f32_16x16x32_bf16 v[94:97], v[146:149], v[204:207], v[94:97]
	v_mfma_f32_16x16x32_bf16 v[90:93], v[154:157], v[204:207], v[90:93]
	v_mfma_f32_16x16x32_bf16 v[78:81], v[146:149], v[212:215], v[78:81]
	v_mfma_f32_16x16x32_bf16 v[74:77], v[154:157], v[212:215], v[74:77]
	s_barrier
	s_add_i32 s4, 0, 0x1c000
	s_add_i32 s5, s10, s28
	v_add_u32_e32 v167, s4, v165
	v_lshl_add_u64 v[162:163], v[162:163], 0, s[6:7]
	s_mov_b32 m0, s5
	ds_read_b128 v[216:219], v167
	ds_read_b128 v[220:223], v167 offset:1024
	ds_read_b128 v[224:227], v167 offset:2048
	ds_read_b128 v[228:231], v167 offset:3072
	global_load_lds_dwordx4 v[162:163], off
	v_lshl_add_u64 v[162:163], v[184:185], 0, s[6:7]
	s_add_i32 m0, s5, 0x2000
	s_nop 0
	global_load_lds_dwordx4 v[162:163], off
	s_barrier
	s_waitcnt lgkmcnt(0)
	s_waitcnt lgkmcnt(0)
	v_mfma_f32_16x16x32_bf16 v[118:121], v[216:219], v[158:161], v[118:121]
	v_mfma_f32_16x16x32_bf16 v[114:117], v[224:227], v[158:161], v[114:117]
	v_mfma_f32_16x16x32_bf16 v[102:105], v[216:219], v[172:175], v[102:105]
	v_mfma_f32_16x16x32_bf16 v[98:101], v[224:227], v[172:175], v[98:101]
	v_mfma_f32_16x16x32_bf16 v[86:89], v[216:219], v[180:183], v[86:89]
	v_mfma_f32_16x16x32_bf16 v[82:85], v[224:227], v[180:183], v[82:85]
	v_mfma_f32_16x16x32_bf16 v[70:73], v[216:219], v[208:211], v[70:73]
	v_mfma_f32_16x16x32_bf16 v[66:69], v[224:227], v[208:211], v[66:69]
	v_mfma_f32_16x16x32_bf16 v[118:121], v[220:223], v[168:171], v[118:121]
	v_mfma_f32_16x16x32_bf16 v[114:117], v[228:231], v[168:171], v[114:117]
	v_mfma_f32_16x16x32_bf16 v[102:105], v[220:223], v[176:179], v[102:105]
	v_mfma_f32_16x16x32_bf16 v[98:101], v[228:231], v[176:179], v[98:101]
	v_mfma_f32_16x16x32_bf16 v[86:89], v[220:223], v[204:207], v[86:89]
	v_mfma_f32_16x16x32_bf16 v[82:85], v[228:231], v[204:207], v[82:85]
	v_mfma_f32_16x16x32_bf16 v[70:73], v[220:223], v[212:215], v[70:73]
	v_mfma_f32_16x16x32_bf16 v[66:69], v[228:231], v[212:215], v[66:69]
	s_mov_b32 m0, s41
	v_lshl_add_u64 v[162:163], v[232:233], 0, s[6:7]
	s_barrier
	ds_read_b128 v[158:161], v166 offset:49152
	ds_read_b128 v[168:171], v166 offset:50176
	ds_read_b128 v[172:175], v166 offset:51200
	ds_read_b128 v[176:179], v166 offset:52224
	ds_read_b128 v[180:183], v166 offset:53248
	ds_read_b128 v[204:207], v166 offset:54272
	ds_read_b128 v[208:211], v166 offset:55296
	ds_read_b128 v[212:215], v166 offset:56320
	global_load_lds_dwordx4 v[162:163], off
	v_lshl_add_u64 v[162:163], v[234:235], 0, s[6:7]
	s_mov_b32 m0, s42
	s_nop 0
	global_load_lds_dwordx4 v[162:163], off
	s_barrier
	s_waitcnt lgkmcnt(0)
	s_waitcnt lgkmcnt(0)
	v_mfma_f32_16x16x32_bf16 v[62:65], v[142:145], v[158:161], v[62:65]
	v_mfma_f32_16x16x32_bf16 v[58:61], v[150:153], v[158:161], v[58:61]
	v_mfma_f32_16x16x32_bf16 v[46:49], v[142:145], v[172:175], v[46:49]
	v_mfma_f32_16x16x32_bf16 v[42:45], v[150:153], v[172:175], v[42:45]
	v_mfma_f32_16x16x32_bf16 v[30:33], v[142:145], v[180:183], v[30:33]
	v_mfma_f32_16x16x32_bf16 v[26:29], v[150:153], v[180:183], v[26:29]
	v_mfma_f32_16x16x32_bf16 v[14:17], v[142:145], v[208:211], v[14:17]
	v_mfma_f32_16x16x32_bf16 v[10:13], v[150:153], v[208:211], v[10:13]
	v_mfma_f32_16x16x32_bf16 v[62:65], v[146:149], v[168:171], v[62:65]
	v_mfma_f32_16x16x32_bf16 v[58:61], v[154:157], v[168:171], v[58:61]
	v_mfma_f32_16x16x32_bf16 v[46:49], v[146:149], v[176:179], v[46:49]
	v_mfma_f32_16x16x32_bf16 v[42:45], v[154:157], v[176:179], v[42:45]
	v_mfma_f32_16x16x32_bf16 v[30:33], v[146:149], v[204:207], v[30:33]
	v_mfma_f32_16x16x32_bf16 v[26:29], v[154:157], v[204:207], v[26:29]
	v_mfma_f32_16x16x32_bf16 v[14:17], v[146:149], v[212:215], v[14:17]
	v_mfma_f32_16x16x32_bf16 v[10:13], v[154:157], v[212:215], v[10:13]
	s_barrier
	s_add_i32 s4, s4, s28
	v_lshl_add_u64 v[142:143], v[236:237], 0, s[6:7]
	s_mov_b32 m0, s4
	s_nop 0
	global_load_lds_dwordx4 v[142:143], off
	v_lshl_add_u64 v[142:143], v[238:239], 0, s[6:7]
	s_add_i32 m0, s4, 0x2000
	s_nop 0
	global_load_lds_dwordx4 v[142:143], off
	s_waitcnt vmcnt(6)
	s_barrier
	v_mfma_f32_16x16x32_bf16 v[54:57], v[216:219], v[158:161], v[54:57]
	v_mfma_f32_16x16x32_bf16 v[50:53], v[224:227], v[158:161], v[50:53]
	v_mfma_f32_16x16x32_bf16 v[38:41], v[216:219], v[172:175], v[38:41]
	v_mfma_f32_16x16x32_bf16 v[34:37], v[224:227], v[172:175], v[34:37]
	v_mfma_f32_16x16x32_bf16 v[22:25], v[216:219], v[180:183], v[22:25]
	v_mfma_f32_16x16x32_bf16 v[18:21], v[224:227], v[180:183], v[18:21]
	v_mfma_f32_16x16x32_bf16 v[6:9], v[216:219], v[208:211], v[6:9]
	v_mfma_f32_16x16x32_bf16 v[2:5], v[224:227], v[208:211], v[2:5]
	v_mfma_f32_16x16x32_bf16 v[54:57], v[220:223], v[168:171], v[54:57]
	v_mfma_f32_16x16x32_bf16 v[50:53], v[228:231], v[168:171], v[50:53]
	v_mfma_f32_16x16x32_bf16 v[38:41], v[220:223], v[176:179], v[38:41]
	v_mfma_f32_16x16x32_bf16 v[34:37], v[228:231], v[176:179], v[34:37]
	v_mfma_f32_16x16x32_bf16 v[22:25], v[220:223], v[204:207], v[22:25]
	v_mfma_f32_16x16x32_bf16 v[18:21], v[228:231], v[204:207], v[18:21]
	v_mfma_f32_16x16x32_bf16 v[6:9], v[220:223], v[212:215], v[6:9]
	v_mfma_f32_16x16x32_bf16 v[2:5], v[228:231], v[212:215], v[2:5]
	s_add_u32 s0, s0, 0x100
	s_addc_u32 s1, s1, 0
	s_add_u32 s65, s65, 0x100
	s_addc_u32 s66, s66, 0
	s_cmp_ge_u32 s70, s35
	s_mov_b32 s4, s70
	s_barrier
	s_cbranch_scc1 .Lkexit_742
.LBB0_742:
	s_add_i32 s70, s4, 2
	s_add_u32 s10, s0, 0x80
	s_addc_u32 s5, s1, 0
	s_add_i32 s71, 0, 0x10000
	v_add_u32_e32 v154, s71, v165
	ds_read_b128 v[142:145], v154
	ds_read_b128 v[146:149], v154 offset:1024
	ds_read_b128 v[150:153], v154 offset:2048
	ds_read_b128 v[154:157], v154 offset:3072
	s_cmp_eq_u32 s43, s4
	s_cselect_b32 s4, s22, s10
	s_cselect_b32 s5, s23, s5
	s_cselect_b32 s11, s13, s66
	s_cselect_b32 s10, s12, s65
	v_lshl_add_u64 v[162:163], s[0:1], 0, v[138:139]
	s_add_i32 m0, s29, 0xc000
	ds_read_b128 v[158:161], v166
	ds_read_b128 v[168:171], v166 offset:1024
	ds_read_b128 v[172:175], v166 offset:2048
	ds_read_b128 v[176:179], v166 offset:3072
	ds_read_b128 v[180:183], v166 offset:4096
	ds_read_b128 v[204:207], v166 offset:5120
	ds_read_b128 v[208:211], v166 offset:6144
	ds_read_b128 v[212:215], v166 offset:7168
	global_load_lds_dwordx4 v[162:163], off
	v_lshl_add_u64 v[162:163], s[0:1], 0, v[140:141]
	s_add_i32 m0, s29, 0xe000
	s_nop 0
	global_load_lds_dwordx4 v[162:163], off
	s_waitcnt lgkmcnt(8)
	s_barrier
	s_waitcnt lgkmcnt(0)
	s_waitcnt lgkmcnt(0)
	v_mfma_f32_16x16x32_bf16 v[126:129], v[142:145], v[158:161], v[126:129]
	v_mfma_f32_16x16x32_bf16 v[122:125], v[150:153], v[158:161], v[122:125]
	v_mfma_f32_16x16x32_bf16 v[110:113], v[142:145], v[172:175], v[110:113]
	v_mfma_f32_16x16x32_bf16 v[106:109], v[150:153], v[172:175], v[106:109]
	v_mfma_f32_16x16x32_bf16 v[94:97], v[142:145], v[180:183], v[94:97]
	v_mfma_f32_16x16x32_bf16 v[90:93], v[150:153], v[180:183], v[90:93]
	v_mfma_f32_16x16x32_bf16 v[78:81], v[142:145], v[208:211], v[78:81]
	v_mfma_f32_16x16x32_bf16 v[74:77], v[150:153], v[208:211], v[74:77]
	v_mfma_f32_16x16x32_bf16 v[126:129], v[146:149], v[168:171], v[126:129]
	v_mfma_f32_16x16x32_bf16 v[122:125], v[154:157], v[168:171], v[122:125]
	v_mfma_f32_16x16x32_bf16 v[110:113], v[146:149], v[176:179], v[110:113]
	v_mfma_f32_16x16x32_bf16 v[106:109], v[154:157], v[176:179], v[106:109]
	v_mfma_f32_16x16x32_bf16 v[94:97], v[146:149], v[204:207], v[94:97]
	v_mfma_f32_16x16x32_bf16 v[90:93], v[154:157], v[204:207], v[90:93]
	v_mfma_f32_16x16x32_bf16 v[78:81], v[146:149], v[212:215], v[78:81]
	v_mfma_f32_16x16x32_bf16 v[74:77], v[154:157], v[212:215], v[74:77]
	s_barrier
	s_add_i32 s72, 0, 0x14000
	v_add_u32_e32 v162, s72, v165
	s_add_i32 s71, s71, s28
	ds_read_b128 v[216:219], v162
	ds_read_b128 v[220:223], v162 offset:1024
	ds_read_b128 v[224:227], v162 offset:2048
	ds_read_b128 v[228:231], v162 offset:3072
	v_lshl_add_u64 v[162:163], s[10:11], 0, v[132:133]
	s_mov_b32 m0, s71
	v_lshl_add_u64 v[184:185], s[10:11], 0, v[136:137]
	global_load_lds_dwordx4 v[162:163], off
	s_add_i32 m0, s71, 0x2000
	s_nop 0
	global_load_lds_dwordx4 v[184:185], off
	s_barrier
	s_waitcnt lgkmcnt(0)
	s_waitcnt lgkmcnt(0)
	v_mfma_f32_16x16x32_bf16 v[118:121], v[216:219], v[158:161], v[118:121]
	v_mfma_f32_16x16x32_bf16 v[114:117], v[224:227], v[158:161], v[114:117]
	v_mfma_f32_16x16x32_bf16 v[102:105], v[216:219], v[172:175], v[102:105]
	v_mfma_f32_16x16x32_bf16 v[98:101], v[224:227], v[172:175], v[98:101]
	v_mfma_f32_16x16x32_bf16 v[86:89], v[216:219], v[180:183], v[86:89]
	v_mfma_f32_16x16x32_bf16 v[82:85], v[224:227], v[180:183], v[82:85]
	v_mfma_f32_16x16x32_bf16 v[70:73], v[216:219], v[208:211], v[70:73]
	v_mfma_f32_16x16x32_bf16 v[66:69], v[224:227], v[208:211], v[66:69]
	v_mfma_f32_16x16x32_bf16 v[118:121], v[220:223], v[168:171], v[118:121]
	v_mfma_f32_16x16x32_bf16 v[114:117], v[228:231], v[168:171], v[114:117]
	v_mfma_f32_16x16x32_bf16 v[102:105], v[220:223], v[176:179], v[102:105]
	v_mfma_f32_16x16x32_bf16 v[98:101], v[228:231], v[176:179], v[98:101]
	v_mfma_f32_16x16x32_bf16 v[86:89], v[220:223], v[204:207], v[86:89]
	v_mfma_f32_16x16x32_bf16 v[82:85], v[228:231], v[204:207], v[82:85]
	v_mfma_f32_16x16x32_bf16 v[70:73], v[220:223], v[212:215], v[70:73]
	v_mfma_f32_16x16x32_bf16 v[66:69], v[228:231], v[212:215], v[66:69]
	s_mov_b32 m0, s29
	v_lshl_add_u64 v[232:233], s[4:5], 0, v[130:131]
	s_barrier
	ds_read_b128 v[158:161], v166 offset:16384
	ds_read_b128 v[168:171], v166 offset:17408
	ds_read_b128 v[172:175], v166 offset:18432
	ds_read_b128 v[176:179], v166 offset:19456
	ds_read_b128 v[180:183], v166 offset:20480
	ds_read_b128 v[204:207], v166 offset:21504
	ds_read_b128 v[208:211], v166 offset:22528
	ds_read_b128 v[212:215], v166 offset:23552
	global_load_lds_dwordx4 v[232:233], off
	v_lshl_add_u64 v[234:235], s[4:5], 0, v[134:135]
	s_mov_b32 m0, s30
	s_nop 0
	global_load_lds_dwordx4 v[234:235], off
	s_barrier
	s_waitcnt lgkmcnt(0)
	s_waitcnt lgkmcnt(0)
	v_mfma_f32_16x16x32_bf16 v[62:65], v[142:145], v[158:161], v[62:65]
	v_mfma_f32_16x16x32_bf16 v[58:61], v[150:153], v[158:161], v[58:61]
	v_mfma_f32_16x16x32_bf16 v[46:49], v[142:145], v[172:175], v[46:49]
	v_mfma_f32_16x16x32_bf16 v[42:45], v[150:153], v[172:175], v[42:45]
	v_mfma_f32_16x16x32_bf16 v[30:33], v[142:145], v[180:183], v[30:33]
	v_mfma_f32_16x16x32_bf16 v[26:29], v[150:153], v[180:183], v[26:29]
	v_mfma_f32_16x16x32_bf16 v[14:17], v[142:145], v[208:211], v[14:17]
	v_mfma_f32_16x16x32_bf16 v[10:13], v[150:153], v[208:211], v[10:13]
	v_mfma_f32_16x16x32_bf16 v[62:65], v[146:149], v[168:171], v[62:65]
	v_mfma_f32_16x16x32_bf16 v[58:61], v[154:157], v[168:171], v[58:61]
	v_mfma_f32_16x16x32_bf16 v[46:49], v[146:149], v[176:179], v[46:49]
	v_mfma_f32_16x16x32_bf16 v[42:45], v[154:157], v[176:179], v[42:45]
	v_mfma_f32_16x16x32_bf16 v[30:33], v[146:149], v[204:207], v[30:33]
	v_mfma_f32_16x16x32_bf16 v[26:29], v[154:157], v[204:207], v[26:29]
	v_mfma_f32_16x16x32_bf16 v[14:17], v[146:149], v[212:215], v[14:17]
	v_mfma_f32_16x16x32_bf16 v[10:13], v[154:157], v[212:215], v[10:13]
	s_barrier
	s_add_u32 s10, s10, s2
	s_addc_u32 s11, s11, 0
	s_add_i32 s71, s72, s28
	v_lshl_add_u64 v[236:237], s[10:11], 0, v[132:133]
	s_mov_b32 m0, s71
	v_lshl_add_u64 v[238:239], s[10:11], 0, v[136:137]
	global_load_lds_dwordx4 v[236:237], off
	s_add_i32 m0, s71, 0x2000
	s_nop 0
	global_load_lds_dwordx4 v[238:239], off
	s_waitcnt vmcnt(6)
	s_barrier
	v_mfma_f32_16x16x32_bf16 v[54:57], v[216:219], v[158:161], v[54:57]
	v_mfma_f32_16x16x32_bf16 v[50:53], v[224:227], v[158:161], v[50:53]
	v_mfma_f32_16x16x32_bf16 v[38:41], v[216:219], v[172:175], v[38:41]
	v_mfma_f32_16x16x32_bf16 v[34:37], v[224:227], v[172:175], v[34:37]
	v_mfma_f32_16x16x32_bf16 v[22:25], v[216:219], v[180:183], v[22:25]
	v_mfma_f32_16x16x32_bf16 v[18:21], v[224:227], v[180:183], v[18:21]
	v_mfma_f32_16x16x32_bf16 v[6:9], v[216:219], v[208:211], v[6:9]
	v_mfma_f32_16x16x32_bf16 v[2:5], v[224:227], v[208:211], v[2:5]
	v_mfma_f32_16x16x32_bf16 v[54:57], v[220:223], v[168:171], v[54:57]
	v_mfma_f32_16x16x32_bf16 v[50:53], v[228:231], v[168:171], v[50:53]
	v_mfma_f32_16x16x32_bf16 v[38:41], v[220:223], v[176:179], v[38:41]
	v_mfma_f32_16x16x32_bf16 v[34:37], v[228:231], v[176:179], v[34:37]
	v_mfma_f32_16x16x32_bf16 v[22:25], v[220:223], v[204:207], v[22:25]
	v_mfma_f32_16x16x32_bf16 v[18:21], v[228:231], v[204:207], v[18:21]
	v_mfma_f32_16x16x32_bf16 v[6:9], v[220:223], v[212:215], v[6:9]
	v_mfma_f32_16x16x32_bf16 v[2:5], v[228:231], v[212:215], v[2:5]
	s_add_i32 s10, 0, 0x18000
	v_add_u32_e32 v154, s10, v165
	s_barrier
	ds_read_b128 v[142:145], v154
	ds_read_b128 v[146:149], v154 offset:1024
	ds_read_b128 v[150:153], v154 offset:2048
	ds_read_b128 v[154:157], v154 offset:3072
	s_add_u32 s4, s4, s2
	s_addc_u32 s5, s5, 0
	s_mov_b32 m0, s31
	v_lshl_add_u64 v[216:217], s[4:5], 0, v[130:131]
	ds_read_b128 v[158:161], v166 offset:32768
	ds_read_b128 v[168:171], v166 offset:33792
	ds_read_b128 v[172:175], v166 offset:34816
	ds_read_b128 v[176:179], v166 offset:35840
	ds_read_b128 v[180:183], v166 offset:36864
	ds_read_b128 v[204:207], v166 offset:37888
	ds_read_b128 v[208:211], v166 offset:38912
	ds_read_b128 v[212:215], v166 offset:39936
	global_load_lds_dwordx4 v[216:217], off
	v_lshl_add_u64 v[216:217], s[4:5], 0, v[134:135]
	s_mov_b32 m0, s34
	s_nop 0
	global_load_lds_dwordx4 v[216:217], off
	s_waitcnt lgkmcnt(8)
	s_barrier
	s_waitcnt lgkmcnt(0)
	s_waitcnt lgkmcnt(0)
	v_mfma_f32_16x16x32_bf16 v[126:129], v[142:145], v[158:161], v[126:129]
	v_mfma_f32_16x16x32_bf16 v[122:125], v[150:153], v[158:161], v[122:125]
	v_mfma_f32_16x16x32_bf16 v[110:113], v[142:145], v[172:175], v[110:113]
	v_mfma_f32_16x16x32_bf16 v[106:109], v[150:153], v[172:175], v[106:109]
	v_mfma_f32_16x16x32_bf16 v[94:97], v[142:145], v[180:183], v[94:97]
	v_mfma_f32_16x16x32_bf16 v[90:93], v[150:153], v[180:183], v[90:93]
	v_mfma_f32_16x16x32_bf16 v[78:81], v[142:145], v[208:211], v[78:81]
	v_mfma_f32_16x16x32_bf16 v[74:77], v[150:153], v[208:211], v[74:77]
	v_mfma_f32_16x16x32_bf16 v[126:129], v[146:149], v[168:171], v[126:129]
	v_mfma_f32_16x16x32_bf16 v[122:125], v[154:157], v[168:171], v[122:125]
	v_mfma_f32_16x16x32_bf16 v[110:113], v[146:149], v[176:179], v[110:113]
	v_mfma_f32_16x16x32_bf16 v[106:109], v[154:157], v[176:179], v[106:109]
	v_mfma_f32_16x16x32_bf16 v[94:97], v[146:149], v[204:207], v[94:97]
	v_mfma_f32_16x16x32_bf16 v[90:93], v[154:157], v[204:207], v[90:93]
	v_mfma_f32_16x16x32_bf16 v[78:81], v[146:149], v[212:215], v[78:81]
	v_mfma_f32_16x16x32_bf16 v[74:77], v[154:157], v[212:215], v[74:77]
	s_barrier
	s_add_i32 s4, 0, 0x1c000
	s_add_i32 s5, s10, s28
	v_add_u32_e32 v167, s4, v165
	v_lshl_add_u64 v[162:163], v[162:163], 0, s[6:7]
	s_mov_b32 m0, s5
	ds_read_b128 v[216:219], v167
	ds_read_b128 v[220:223], v167 offset:1024
	ds_read_b128 v[224:227], v167 offset:2048
	ds_read_b128 v[228:231], v167 offset:3072
	global_load_lds_dwordx4 v[162:163], off
	v_lshl_add_u64 v[162:163], v[184:185], 0, s[6:7]
	s_add_i32 m0, s5, 0x2000
	s_nop 0
	global_load_lds_dwordx4 v[162:163], off
	s_barrier
	s_waitcnt lgkmcnt(0)
	s_waitcnt lgkmcnt(0)
	v_mfma_f32_16x16x32_bf16 v[118:121], v[216:219], v[158:161], v[118:121]
	v_mfma_f32_16x16x32_bf16 v[114:117], v[224:227], v[158:161], v[114:117]
	v_mfma_f32_16x16x32_bf16 v[102:105], v[216:219], v[172:175], v[102:105]
	v_mfma_f32_16x16x32_bf16 v[98:101], v[224:227], v[172:175], v[98:101]
	v_mfma_f32_16x16x32_bf16 v[86:89], v[216:219], v[180:183], v[86:89]
	v_mfma_f32_16x16x32_bf16 v[82:85], v[224:227], v[180:183], v[82:85]
	v_mfma_f32_16x16x32_bf16 v[70:73], v[216:219], v[208:211], v[70:73]
	v_mfma_f32_16x16x32_bf16 v[66:69], v[224:227], v[208:211], v[66:69]
	v_mfma_f32_16x16x32_bf16 v[118:121], v[220:223], v[168:171], v[118:121]
	v_mfma_f32_16x16x32_bf16 v[114:117], v[228:231], v[168:171], v[114:117]
	v_mfma_f32_16x16x32_bf16 v[102:105], v[220:223], v[176:179], v[102:105]
	v_mfma_f32_16x16x32_bf16 v[98:101], v[228:231], v[176:179], v[98:101]
	v_mfma_f32_16x16x32_bf16 v[86:89], v[220:223], v[204:207], v[86:89]
	v_mfma_f32_16x16x32_bf16 v[82:85], v[228:231], v[204:207], v[82:85]
	v_mfma_f32_16x16x32_bf16 v[70:73], v[220:223], v[212:215], v[70:73]
	v_mfma_f32_16x16x32_bf16 v[66:69], v[228:231], v[212:215], v[66:69]
	s_mov_b32 m0, s41
	v_lshl_add_u64 v[162:163], v[232:233], 0, s[6:7]
	s_barrier
	ds_read_b128 v[158:161], v166 offset:49152
	ds_read_b128 v[168:171], v166 offset:50176
	ds_read_b128 v[172:175], v166 offset:51200
	ds_read_b128 v[176:179], v166 offset:52224
	ds_read_b128 v[180:183], v166 offset:53248
	ds_read_b128 v[204:207], v166 offset:54272
	ds_read_b128 v[208:211], v166 offset:55296
	ds_read_b128 v[212:215], v166 offset:56320
	global_load_lds_dwordx4 v[162:163], off
	v_lshl_add_u64 v[162:163], v[234:235], 0, s[6:7]
	s_mov_b32 m0, s42
	s_nop 0
	global_load_lds_dwordx4 v[162:163], off
	s_barrier
	s_waitcnt lgkmcnt(0)
	s_waitcnt lgkmcnt(0)
	v_mfma_f32_16x16x32_bf16 v[62:65], v[142:145], v[158:161], v[62:65]
	v_mfma_f32_16x16x32_bf16 v[58:61], v[150:153], v[158:161], v[58:61]
	v_mfma_f32_16x16x32_bf16 v[46:49], v[142:145], v[172:175], v[46:49]
	v_mfma_f32_16x16x32_bf16 v[42:45], v[150:153], v[172:175], v[42:45]
	v_mfma_f32_16x16x32_bf16 v[30:33], v[142:145], v[180:183], v[30:33]
	v_mfma_f32_16x16x32_bf16 v[26:29], v[150:153], v[180:183], v[26:29]
	v_mfma_f32_16x16x32_bf16 v[14:17], v[142:145], v[208:211], v[14:17]
	v_mfma_f32_16x16x32_bf16 v[10:13], v[150:153], v[208:211], v[10:13]
	v_mfma_f32_16x16x32_bf16 v[62:65], v[146:149], v[168:171], v[62:65]
	v_mfma_f32_16x16x32_bf16 v[58:61], v[154:157], v[168:171], v[58:61]
	v_mfma_f32_16x16x32_bf16 v[46:49], v[146:149], v[176:179], v[46:49]
	v_mfma_f32_16x16x32_bf16 v[42:45], v[154:157], v[176:179], v[42:45]
	v_mfma_f32_16x16x32_bf16 v[30:33], v[146:149], v[204:207], v[30:33]
	v_mfma_f32_16x16x32_bf16 v[26:29], v[154:157], v[204:207], v[26:29]
	v_mfma_f32_16x16x32_bf16 v[14:17], v[146:149], v[212:215], v[14:17]
	v_mfma_f32_16x16x32_bf16 v[10:13], v[154:157], v[212:215], v[10:13]
	s_barrier
	s_add_i32 s4, s4, s28
	v_lshl_add_u64 v[142:143], v[236:237], 0, s[6:7]
	s_mov_b32 m0, s4
	s_nop 0
	global_load_lds_dwordx4 v[142:143], off
	v_lshl_add_u64 v[142:143], v[238:239], 0, s[6:7]
	s_add_i32 m0, s4, 0x2000
	s_nop 0
	global_load_lds_dwordx4 v[142:143], off
	s_waitcnt vmcnt(6)
	s_barrier
	v_mfma_f32_16x16x32_bf16 v[54:57], v[216:219], v[158:161], v[54:57]
	v_mfma_f32_16x16x32_bf16 v[50:53], v[224:227], v[158:161], v[50:53]
	v_mfma_f32_16x16x32_bf16 v[38:41], v[216:219], v[172:175], v[38:41]
	v_mfma_f32_16x16x32_bf16 v[34:37], v[224:227], v[172:175], v[34:37]
	v_mfma_f32_16x16x32_bf16 v[22:25], v[216:219], v[180:183], v[22:25]
	v_mfma_f32_16x16x32_bf16 v[18:21], v[224:227], v[180:183], v[18:21]
	v_mfma_f32_16x16x32_bf16 v[6:9], v[216:219], v[208:211], v[6:9]
	v_mfma_f32_16x16x32_bf16 v[2:5], v[224:227], v[208:211], v[2:5]
	v_mfma_f32_16x16x32_bf16 v[54:57], v[220:223], v[168:171], v[54:57]
	v_mfma_f32_16x16x32_bf16 v[50:53], v[228:231], v[168:171], v[50:53]
	v_mfma_f32_16x16x32_bf16 v[38:41], v[220:223], v[176:179], v[38:41]
	v_mfma_f32_16x16x32_bf16 v[34:37], v[228:231], v[176:179], v[34:37]
	v_mfma_f32_16x16x32_bf16 v[22:25], v[220:223], v[204:207], v[22:25]
	v_mfma_f32_16x16x32_bf16 v[18:21], v[228:231], v[204:207], v[18:21]
	v_mfma_f32_16x16x32_bf16 v[6:9], v[220:223], v[212:215], v[6:9]
	v_mfma_f32_16x16x32_bf16 v[2:5], v[228:231], v[212:215], v[2:5]
	s_add_u32 s0, s0, 0x100
	s_addc_u32 s1, s1, 0
	s_add_u32 s65, s65, 0x100
	s_addc_u32 s66, s66, 0
	s_cmp_ge_u32 s70, s35
	s_mov_b32 s4, s70
	s_barrier
	s_cbranch_scc0 .LBB0_742

.LBB0_790:
	s_andn2_b64 vcc, exec, s[0:1]
	s_cbranch_vccnz .LBB0_974
	s_waitcnt lgkmcnt(0)
	v_bfe_i32 v3, v14, 27, 1
	v_lshlrev_b32_e32 v1, 4, v14
	v_lshrrev_b32_e32 v3, 22, v3
	v_add_u32_e32 v3, v1, v3
	v_and_b32_e32 v3, 0xfffffc00, v3
	v_ashrrev_i32_e32 v2, 31, v14
	v_sub_u32_e32 v3, v1, v3
	v_lshrrev_b32_e32 v2, 26, v2
	v_lshrrev_b32_e32 v4, 4, v3
	v_add_u32_e32 v2, v14, v2
	v_bitop3_b32 v4, v4, v3, 32 bitop3:0x6c
	v_ashrrev_i32_e32 v3, 31, v3
	v_ashrrev_i32_e32 v2, 6, v2
	v_lshrrev_b32_e32 v3, 26, v3
	v_lshlrev_b32_e32 v5, 3, v2
	v_add_u32_e32 v3, v4, v3
	v_and_b32_e32 v5, -16, v5
	v_ashrrev_i32_e32 v3, 6, v3
	v_lshlrev_b32_e32 v2, 5, v2
	v_add_u32_e32 v5, v3, v5
	v_and_b32_e32 v15, 32, v2
	v_mul_i32_i24_e32 v2, 64, v3
	v_sub_u32_e32 v2, v4, v2
	v_lshlrev_b32_e32 v4, 1, v5
	v_lshrrev_b32_e32 v6, 2, v5
	v_and_b32_e32 v3, 3, v3
	s_mov_b32 s0, 0x7fffffe0
	v_ashrrev_i16_sdwa v2, v190, sext(v2) dst_sel:DWORD dst_unused:UNUSED_PAD src0_sel:DWORD src1_sel:BYTE_0
	v_and_b32_e32 v4, 24, v4
	v_and_b32_e32 v6, 4, v6
	v_and_or_b32 v3, v5, s0, v3
	v_bfe_i32 v16, v2, 0, 16
	v_or3_b32 v3, v3, v6, v4
	v_add_u32_e32 v2, v15, v16
	v_mul_lo_u32 v17, v5, s64
	v_mul_lo_u32 v3, v3, s64
	v_add_u32_e32 v1, 0x2000, v1
	v_add_lshl_u32 v130, v2, v17, 1
	v_add_lshl_u32 v132, v3, v2, 1
	v_ashrrev_i32_e32 v2, 31, v1
	v_lshrrev_b32_e32 v2, 22, v2
	v_add_u32_e32 v2, v1, v2
	v_ashrrev_i32_e32 v2, 10, v2
	v_mul_i32_i24_e32 v3, 0x400, v2
	v_sub_u32_e32 v1, v1, v3
	v_lshrrev_b32_e32 v3, 4, v1
	v_bitop3_b32 v1, v3, v1, 32 bitop3:0x6c
	v_ashrrev_i32_e32 v4, 31, v1
	v_lshrrev_b32_e32 v4, 26, v4
	v_lshlrev_b32_e32 v3, 3, v2
	v_add_u32_e32 v4, v1, v4
	v_and_b32_e32 v3, -16, v3
	v_ashrrev_i32_e32 v5, 6, v4
	v_add_u32_e32 v3, v5, v3
	v_and_b32_e32 v5, 3, v5
	s_lshl_b32 s92, s64, 8
	v_and_or_b32 v5, v3, s0, v5
	s_lshl_b64 s[2:3], s[92:93], 1
	s_ashr_i32 s0, s31, 31
	s_mul_i32 s0, s2, s0
	s_mul_hi_u32 s1, s2, s31
	s_add_i32 s0, s1, s0
	s_bfe_u32 s1, s64, 0x10017
	s_mul_i32 s4, s1, s31
	s_add_i32 s10, s0, s4
	s_ashr_i32 s4, s71, 31
	s_mul_i32 s4, s2, s4
	s_mul_hi_u32 s5, s2, s71
	s_ashr_i32 s8, s30, 6
	v_lshlrev_b32_e32 v2, 5, v2
	s_add_i32 s4, s5, s4
	s_mul_i32 s1, s1, s71
	v_and_b32_e32 v18, 32, v2
	v_and_b32_e32 v2, 0xc0, v4
	s_ashr_i32 s9, s30, 8
	s_lshl_b32 s34, s8, 10
	s_add_i32 s1, s4, s1
	s_mul_i32 s4, s2, s71
	v_sub_u32_e32 v1, v1, v2
	v_lshlrev_b32_e32 v2, 1, v3
	v_lshrrev_b32_e32 v4, 2, v3
	s_add_u32 s4, s36, s4
	v_ashrrev_i16_sdwa v1, v190, sext(v1) dst_sel:DWORD dst_unused:UNUSED_PAD src0_sel:DWORD src1_sel:BYTE_0
	v_and_b32_e32 v2, 24, v2
	v_and_b32_e32 v4, 4, v4
	s_addc_u32 s5, s37, s1
	s_add_i32 s35, s34, 0
	v_bfe_i32 v19, v1, 0, 16
	v_or3_b32 v2, v5, v4, v2
	s_add_i32 m0, s35, 0x10000
	v_add_u32_e32 v1, v18, v19
	v_mul_lo_u32 v2, v2, s64
	s_mul_i32 s0, s2, s31
	global_load_lds_dwordx4 v132, s[4:5]
	s_add_i32 m0, s35, 0x12000
	v_add_lshl_u32 v136, v2, v1, 1
	s_add_u32 s0, s56, s0
	v_mul_lo_u32 v20, v3, s64
	global_load_lds_dwordx4 v136, s[4:5]
	s_addc_u32 s1, s52, s10
	s_mov_b32 m0, s35
	s_add_i32 s40, s35, 0x2000
	v_add_lshl_u32 v134, v1, v20, 1
	global_load_lds_dwordx4 v130, s[0:1]
	s_mov_b32 m0, s40
	s_add_u32 s10, s4, s92
	global_load_lds_dwordx4 v134, s[0:1]
	s_addc_u32 s11, s5, 0
	s_add_i32 m0, s35, 0x14000
	v_mov_b32_e32 v133, v0
	global_load_lds_dwordx4 v132, s[10:11]
	s_add_i32 m0, s35, 0x16000
	s_add_u32 s12, s0, s92
	s_addc_u32 s13, s1, 0
	s_add_i32 s41, s35, 0x4000
	global_load_lds_dwordx4 v136, s[10:11]
	s_mov_b32 m0, s41
	s_add_i32 s42, s35, 0x6000
	global_load_lds_dwordx4 v130, s[12:13]
	s_mov_b32 m0, s42
	v_mov_b32_e32 v137, v0
	global_load_lds_dwordx4 v134, s[12:13]
	v_mov_b32_e32 v131, v0
	v_mov_b32_e32 v135, v0
	v_lshl_add_u64 v[12:13], s[4:5], 0, v[132:133]
	v_lshl_add_u64 v[10:11], s[4:5], 0, v[136:137]
	v_lshl_add_u64 v[8:9], s[0:1], 0, v[130:131]
	v_lshl_add_u64 v[6:7], s[0:1], 0, v[134:135]
	v_lshl_add_u64 v[4:5], s[10:11], 0, v[132:133]
	s_cmp_lg_u32 s9, 1
	v_lshl_add_u64 v[2:3], s[10:11], 0, v[136:137]
	s_cbranch_scc1 .LBB0_793
	s_barrier
	s_setprio 1

.LBB0_805:
	s_add_u32 s0, s0, 0x80
	s_addc_u32 s1, s1, 0
	s_add_u32 s12, s4, 0x100
	s_addc_u32 s13, s5, 0
	s_mov_b32 s4, 0
	s_waitcnt vmcnt(0)
	s_add_i32 s27, s4, 2
	s_add_u32 s10, s0, 0x80
	s_addc_u32 s5, s1, 0
	s_add_i32 s28, 0, 0x10000
	v_add_u32_e32 v154, s28, v171
	ds_read_b128 v[142:145], v154
	ds_read_b128 v[146:149], v154 offset:1024
	ds_read_b128 v[150:153], v154 offset:2048
	ds_read_b128 v[154:157], v154 offset:3072
	s_cmp_eq_u32 s48, s4
	s_cselect_b32 s4, s22, s10
	s_cselect_b32 s5, s23, s5
	s_cselect_b32 s11, s25, s13
	s_cselect_b32 s10, s24, s12
	v_lshl_add_u64 v[212:213], s[0:1], 0, v[138:139]
	s_add_i32 m0, s35, 0xc000
	ds_read_b128 v[158:161], v172
	ds_read_b128 v[162:165], v172 offset:1024
	ds_read_b128 v[166:169], v172 offset:2048
	ds_read_b128 v[174:177], v172 offset:3072
	ds_read_b128 v[178:181], v172 offset:4096
	ds_read_b128 v[182:185], v172 offset:5120
	ds_read_b128 v[204:207], v172 offset:6144
	ds_read_b128 v[208:211], v172 offset:7168
	global_load_lds_dwordx4 v[212:213], off
	v_lshl_add_u64 v[212:213], s[0:1], 0, v[140:141]
	s_add_i32 m0, s35, 0xe000
	s_nop 0
	global_load_lds_dwordx4 v[212:213], off
	s_waitcnt lgkmcnt(8)
	s_barrier
	s_waitcnt lgkmcnt(0)
	s_waitcnt lgkmcnt(0)
	v_mfma_f32_16x16x32_bf16 v[126:129], v[142:145], v[158:161], 0
	v_mfma_f32_16x16x32_bf16 v[122:125], v[150:153], v[158:161], 0
	v_mfma_f32_16x16x32_bf16 v[110:113], v[142:145], v[166:169], 0
	v_mfma_f32_16x16x32_bf16 v[106:109], v[150:153], v[166:169], 0
	v_mfma_f32_16x16x32_bf16 v[94:97], v[142:145], v[178:181], 0
	v_mfma_f32_16x16x32_bf16 v[90:93], v[150:153], v[178:181], 0
	v_mfma_f32_16x16x32_bf16 v[78:81], v[142:145], v[204:207], 0
	v_mfma_f32_16x16x32_bf16 v[74:77], v[150:153], v[204:207], 0
	v_mfma_f32_16x16x32_bf16 v[126:129], v[146:149], v[162:165], v[126:129]
	v_mfma_f32_16x16x32_bf16 v[122:125], v[154:157], v[162:165], v[122:125]
	v_mfma_f32_16x16x32_bf16 v[110:113], v[146:149], v[174:177], v[110:113]
	v_mfma_f32_16x16x32_bf16 v[106:109], v[154:157], v[174:177], v[106:109]
	v_mfma_f32_16x16x32_bf16 v[94:97], v[146:149], v[182:185], v[94:97]
	v_mfma_f32_16x16x32_bf16 v[90:93], v[154:157], v[182:185], v[90:93]
	v_mfma_f32_16x16x32_bf16 v[78:81], v[146:149], v[208:211], v[78:81]
	v_mfma_f32_16x16x32_bf16 v[74:77], v[154:157], v[208:211], v[74:77]
	s_barrier
	s_add_i32 s29, 0, 0x14000
	s_add_i32 s28, s28, s34
	v_add_u32_e32 v173, s29, v171
	v_lshl_add_u64 v[228:229], s[10:11], 0, v[132:133]
	s_mov_b32 m0, s28
	ds_read_b128 v[212:215], v173
	ds_read_b128 v[216:219], v173 offset:1024
	ds_read_b128 v[220:223], v173 offset:2048
	ds_read_b128 v[224:227], v173 offset:3072
	global_load_lds_dwordx4 v[228:229], off
	v_lshl_add_u64 v[230:231], s[10:11], 0, v[136:137]
	s_add_i32 m0, s28, 0x2000
	s_nop 0
	global_load_lds_dwordx4 v[230:231], off
	s_barrier
	s_waitcnt lgkmcnt(0)
	s_waitcnt lgkmcnt(0)
	v_mfma_f32_16x16x32_bf16 v[118:121], v[212:215], v[158:161], 0
	v_mfma_f32_16x16x32_bf16 v[114:117], v[220:223], v[158:161], 0
	v_mfma_f32_16x16x32_bf16 v[102:105], v[212:215], v[166:169], 0
	v_mfma_f32_16x16x32_bf16 v[98:101], v[220:223], v[166:169], 0
	v_mfma_f32_16x16x32_bf16 v[86:89], v[212:215], v[178:181], 0
	v_mfma_f32_16x16x32_bf16 v[82:85], v[220:223], v[178:181], 0
	v_mfma_f32_16x16x32_bf16 v[70:73], v[212:215], v[204:207], 0
	v_mfma_f32_16x16x32_bf16 v[66:69], v[220:223], v[204:207], 0
	v_mfma_f32_16x16x32_bf16 v[118:121], v[216:219], v[162:165], v[118:121]
	v_mfma_f32_16x16x32_bf16 v[114:117], v[224:227], v[162:165], v[114:117]
	v_mfma_f32_16x16x32_bf16 v[102:105], v[216:219], v[174:177], v[102:105]
	v_mfma_f32_16x16x32_bf16 v[98:101], v[224:227], v[174:177], v[98:101]
	v_mfma_f32_16x16x32_bf16 v[86:89], v[216:219], v[182:185], v[86:89]
	v_mfma_f32_16x16x32_bf16 v[82:85], v[224:227], v[182:185], v[82:85]
	v_mfma_f32_16x16x32_bf16 v[70:73], v[216:219], v[208:211], v[70:73]
	v_mfma_f32_16x16x32_bf16 v[66:69], v[224:227], v[208:211], v[66:69]
	s_mov_b32 m0, s35
	v_lshl_add_u64 v[232:233], s[4:5], 0, v[130:131]
	s_barrier
	ds_read_b128 v[158:161], v172 offset:16384
	ds_read_b128 v[162:165], v172 offset:17408
	ds_read_b128 v[166:169], v172 offset:18432
	ds_read_b128 v[174:177], v172 offset:19456
	ds_read_b128 v[178:181], v172 offset:20480
	ds_read_b128 v[182:185], v172 offset:21504
	ds_read_b128 v[204:207], v172 offset:22528
	ds_read_b128 v[208:211], v172 offset:23552
	global_load_lds_dwordx4 v[232:233], off
	v_lshl_add_u64 v[234:235], s[4:5], 0, v[134:135]
	s_mov_b32 m0, s40
	s_nop 0
	global_load_lds_dwordx4 v[234:235], off
	s_barrier
	s_waitcnt lgkmcnt(0)
	s_waitcnt lgkmcnt(0)
	v_mfma_f32_16x16x32_bf16 v[62:65], v[142:145], v[158:161], 0
	v_mfma_f32_16x16x32_bf16 v[58:61], v[150:153], v[158:161], 0
	v_mfma_f32_16x16x32_bf16 v[46:49], v[142:145], v[166:169], 0
	v_mfma_f32_16x16x32_bf16 v[42:45], v[150:153], v[166:169], 0
	v_mfma_f32_16x16x32_bf16 v[30:33], v[142:145], v[178:181], 0
	v_mfma_f32_16x16x32_bf16 v[26:29], v[150:153], v[178:181], 0
	v_mfma_f32_16x16x32_bf16 v[14:17], v[142:145], v[204:207], 0
	v_mfma_f32_16x16x32_bf16 v[10:13], v[150:153], v[204:207], 0
	v_mfma_f32_16x16x32_bf16 v[62:65], v[146:149], v[162:165], v[62:65]
	v_mfma_f32_16x16x32_bf16 v[58:61], v[154:157], v[162:165], v[58:61]
	v_mfma_f32_16x16x32_bf16 v[46:49], v[146:149], v[174:177], v[46:49]
	v_mfma_f32_16x16x32_bf16 v[42:45], v[154:157], v[174:177], v[42:45]
	v_mfma_f32_16x16x32_bf16 v[30:33], v[146:149], v[182:185], v[30:33]
	v_mfma_f32_16x16x32_bf16 v[26:29], v[154:157], v[182:185], v[26:29]
	v_mfma_f32_16x16x32_bf16 v[14:17], v[146:149], v[208:211], v[14:17]
	v_mfma_f32_16x16x32_bf16 v[10:13], v[154:157], v[208:211], v[10:13]
	s_barrier
	s_add_u32 s10, s10, s92
	s_addc_u32 s11, s11, 0
	s_add_i32 s28, s29, s34
	v_lshl_add_u64 v[236:237], s[10:11], 0, v[132:133]
	s_mov_b32 m0, s28
	v_lshl_add_u64 v[238:239], s[10:11], 0, v[136:137]
	global_load_lds_dwordx4 v[236:237], off
	s_add_i32 m0, s28, 0x2000
	s_nop 0
	global_load_lds_dwordx4 v[238:239], off
	s_waitcnt vmcnt(6)
	s_barrier
	v_mfma_f32_16x16x32_bf16 v[54:57], v[212:215], v[158:161], 0
	v_mfma_f32_16x16x32_bf16 v[50:53], v[220:223], v[158:161], 0
	v_mfma_f32_16x16x32_bf16 v[38:41], v[212:215], v[166:169], 0
	v_mfma_f32_16x16x32_bf16 v[34:37], v[220:223], v[166:169], 0
	v_mfma_f32_16x16x32_bf16 v[22:25], v[212:215], v[178:181], 0
	v_mfma_f32_16x16x32_bf16 v[18:21], v[220:223], v[178:181], 0
	v_mfma_f32_16x16x32_bf16 v[6:9], v[212:215], v[204:207], 0
	v_mfma_f32_16x16x32_bf16 v[2:5], v[220:223], v[204:207], 0
	v_mfma_f32_16x16x32_bf16 v[54:57], v[216:219], v[162:165], v[54:57]
	v_mfma_f32_16x16x32_bf16 v[50:53], v[224:227], v[162:165], v[50:53]
	v_mfma_f32_16x16x32_bf16 v[38:41], v[216:219], v[174:177], v[38:41]
	v_mfma_f32_16x16x32_bf16 v[34:37], v[224:227], v[174:177], v[34:37]
	v_mfma_f32_16x16x32_bf16 v[22:25], v[216:219], v[182:185], v[22:25]
	v_mfma_f32_16x16x32_bf16 v[18:21], v[224:227], v[182:185], v[18:21]
	v_mfma_f32_16x16x32_bf16 v[6:9], v[216:219], v[208:211], v[6:9]
	v_mfma_f32_16x16x32_bf16 v[2:5], v[224:227], v[208:211], v[2:5]
	s_add_i32 s10, 0, 0x18000
	v_add_u32_e32 v154, s10, v171
	s_barrier
	ds_read_b128 v[142:145], v154
	ds_read_b128 v[146:149], v154 offset:1024
	ds_read_b128 v[150:153], v154 offset:2048
	ds_read_b128 v[154:157], v154 offset:3072
	s_add_u32 s4, s4, s92
	s_addc_u32 s5, s5, 0
	s_mov_b32 m0, s41
	v_lshl_add_u64 v[212:213], s[4:5], 0, v[130:131]
	ds_read_b128 v[158:161], v172 offset:32768
	ds_read_b128 v[162:165], v172 offset:33792
	ds_read_b128 v[166:169], v172 offset:34816
	ds_read_b128 v[174:177], v172 offset:35840
	ds_read_b128 v[178:181], v172 offset:36864
	ds_read_b128 v[182:185], v172 offset:37888
	ds_read_b128 v[204:207], v172 offset:38912
	ds_read_b128 v[208:211], v172 offset:39936
	global_load_lds_dwordx4 v[212:213], off
	v_lshl_add_u64 v[212:213], s[4:5], 0, v[134:135]
	s_mov_b32 m0, s42
	s_nop 0
	global_load_lds_dwordx4 v[212:213], off
	s_waitcnt lgkmcnt(8)
	s_barrier
	s_waitcnt lgkmcnt(0)
	s_waitcnt lgkmcnt(0)
	v_mfma_f32_16x16x32_bf16 v[126:129], v[142:145], v[158:161], v[126:129]
	v_mfma_f32_16x16x32_bf16 v[122:125], v[150:153], v[158:161], v[122:125]
	v_mfma_f32_16x16x32_bf16 v[110:113], v[142:145], v[166:169], v[110:113]
	v_mfma_f32_16x16x32_bf16 v[106:109], v[150:153], v[166:169], v[106:109]
	v_mfma_f32_16x16x32_bf16 v[94:97], v[142:145], v[178:181], v[94:97]
	v_mfma_f32_16x16x32_bf16 v[90:93], v[150:153], v[178:181], v[90:93]
	v_mfma_f32_16x16x32_bf16 v[78:81], v[142:145], v[204:207], v[78:81]
	v_mfma_f32_16x16x32_bf16 v[74:77], v[150:153], v[204:207], v[74:77]
	v_mfma_f32_16x16x32_bf16 v[126:129], v[146:149], v[162:165], v[126:129]
	v_mfma_f32_16x16x32_bf16 v[122:125], v[154:157], v[162:165], v[122:125]
	v_mfma_f32_16x16x32_bf16 v[110:113], v[146:149], v[174:177], v[110:113]
	v_mfma_f32_16x16x32_bf16 v[106:109], v[154:157], v[174:177], v[106:109]
	v_mfma_f32_16x16x32_bf16 v[94:97], v[146:149], v[182:185], v[94:97]
	v_mfma_f32_16x16x32_bf16 v[90:93], v[154:157], v[182:185], v[90:93]
	v_mfma_f32_16x16x32_bf16 v[78:81], v[146:149], v[208:211], v[78:81]
	v_mfma_f32_16x16x32_bf16 v[74:77], v[154:157], v[208:211], v[74:77]
	s_barrier
	s_add_i32 s4, 0, 0x1c000
	s_add_i32 s5, s10, s34
	v_add_u32_e32 v173, s4, v171
	v_lshl_add_u64 v[228:229], v[228:229], 0, s[6:7]
	s_mov_b32 m0, s5
	ds_read_b128 v[212:215], v173
	ds_read_b128 v[216:219], v173 offset:1024
	ds_read_b128 v[220:223], v173 offset:2048
	ds_read_b128 v[224:227], v173 offset:3072
	global_load_lds_dwordx4 v[228:229], off
	v_lshl_add_u64 v[228:229], v[230:231], 0, s[6:7]
	s_add_i32 m0, s5, 0x2000
	s_nop 0
	global_load_lds_dwordx4 v[228:229], off
	s_barrier
	s_waitcnt lgkmcnt(0)
	s_waitcnt lgkmcnt(0)
	v_mfma_f32_16x16x32_bf16 v[118:121], v[212:215], v[158:161], v[118:121]
	v_mfma_f32_16x16x32_bf16 v[114:117], v[220:223], v[158:161], v[114:117]
	v_mfma_f32_16x16x32_bf16 v[102:105], v[212:215], v[166:169], v[102:105]
	v_mfma_f32_16x16x32_bf16 v[98:101], v[220:223], v[166:169], v[98:101]
	v_mfma_f32_16x16x32_bf16 v[86:89], v[212:215], v[178:181], v[86:89]
	v_mfma_f32_16x16x32_bf16 v[82:85], v[220:223], v[178:181], v[82:85]
	v_mfma_f32_16x16x32_bf16 v[70:73], v[212:215], v[204:207], v[70:73]
	v_mfma_f32_16x16x32_bf16 v[66:69], v[220:223], v[204:207], v[66:69]
	v_mfma_f32_16x16x32_bf16 v[118:121], v[216:219], v[162:165], v[118:121]
	v_mfma_f32_16x16x32_bf16 v[114:117], v[224:227], v[162:165], v[114:117]
	v_mfma_f32_16x16x32_bf16 v[102:105], v[216:219], v[174:177], v[102:105]
	v_mfma_f32_16x16x32_bf16 v[98:101], v[224:227], v[174:177], v[98:101]
	v_mfma_f32_16x16x32_bf16 v[86:89], v[216:219], v[182:185], v[86:89]
	v_mfma_f32_16x16x32_bf16 v[82:85], v[224:227], v[182:185], v[82:85]
	v_mfma_f32_16x16x32_bf16 v[70:73], v[216:219], v[208:211], v[70:73]
	v_mfma_f32_16x16x32_bf16 v[66:69], v[224:227], v[208:211], v[66:69]
	s_mov_b32 m0, s46
	v_lshl_add_u64 v[228:229], v[232:233], 0, s[6:7]
	s_barrier
	ds_read_b128 v[158:161], v172 offset:49152
	ds_read_b128 v[162:165], v172 offset:50176
	ds_read_b128 v[166:169], v172 offset:51200
	ds_read_b128 v[174:177], v172 offset:52224
	ds_read_b128 v[178:181], v172 offset:53248
	ds_read_b128 v[182:185], v172 offset:54272
	ds_read_b128 v[204:207], v172 offset:55296
	ds_read_b128 v[208:211], v172 offset:56320
	global_load_lds_dwordx4 v[228:229], off
	v_lshl_add_u64 v[228:229], v[234:235], 0, s[6:7]
	s_mov_b32 m0, s47
	s_nop 0
	global_load_lds_dwordx4 v[228:229], off
	s_barrier
	s_waitcnt lgkmcnt(0)
	s_waitcnt lgkmcnt(0)
	v_mfma_f32_16x16x32_bf16 v[62:65], v[142:145], v[158:161], v[62:65]
	v_mfma_f32_16x16x32_bf16 v[58:61], v[150:153], v[158:161], v[58:61]
	v_mfma_f32_16x16x32_bf16 v[46:49], v[142:145], v[166:169], v[46:49]
	v_mfma_f32_16x16x32_bf16 v[42:45], v[150:153], v[166:169], v[42:45]
	v_mfma_f32_16x16x32_bf16 v[30:33], v[142:145], v[178:181], v[30:33]
	v_mfma_f32_16x16x32_bf16 v[26:29], v[150:153], v[178:181], v[26:29]
	v_mfma_f32_16x16x32_bf16 v[14:17], v[142:145], v[204:207], v[14:17]
	v_mfma_f32_16x16x32_bf16 v[10:13], v[150:153], v[204:207], v[10:13]
	v_mfma_f32_16x16x32_bf16 v[62:65], v[146:149], v[162:165], v[62:65]
	v_mfma_f32_16x16x32_bf16 v[58:61], v[154:157], v[162:165], v[58:61]
	v_mfma_f32_16x16x32_bf16 v[46:49], v[146:149], v[174:177], v[46:49]
	v_mfma_f32_16x16x32_bf16 v[42:45], v[154:157], v[174:177], v[42:45]
	v_mfma_f32_16x16x32_bf16 v[30:33], v[146:149], v[182:185], v[30:33]
	v_mfma_f32_16x16x32_bf16 v[26:29], v[154:157], v[182:185], v[26:29]
	v_mfma_f32_16x16x32_bf16 v[14:17], v[146:149], v[208:211], v[14:17]
	v_mfma_f32_16x16x32_bf16 v[10:13], v[154:157], v[208:211], v[10:13]
	s_barrier
	s_add_i32 s4, s4, s34
	v_lshl_add_u64 v[142:143], v[236:237], 0, s[6:7]
	s_mov_b32 m0, s4
	s_nop 0
	global_load_lds_dwordx4 v[142:143], off
	v_lshl_add_u64 v[142:143], v[238:239], 0, s[6:7]
	s_add_i32 m0, s4, 0x2000
	s_nop 0
	global_load_lds_dwordx4 v[142:143], off
	s_waitcnt vmcnt(6)
	s_barrier
	v_mfma_f32_16x16x32_bf16 v[54:57], v[212:215], v[158:161], v[54:57]
	v_mfma_f32_16x16x32_bf16 v[50:53], v[220:223], v[158:161], v[50:53]
	v_mfma_f32_16x16x32_bf16 v[38:41], v[212:215], v[166:169], v[38:41]
	v_mfma_f32_16x16x32_bf16 v[34:37], v[220:223], v[166:169], v[34:37]
	v_mfma_f32_16x16x32_bf16 v[22:25], v[212:215], v[178:181], v[22:25]
	v_mfma_f32_16x16x32_bf16 v[18:21], v[220:223], v[178:181], v[18:21]
	v_mfma_f32_16x16x32_bf16 v[6:9], v[212:215], v[204:207], v[6:9]
	v_mfma_f32_16x16x32_bf16 v[2:5], v[220:223], v[204:207], v[2:5]
	v_mfma_f32_16x16x32_bf16 v[54:57], v[216:219], v[162:165], v[54:57]
	v_mfma_f32_16x16x32_bf16 v[50:53], v[224:227], v[162:165], v[50:53]
	v_mfma_f32_16x16x32_bf16 v[38:41], v[216:219], v[174:177], v[38:41]
	v_mfma_f32_16x16x32_bf16 v[34:37], v[224:227], v[174:177], v[34:37]
	v_mfma_f32_16x16x32_bf16 v[22:25], v[216:219], v[182:185], v[22:25]
	v_mfma_f32_16x16x32_bf16 v[18:21], v[224:227], v[182:185], v[18:21]
	v_mfma_f32_16x16x32_bf16 v[6:9], v[216:219], v[208:211], v[6:9]
	v_mfma_f32_16x16x32_bf16 v[2:5], v[224:227], v[208:211], v[2:5]
	s_add_u32 s0, s0, 0x100
	s_addc_u32 s1, s1, 0
	s_add_u32 s12, s12, 0x100
	s_addc_u32 s13, s13, 0
	s_cmp_ge_u32 s27, s43
	s_mov_b32 s4, s27
	s_barrier
	s_cbranch_scc1 .Lkexit_806
.LBB0_806:
	s_add_i32 s27, s4, 2
	s_add_u32 s10, s0, 0x80
	s_addc_u32 s5, s1, 0
	s_add_i32 s28, 0, 0x10000
	v_add_u32_e32 v154, s28, v171
	ds_read_b128 v[142:145], v154
	ds_read_b128 v[146:149], v154 offset:1024
	ds_read_b128 v[150:153], v154 offset:2048
	ds_read_b128 v[154:157], v154 offset:3072
	s_cmp_eq_u32 s48, s4
	s_cselect_b32 s4, s22, s10
	s_cselect_b32 s5, s23, s5
	s_cselect_b32 s11, s25, s13
	s_cselect_b32 s10, s24, s12
	v_lshl_add_u64 v[212:213], s[0:1], 0, v[138:139]
	s_add_i32 m0, s35, 0xc000
	ds_read_b128 v[158:161], v172
	ds_read_b128 v[162:165], v172 offset:1024
	ds_read_b128 v[166:169], v172 offset:2048
	ds_read_b128 v[174:177], v172 offset:3072
	ds_read_b128 v[178:181], v172 offset:4096
	ds_read_b128 v[182:185], v172 offset:5120
	ds_read_b128 v[204:207], v172 offset:6144
	ds_read_b128 v[208:211], v172 offset:7168
	global_load_lds_dwordx4 v[212:213], off
	v_lshl_add_u64 v[212:213], s[0:1], 0, v[140:141]
	s_add_i32 m0, s35, 0xe000
	s_nop 0
	global_load_lds_dwordx4 v[212:213], off
	s_waitcnt lgkmcnt(8)
	s_barrier
	s_waitcnt lgkmcnt(0)
	s_waitcnt lgkmcnt(0)
	v_mfma_f32_16x16x32_bf16 v[126:129], v[142:145], v[158:161], v[126:129]
	v_mfma_f32_16x16x32_bf16 v[122:125], v[150:153], v[158:161], v[122:125]
	v_mfma_f32_16x16x32_bf16 v[110:113], v[142:145], v[166:169], v[110:113]
	v_mfma_f32_16x16x32_bf16 v[106:109], v[150:153], v[166:169], v[106:109]
	v_mfma_f32_16x16x32_bf16 v[94:97], v[142:145], v[178:181], v[94:97]
	v_mfma_f32_16x16x32_bf16 v[90:93], v[150:153], v[178:181], v[90:93]
	v_mfma_f32_16x16x32_bf16 v[78:81], v[142:145], v[204:207], v[78:81]
	v_mfma_f32_16x16x32_bf16 v[74:77], v[150:153], v[204:207], v[74:77]
	v_mfma_f32_16x16x32_bf16 v[126:129], v[146:149], v[162:165], v[126:129]
	v_mfma_f32_16x16x32_bf16 v[122:125], v[154:157], v[162:165], v[122:125]
	v_mfma_f32_16x16x32_bf16 v[110:113], v[146:149], v[174:177], v[110:113]
	v_mfma_f32_16x16x32_bf16 v[106:109], v[154:157], v[174:177], v[106:109]
	v_mfma_f32_16x16x32_bf16 v[94:97], v[146:149], v[182:185], v[94:97]
	v_mfma_f32_16x16x32_bf16 v[90:93], v[154:157], v[182:185], v[90:93]
	v_mfma_f32_16x16x32_bf16 v[78:81], v[146:149], v[208:211], v[78:81]
	v_mfma_f32_16x16x32_bf16 v[74:77], v[154:157], v[208:211], v[74:77]
	s_barrier
	s_add_i32 s29, 0, 0x14000
	s_add_i32 s28, s28, s34
	v_add_u32_e32 v173, s29, v171
	v_lshl_add_u64 v[228:229], s[10:11], 0, v[132:133]
	s_mov_b32 m0, s28
	ds_read_b128 v[212:215], v173
	ds_read_b128 v[216:219], v173 offset:1024
	ds_read_b128 v[220:223], v173 offset:2048
	ds_read_b128 v[224:227], v173 offset:3072
	global_load_lds_dwordx4 v[228:229], off
	v_lshl_add_u64 v[230:231], s[10:11], 0, v[136:137]
	s_add_i32 m0, s28, 0x2000
	s_nop 0
	global_load_lds_dwordx4 v[230:231], off
	s_barrier
	s_waitcnt lgkmcnt(0)
	s_waitcnt lgkmcnt(0)
	v_mfma_f32_16x16x32_bf16 v[118:121], v[212:215], v[158:161], v[118:121]
	v_mfma_f32_16x16x32_bf16 v[114:117], v[220:223], v[158:161], v[114:117]
	v_mfma_f32_16x16x32_bf16 v[102:105], v[212:215], v[166:169], v[102:105]
	v_mfma_f32_16x16x32_bf16 v[98:101], v[220:223], v[166:169], v[98:101]
	v_mfma_f32_16x16x32_bf16 v[86:89], v[212:215], v[178:181], v[86:89]
	v_mfma_f32_16x16x32_bf16 v[82:85], v[220:223], v[178:181], v[82:85]
	v_mfma_f32_16x16x32_bf16 v[70:73], v[212:215], v[204:207], v[70:73]
	v_mfma_f32_16x16x32_bf16 v[66:69], v[220:223], v[204:207], v[66:69]
	v_mfma_f32_16x16x32_bf16 v[118:121], v[216:219], v[162:165], v[118:121]
	v_mfma_f32_16x16x32_bf16 v[114:117], v[224:227], v[162:165], v[114:117]
	v_mfma_f32_16x16x32_bf16 v[102:105], v[216:219], v[174:177], v[102:105]
	v_mfma_f32_16x16x32_bf16 v[98:101], v[224:227], v[174:177], v[98:101]
	v_mfma_f32_16x16x32_bf16 v[86:89], v[216:219], v[182:185], v[86:89]
	v_mfma_f32_16x16x32_bf16 v[82:85], v[224:227], v[182:185], v[82:85]
	v_mfma_f32_16x16x32_bf16 v[70:73], v[216:219], v[208:211], v[70:73]
	v_mfma_f32_16x16x32_bf16 v[66:69], v[224:227], v[208:211], v[66:69]
	s_mov_b32 m0, s35
	v_lshl_add_u64 v[232:233], s[4:5], 0, v[130:131]
	s_barrier
	ds_read_b128 v[158:161], v172 offset:16384
	ds_read_b128 v[162:165], v172 offset:17408
	ds_read_b128 v[166:169], v172 offset:18432
	ds_read_b128 v[174:177], v172 offset:19456
	ds_read_b128 v[178:181], v172 offset:20480
	ds_read_b128 v[182:185], v172 offset:21504
	ds_read_b128 v[204:207], v172 offset:22528
	ds_read_b128 v[208:211], v172 offset:23552
	global_load_lds_dwordx4 v[232:233], off
	v_lshl_add_u64 v[234:235], s[4:5], 0, v[134:135]
	s_mov_b32 m0, s40
	s_nop 0
	global_load_lds_dwordx4 v[234:235], off
	s_barrier
	s_waitcnt lgkmcnt(0)
	s_waitcnt lgkmcnt(0)
	v_mfma_f32_16x16x32_bf16 v[62:65], v[142:145], v[158:161], v[62:65]
	v_mfma_f32_16x16x32_bf16 v[58:61], v[150:153], v[158:161], v[58:61]
	v_mfma_f32_16x16x32_bf16 v[46:49], v[142:145], v[166:169], v[46:49]
	v_mfma_f32_16x16x32_bf16 v[42:45], v[150:153], v[166:169], v[42:45]
	v_mfma_f32_16x16x32_bf16 v[30:33], v[142:145], v[178:181], v[30:33]
	v_mfma_f32_16x16x32_bf16 v[26:29], v[150:153], v[178:181], v[26:29]
	v_mfma_f32_16x16x32_bf16 v[14:17], v[142:145], v[204:207], v[14:17]
	v_mfma_f32_16x16x32_bf16 v[10:13], v[150:153], v[204:207], v[10:13]
	v_mfma_f32_16x16x32_bf16 v[62:65], v[146:149], v[162:165], v[62:65]
	v_mfma_f32_16x16x32_bf16 v[58:61], v[154:157], v[162:165], v[58:61]
	v_mfma_f32_16x16x32_bf16 v[46:49], v[146:149], v[174:177], v[46:49]
	v_mfma_f32_16x16x32_bf16 v[42:45], v[154:157], v[174:177], v[42:45]
	v_mfma_f32_16x16x32_bf16 v[30:33], v[146:149], v[182:185], v[30:33]
	v_mfma_f32_16x16x32_bf16 v[26:29], v[154:157], v[182:185], v[26:29]
	v_mfma_f32_16x16x32_bf16 v[14:17], v[146:149], v[208:211], v[14:17]
	v_mfma_f32_16x16x32_bf16 v[10:13], v[154:157], v[208:211], v[10:13]
	s_barrier
	s_add_u32 s10, s10, s92
	s_addc_u32 s11, s11, 0
	s_add_i32 s28, s29, s34
	v_lshl_add_u64 v[236:237], s[10:11], 0, v[132:133]
	s_mov_b32 m0, s28
	v_lshl_add_u64 v[238:239], s[10:11], 0, v[136:137]
	global_load_lds_dwordx4 v[236:237], off
	s_add_i32 m0, s28, 0x2000
	s_nop 0
	global_load_lds_dwordx4 v[238:239], off
	s_waitcnt vmcnt(6)
	s_barrier
	v_mfma_f32_16x16x32_bf16 v[54:57], v[212:215], v[158:161], v[54:57]
	v_mfma_f32_16x16x32_bf16 v[50:53], v[220:223], v[158:161], v[50:53]
	v_mfma_f32_16x16x32_bf16 v[38:41], v[212:215], v[166:169], v[38:41]
	v_mfma_f32_16x16x32_bf16 v[34:37], v[220:223], v[166:169], v[34:37]
	v_mfma_f32_16x16x32_bf16 v[22:25], v[212:215], v[178:181], v[22:25]
	v_mfma_f32_16x16x32_bf16 v[18:21], v[220:223], v[178:181], v[18:21]
	v_mfma_f32_16x16x32_bf16 v[6:9], v[212:215], v[204:207], v[6:9]
	v_mfma_f32_16x16x32_bf16 v[2:5], v[220:223], v[204:207], v[2:5]
	v_mfma_f32_16x16x32_bf16 v[54:57], v[216:219], v[162:165], v[54:57]
	v_mfma_f32_16x16x32_bf16 v[50:53], v[224:227], v[162:165], v[50:53]
	v_mfma_f32_16x16x32_bf16 v[38:41], v[216:219], v[174:177], v[38:41]
	v_mfma_f32_16x16x32_bf16 v[34:37], v[224:227], v[174:177], v[34:37]
	v_mfma_f32_16x16x32_bf16 v[22:25], v[216:219], v[182:185], v[22:25]
	v_mfma_f32_16x16x32_bf16 v[18:21], v[224:227], v[182:185], v[18:21]
	v_mfma_f32_16x16x32_bf16 v[6:9], v[216:219], v[208:211], v[6:9]
	v_mfma_f32_16x16x32_bf16 v[2:5], v[224:227], v[208:211], v[2:5]
	s_add_i32 s10, 0, 0x18000
	v_add_u32_e32 v154, s10, v171
	s_barrier
	ds_read_b128 v[142:145], v154
	ds_read_b128 v[146:149], v154 offset:1024
	ds_read_b128 v[150:153], v154 offset:2048
	ds_read_b128 v[154:157], v154 offset:3072
	s_add_u32 s4, s4, s92
	s_addc_u32 s5, s5, 0
	s_mov_b32 m0, s41
	v_lshl_add_u64 v[212:213], s[4:5], 0, v[130:131]
	ds_read_b128 v[158:161], v172 offset:32768
	ds_read_b128 v[162:165], v172 offset:33792
	ds_read_b128 v[166:169], v172 offset:34816
	ds_read_b128 v[174:177], v172 offset:35840
	ds_read_b128 v[178:181], v172 offset:36864
	ds_read_b128 v[182:185], v172 offset:37888
	ds_read_b128 v[204:207], v172 offset:38912
	ds_read_b128 v[208:211], v172 offset:39936
	global_load_lds_dwordx4 v[212:213], off
	v_lshl_add_u64 v[212:213], s[4:5], 0, v[134:135]
	s_mov_b32 m0, s42
	s_nop 0
	global_load_lds_dwordx4 v[212:213], off
	s_waitcnt lgkmcnt(8)
	s_barrier
	s_waitcnt lgkmcnt(0)
	s_waitcnt lgkmcnt(0)
	v_mfma_f32_16x16x32_bf16 v[126:129], v[142:145], v[158:161], v[126:129]
	v_mfma_f32_16x16x32_bf16 v[122:125], v[150:153], v[158:161], v[122:125]
	v_mfma_f32_16x16x32_bf16 v[110:113], v[142:145], v[166:169], v[110:113]
	v_mfma_f32_16x16x32_bf16 v[106:109], v[150:153], v[166:169], v[106:109]
	v_mfma_f32_16x16x32_bf16 v[94:97], v[142:145], v[178:181], v[94:97]
	v_mfma_f32_16x16x32_bf16 v[90:93], v[150:153], v[178:181], v[90:93]
	v_mfma_f32_16x16x32_bf16 v[78:81], v[142:145], v[204:207], v[78:81]
	v_mfma_f32_16x16x32_bf16 v[74:77], v[150:153], v[204:207], v[74:77]
	v_mfma_f32_16x16x32_bf16 v[126:129], v[146:149], v[162:165], v[126:129]
	v_mfma_f32_16x16x32_bf16 v[122:125], v[154:157], v[162:165], v[122:125]
	v_mfma_f32_16x16x32_bf16 v[110:113], v[146:149], v[174:177], v[110:113]
	v_mfma_f32_16x16x32_bf16 v[106:109], v[154:157], v[174:177], v[106:109]
	v_mfma_f32_16x16x32_bf16 v[94:97], v[146:149], v[182:185], v[94:97]
	v_mfma_f32_16x16x32_bf16 v[90:93], v[154:157], v[182:185], v[90:93]
	v_mfma_f32_16x16x32_bf16 v[78:81], v[146:149], v[208:211], v[78:81]
	v_mfma_f32_16x16x32_bf16 v[74:77], v[154:157], v[208:211], v[74:77]
	s_barrier
	s_add_i32 s4, 0, 0x1c000
	s_add_i32 s5, s10, s34
	v_add_u32_e32 v173, s4, v171
	v_lshl_add_u64 v[228:229], v[228:229], 0, s[6:7]
	s_mov_b32 m0, s5
	ds_read_b128 v[212:215], v173
	ds_read_b128 v[216:219], v173 offset:1024
	ds_read_b128 v[220:223], v173 offset:2048
	ds_read_b128 v[224:227], v173 offset:3072
	global_load_lds_dwordx4 v[228:229], off
	v_lshl_add_u64 v[228:229], v[230:231], 0, s[6:7]
	s_add_i32 m0, s5, 0x2000
	s_nop 0
	global_load_lds_dwordx4 v[228:229], off
	s_barrier
	s_waitcnt lgkmcnt(0)
	s_waitcnt lgkmcnt(0)
	v_mfma_f32_16x16x32_bf16 v[118:121], v[212:215], v[158:161], v[118:121]
	v_mfma_f32_16x16x32_bf16 v[114:117], v[220:223], v[158:161], v[114:117]
	v_mfma_f32_16x16x32_bf16 v[102:105], v[212:215], v[166:169], v[102:105]
	v_mfma_f32_16x16x32_bf16 v[98:101], v[220:223], v[166:169], v[98:101]
	v_mfma_f32_16x16x32_bf16 v[86:89], v[212:215], v[178:181], v[86:89]
	v_mfma_f32_16x16x32_bf16 v[82:85], v[220:223], v[178:181], v[82:85]
	v_mfma_f32_16x16x32_bf16 v[70:73], v[212:215], v[204:207], v[70:73]
	v_mfma_f32_16x16x32_bf16 v[66:69], v[220:223], v[204:207], v[66:69]
	v_mfma_f32_16x16x32_bf16 v[118:121], v[216:219], v[162:165], v[118:121]
	v_mfma_f32_16x16x32_bf16 v[114:117], v[224:227], v[162:165], v[114:117]
	v_mfma_f32_16x16x32_bf16 v[102:105], v[216:219], v[174:177], v[102:105]
	v_mfma_f32_16x16x32_bf16 v[98:101], v[224:227], v[174:177], v[98:101]
	v_mfma_f32_16x16x32_bf16 v[86:89], v[216:219], v[182:185], v[86:89]
	v_mfma_f32_16x16x32_bf16 v[82:85], v[224:227], v[182:185], v[82:85]
	v_mfma_f32_16x16x32_bf16 v[70:73], v[216:219], v[208:211], v[70:73]
	v_mfma_f32_16x16x32_bf16 v[66:69], v[224:227], v[208:211], v[66:69]
	s_mov_b32 m0, s46
	v_lshl_add_u64 v[228:229], v[232:233], 0, s[6:7]
	s_barrier
	ds_read_b128 v[158:161], v172 offset:49152
	ds_read_b128 v[162:165], v172 offset:50176
	ds_read_b128 v[166:169], v172 offset:51200
	ds_read_b128 v[174:177], v172 offset:52224
	ds_read_b128 v[178:181], v172 offset:53248
	ds_read_b128 v[182:185], v172 offset:54272
	ds_read_b128 v[204:207], v172 offset:55296
	ds_read_b128 v[208:211], v172 offset:56320
	global_load_lds_dwordx4 v[228:229], off
	v_lshl_add_u64 v[228:229], v[234:235], 0, s[6:7]
	s_mov_b32 m0, s47
	s_nop 0
	global_load_lds_dwordx4 v[228:229], off
	s_barrier
	s_waitcnt lgkmcnt(0)
	s_waitcnt lgkmcnt(0)
	v_mfma_f32_16x16x32_bf16 v[62:65], v[142:145], v[158:161], v[62:65]
	v_mfma_f32_16x16x32_bf16 v[58:61], v[150:153], v[158:161], v[58:61]
	v_mfma_f32_16x16x32_bf16 v[46:49], v[142:145], v[166:169], v[46:49]
	v_mfma_f32_16x16x32_bf16 v[42:45], v[150:153], v[166:169], v[42:45]
	v_mfma_f32_16x16x32_bf16 v[30:33], v[142:145], v[178:181], v[30:33]
	v_mfma_f32_16x16x32_bf16 v[26:29], v[150:153], v[178:181], v[26:29]
	v_mfma_f32_16x16x32_bf16 v[14:17], v[142:145], v[204:207], v[14:17]
	v_mfma_f32_16x16x32_bf16 v[10:13], v[150:153], v[204:207], v[10:13]
	v_mfma_f32_16x16x32_bf16 v[62:65], v[146:149], v[162:165], v[62:65]
	v_mfma_f32_16x16x32_bf16 v[58:61], v[154:157], v[162:165], v[58:61]
	v_mfma_f32_16x16x32_bf16 v[46:49], v[146:149], v[174:177], v[46:49]
	v_mfma_f32_16x16x32_bf16 v[42:45], v[154:157], v[174:177], v[42:45]
	v_mfma_f32_16x16x32_bf16 v[30:33], v[146:149], v[182:185], v[30:33]
	v_mfma_f32_16x16x32_bf16 v[26:29], v[154:157], v[182:185], v[26:29]
	v_mfma_f32_16x16x32_bf16 v[14:17], v[146:149], v[208:211], v[14:17]
	v_mfma_f32_16x16x32_bf16 v[10:13], v[154:157], v[208:211], v[10:13]
	s_barrier
	s_add_i32 s4, s4, s34
	v_lshl_add_u64 v[142:143], v[236:237], 0, s[6:7]
	s_mov_b32 m0, s4
	s_nop 0
	global_load_lds_dwordx4 v[142:143], off
	v_lshl_add_u64 v[142:143], v[238:239], 0, s[6:7]
	s_add_i32 m0, s4, 0x2000
	s_nop 0
	global_load_lds_dwordx4 v[142:143], off
	s_waitcnt vmcnt(6)
	s_barrier
	v_mfma_f32_16x16x32_bf16 v[54:57], v[212:215], v[158:161], v[54:57]
	v_mfma_f32_16x16x32_bf16 v[50:53], v[220:223], v[158:161], v[50:53]
	v_mfma_f32_16x16x32_bf16 v[38:41], v[212:215], v[166:169], v[38:41]
	v_mfma_f32_16x16x32_bf16 v[34:37], v[220:223], v[166:169], v[34:37]
	v_mfma_f32_16x16x32_bf16 v[22:25], v[212:215], v[178:181], v[22:25]
	v_mfma_f32_16x16x32_bf16 v[18:21], v[220:223], v[178:181], v[18:21]
	v_mfma_f32_16x16x32_bf16 v[6:9], v[212:215], v[204:207], v[6:9]
	v_mfma_f32_16x16x32_bf16 v[2:5], v[220:223], v[204:207], v[2:5]
	v_mfma_f32_16x16x32_bf16 v[54:57], v[216:219], v[162:165], v[54:57]
	v_mfma_f32_16x16x32_bf16 v[50:53], v[224:227], v[162:165], v[50:53]
	v_mfma_f32_16x16x32_bf16 v[38:41], v[216:219], v[174:177], v[38:41]
	v_mfma_f32_16x16x32_bf16 v[34:37], v[224:227], v[174:177], v[34:37]
	v_mfma_f32_16x16x32_bf16 v[22:25], v[216:219], v[182:185], v[22:25]
	v_mfma_f32_16x16x32_bf16 v[18:21], v[224:227], v[182:185], v[18:21]
	v_mfma_f32_16x16x32_bf16 v[6:9], v[216:219], v[208:211], v[6:9]
	v_mfma_f32_16x16x32_bf16 v[2:5], v[224:227], v[208:211], v[2:5]
	s_add_u32 s0, s0, 0x100
	s_addc_u32 s1, s1, 0
	s_add_u32 s12, s12, 0x100
	s_addc_u32 s13, s13, 0
	s_cmp_ge_u32 s27, s43
	s_mov_b32 s4, s27
	s_barrier
	s_cbranch_scc0 .LBB0_806
